# peel first K-loop iteration of all 9 GEMM instances: first-touch MFMAs use C=0, removing 256 accumulator-zeroing v_mov per unit
# speedup vs baseline: 1.0232x; 1.0129x over previous
; #define PG8_STAGE(bufoff, gbase, voff) do { _Pragma("unroll") for (int _i = 0; _i < 2; ++_i) \
;         __builtin_amdgcn_global_load_lds((const unsigned*)((const char*)(gbase) + (voff)[_i]), (PG8_LAS unsigned*)(lds + (bufoff) + ldsw + _i * 8192), 16, 0, 0); } while (0)
; #define PG8_LDA(dst, b, h) do { _Pragma("unroll") for (int m = 0; m < 4; ++m) _Pragma("unroll") for (int k = 0; k < 2; ++k) dst[m][k] = *(const PG8_LAS bf16x8*)(lds + PG8_SA(b, h) + aoff + m * 2048 + k * 1024); } while (0)
; #define PG8_LDB(dst, b, h) do { _Pragma("unroll") for (int n = 0; n < 2; ++n) _Pragma("unroll") for (int k = 0; k < 2; ++k) dst[n][k] = *(const PG8_LAS bf16x8*)(lds + PG8_SB(b, h) + boff + n * 2048 + k * 1024); } while (0)
; #define PG8_SCHED __builtin_amdgcn_sched_barrier(0)
; template <class Epi, class Sched, bool ALIGN_EPI = false, bool SP2 = false>
; __device__ __forceinline__ void gemm_phase(PG8_LAS unsigned char* lds, const Gemm g, const Sched& S, const Epi& E) {
;     ...
;     f32x4 acc[2][2][4][2];
; #pragma unroll
;     for (int a = 0; a < 2; ++a)
; #pragma unroll
;         for (int b = 0; b < 2; ++b)
; #pragma unroll
;             for (int m = 0; m < 4; ++m)
; #pragma unroll
;                 for (int n = 0; n < 2; ++n) acc[a][b][m][n] = (f32x4){0.f, 0.f, 0.f, 0.f};
;     ...
;         const bool has_next = S.next(ui + 1, nxt);
;         const char* nA = has_next ? (const char*)g.A + (size_t)nxt.pm * tstep : cA; const char* nB = has_next ? (const char*)g.Bt + (size_t)nxt.pn * tstep : cB;
;         for (int t = 0; t < nt; t += 2) {
;             const bool last = (t == nt - 2);
;             const char* a1 = cA + (size_t)(t + 1) * kstep;
;             const char* a2 = last ? nA : cA + (size_t)(t + 2) * kstep; const char* b2 = last ? nB : cB + (size_t)(t + 2) * kstep;
;             const char* a3 = a2 + kstep; const char* b3 = b2 + kstep;
;             if (last && has_next) S.a_ready(nxt);
;             if constexpr (SP2) {
;             PG8_LDB(B0, 0, 0); PG8_LDB(B1, 0, 1); PG8_SCHED; PG8_LDA(At, 0, 0); PG8_STAGE(PG8_SA(1, 1), a1 + hstep, voffA);
.LBB0_189:
	s_andn2_b64 vcc, exec, s[52:53]
	s_cbranch_vccz .Lpeel_k1
	v_mov_b32_e32 v123, 0
	v_mov_b32_e32 v122, v123
	v_mov_b32_e32 v121, v123
	v_mov_b32_e32 v120, v123
	v_mov_b32_e32 v119, v123
	v_mov_b32_e32 v118, v123
	v_mov_b32_e32 v117, v123
	v_mov_b32_e32 v116, v123
	v_mov_b32_e32 v111, v123
	v_mov_b32_e32 v110, v123
	v_mov_b32_e32 v109, v123
	v_mov_b32_e32 v108, v123
	v_mov_b32_e32 v103, v123
	v_mov_b32_e32 v102, v123
	v_mov_b32_e32 v101, v123
	v_mov_b32_e32 v100, v123
	v_mov_b32_e32 v95, v123
	v_mov_b32_e32 v94, v123
	v_mov_b32_e32 v93, v123
	v_mov_b32_e32 v92, v123
	v_mov_b32_e32 v87, v123
	v_mov_b32_e32 v86, v123
	v_mov_b32_e32 v85, v123
	v_mov_b32_e32 v84, v123
	v_mov_b32_e32 v79, v123
	v_mov_b32_e32 v78, v123
	v_mov_b32_e32 v77, v123
	v_mov_b32_e32 v76, v123
	v_mov_b32_e32 v71, v123
	v_mov_b32_e32 v70, v123
	v_mov_b32_e32 v69, v123
	v_mov_b32_e32 v68, v123
	v_mov_b32_e32 v127, v123
	v_mov_b32_e32 v126, v123
	v_mov_b32_e32 v125, v123
	v_mov_b32_e32 v124, v123
	v_mov_b32_e32 v115, v123
	v_mov_b32_e32 v114, v123
	v_mov_b32_e32 v113, v123
	v_mov_b32_e32 v112, v123
	v_mov_b32_e32 v107, v123
	v_mov_b32_e32 v106, v123
	v_mov_b32_e32 v105, v123
	v_mov_b32_e32 v104, v123
	v_mov_b32_e32 v99, v123
	v_mov_b32_e32 v98, v123
	v_mov_b32_e32 v97, v123
	v_mov_b32_e32 v96, v123
	v_mov_b32_e32 v91, v123
	v_mov_b32_e32 v90, v123
	v_mov_b32_e32 v89, v123
	v_mov_b32_e32 v88, v123
	v_mov_b32_e32 v83, v123
	v_mov_b32_e32 v82, v123
	v_mov_b32_e32 v81, v123
	v_mov_b32_e32 v80, v123
	v_mov_b32_e32 v75, v123
	v_mov_b32_e32 v74, v123
	v_mov_b32_e32 v73, v123
	v_mov_b32_e32 v72, v123
	v_mov_b32_e32 v67, v123
	v_mov_b32_e32 v66, v123
	v_mov_b32_e32 v65, v123
	v_mov_b32_e32 v64, v123
	v_mov_b32_e32 v63, v123
	v_mov_b32_e32 v62, v123
	v_mov_b32_e32 v61, v123
	v_mov_b32_e32 v60, v123
	v_mov_b32_e32 v55, v123
	v_mov_b32_e32 v54, v123
	v_mov_b32_e32 v53, v123
	v_mov_b32_e32 v52, v123
	v_mov_b32_e32 v47, v123
	v_mov_b32_e32 v46, v123
	v_mov_b32_e32 v45, v123
	v_mov_b32_e32 v44, v123
	v_mov_b32_e32 v39, v123
	v_mov_b32_e32 v38, v123
	v_mov_b32_e32 v37, v123
	v_mov_b32_e32 v36, v123
	v_mov_b32_e32 v31, v123
	v_mov_b32_e32 v30, v123
	v_mov_b32_e32 v29, v123
	v_mov_b32_e32 v28, v123
	v_mov_b32_e32 v23, v123
	v_mov_b32_e32 v22, v123
	v_mov_b32_e32 v21, v123
	v_mov_b32_e32 v20, v123
	v_mov_b32_e32 v15, v123
	v_mov_b32_e32 v14, v123
	v_mov_b32_e32 v13, v123
	v_mov_b32_e32 v12, v123
	v_mov_b32_e32 v7, v123
	v_mov_b32_e32 v6, v123
	v_mov_b32_e32 v5, v123
	v_mov_b32_e32 v4, v123
	v_mov_b32_e32 v59, v123
	v_mov_b32_e32 v58, v123
	v_mov_b32_e32 v57, v123
	v_mov_b32_e32 v56, v123
	v_mov_b32_e32 v51, v123
	v_mov_b32_e32 v50, v123
	v_mov_b32_e32 v49, v123
	v_mov_b32_e32 v48, v123
	v_mov_b32_e32 v43, v123
	v_mov_b32_e32 v42, v123
	v_mov_b32_e32 v41, v123
	v_mov_b32_e32 v40, v123
	v_mov_b32_e32 v35, v123
	v_mov_b32_e32 v34, v123
	v_mov_b32_e32 v33, v123
	v_mov_b32_e32 v32, v123
	v_mov_b32_e32 v27, v123
	v_mov_b32_e32 v26, v123
	v_mov_b32_e32 v25, v123
	v_mov_b32_e32 v24, v123
	v_mov_b32_e32 v19, v123
	v_mov_b32_e32 v18, v123
	v_mov_b32_e32 v17, v123
	v_mov_b32_e32 v16, v123
	v_mov_b32_e32 v11, v123
	v_mov_b32_e32 v10, v123
	v_mov_b32_e32 v9, v123
	v_mov_b32_e32 v8, v123
	v_mov_b32_e32 v3, v123
	v_mov_b32_e32 v2, v123
	v_mov_b32_e32 v1, v123
	v_mov_b32_e32 v0, v123
	s_branch .LBB0_192
.Lpeel_k1:
	s_add_u32 s30, s30, 0x80
	s_addc_u32 s31, s31, 0
	s_add_u32 s77, s34, 0x100
	s_addc_u32 s82, s35, 0
	s_mov_b32 s34, 0
	s_add_i32 s84, s34, 2
	s_add_u32 s85, s30, 0x80
	s_addc_u32 s35, s31, 0
	s_add_i32 s92, 0, 0x10000
	s_cmp_eq_u32 s68, s34
	s_cselect_b32 s35, s1, s35
	s_cselect_b32 s34, s0, s85
	v_add_u32_e32 v146, s92, v151
	s_cselect_b32 s97, s57, s82
	s_cselect_b32 s96, s56, s77
	s_add_i32 s85, 0, 0x14000
	ds_read_b128 v[142:145], v146
	ds_read_b128 v[162:165], v146 offset:1024
	ds_read_b128 v[166:169], v146 offset:2048
	ds_read_b128 v[170:173], v146 offset:3072
	v_add_u32_e32 v146, s85, v151
	ds_read_b128 v[174:177], v146
	ds_read_b128 v[178:181], v146 offset:1024
	ds_read_b128 v[182:185], v146 offset:2048
	ds_read_b128 v[186:189], v146 offset:3072
	v_lshl_add_u64 v[148:149], s[30:31], 0, v[138:139]
	s_add_i32 m0, s61, 0xc000
	ds_read_b128 v[190:193], v161
	ds_read_b128 v[194:197], v161 offset:1024
	ds_read_b128 v[198:201], v161 offset:2048
	ds_read_b128 v[202:205], v161 offset:3072
	ds_read_b128 v[212:215], v161 offset:4096
	ds_read_b128 v[216:219], v161 offset:5120
	ds_read_b128 v[220:223], v161 offset:6144
	ds_read_b128 v[224:227], v161 offset:7168
	global_load_lds_dwordx4 v[148:149], off
	v_lshl_add_u64 v[148:149], s[30:31], 0, v[140:141]
	s_add_i32 m0, s61, 0xe000
	s_nop 0
	global_load_lds_dwordx4 v[148:149], off
	s_waitcnt vmcnt(8)
	s_waitcnt lgkmcnt(0)
	s_barrier
; #define PG8_STAGE(bufoff, gbase, voff) do { _Pragma("unroll") for (int _i = 0; _i < 2; ++_i) \
;         __builtin_amdgcn_global_load_lds((const unsigned*)((const char*)(gbase) + (voff)[_i]), (PG8_LAS unsigned*)(lds + (bufoff) + ldsw + _i * 8192), 16, 0, 0); } while (0)
; #define PG8_LDA(dst, b, h) do { _Pragma("unroll") for (int m = 0; m < 4; ++m) _Pragma("unroll") for (int k = 0; k < 2; ++k) dst[m][k] = *(const PG8_LAS bf16x8*)(lds + PG8_SA(b, h) + aoff + m * 2048 + k * 1024); } while (0)
; #define PG8_MMA(ai, bj, At, Bt) do { __builtin_amdgcn_s_setprio(1); _Pragma("unroll") for (int m = 0; m < 4; ++m) _Pragma("unroll") for (int n = 0; n < 2; ++n) _Pragma("unroll") for (int k = 0; k < 2; ++k) \
;         acc[ai][bj][m][n] = mma16<Epi::F16>(Bt[n][k], At[m][k], acc[ai][bj][m][n]); __builtin_amdgcn_s_setprio(0); } while (0)
; #define PG8_WAIT_V(n) asm volatile("s_waitcnt vmcnt(" #n ")" ::: "memory")
; #define PG8_WAIT_L(n) asm volatile("s_waitcnt lgkmcnt(" #n ")" ::: "memory")
; #define PG8_BAR __builtin_amdgcn_s_barrier()
; #define PG8_SCHED __builtin_amdgcn_sched_barrier(0)
; template <class Epi, class Sched, bool ALIGN_EPI = false, bool SP2 = false>
; __device__ __forceinline__ void gemm_phase(PG8_LAS unsigned char* lds, const Gemm g, const Sched& S, const Epi& E) {
;     ...
;             PG8_WAIT_V(8); PG8_WAIT_L(0); PG8_BAR; PG8_MMA(0, 0, At, B0); PG8_MMA(0, 1, At, B1); PG8_BAR; PG8_SCHED;
;             PG8_LDA(At, 0, 1); PG8_STAGE(PG8_SB(0, 0), b2, voffB); PG8_STAGE(PG8_SB(0, 1), b2 + hstep, voffB); PG8_STAGE(PG8_SA(0, 0), a2, voffA);
;             PG8_WAIT_V(8); PG8_WAIT_L(0); PG8_BAR; PG8_MMA(1, 0, At, B0); PG8_MMA(1, 1, At, B1); PG8_BAR; PG8_SCHED;
	s_setprio 1
	s_waitcnt lgkmcnt(0)
	v_mfma_f32_16x16x32_bf16 v[120:123], v[142:145], v[190:193], 0
	v_mfma_f32_16x16x32_bf16 v[116:119], v[166:169], v[190:193], 0
	v_mfma_f32_16x16x32_bf16 v[108:111], v[142:145], v[198:201], 0
	v_mfma_f32_16x16x32_bf16 v[100:103], v[166:169], v[198:201], 0
	v_mfma_f32_16x16x32_bf16 v[92:95], v[142:145], v[212:215], 0
	v_mfma_f32_16x16x32_bf16 v[84:87], v[166:169], v[212:215], 0
	v_mfma_f32_16x16x32_bf16 v[76:79], v[142:145], v[220:223], 0
	v_mfma_f32_16x16x32_bf16 v[68:71], v[166:169], v[220:223], 0
	v_mfma_f32_16x16x32_bf16 v[120:123], v[162:165], v[194:197], v[120:123]
	v_mfma_f32_16x16x32_bf16 v[116:119], v[170:173], v[194:197], v[116:119]
	v_mfma_f32_16x16x32_bf16 v[108:111], v[162:165], v[202:205], v[108:111]
	v_mfma_f32_16x16x32_bf16 v[100:103], v[170:173], v[202:205], v[100:103]
	v_mfma_f32_16x16x32_bf16 v[92:95], v[162:165], v[216:219], v[92:95]
	v_mfma_f32_16x16x32_bf16 v[84:87], v[170:173], v[216:219], v[84:87]
	v_mfma_f32_16x16x32_bf16 v[76:79], v[162:165], v[224:227], v[76:79]
	v_mfma_f32_16x16x32_bf16 v[68:71], v[170:173], v[224:227], v[68:71]
	s_setprio 0
	s_setprio 1
	v_mfma_f32_16x16x32_bf16 v[124:127], v[174:177], v[190:193], 0
	v_mfma_f32_16x16x32_bf16 v[112:115], v[182:185], v[190:193], 0
	v_mfma_f32_16x16x32_bf16 v[104:107], v[174:177], v[198:201], 0
	v_mfma_f32_16x16x32_bf16 v[96:99], v[182:185], v[198:201], 0
	v_mfma_f32_16x16x32_bf16 v[88:91], v[174:177], v[212:215], 0
	v_mfma_f32_16x16x32_bf16 v[80:83], v[182:185], v[212:215], 0
	v_mfma_f32_16x16x32_bf16 v[72:75], v[174:177], v[220:223], 0
	v_mfma_f32_16x16x32_bf16 v[64:67], v[182:185], v[220:223], 0
	v_mfma_f32_16x16x32_bf16 v[124:127], v[178:181], v[194:197], v[124:127]
	v_mfma_f32_16x16x32_bf16 v[112:115], v[186:189], v[194:197], v[112:115]
	v_mfma_f32_16x16x32_bf16 v[104:107], v[178:181], v[202:205], v[104:107]
	v_mfma_f32_16x16x32_bf16 v[96:99], v[186:189], v[202:205], v[96:99]
	v_mfma_f32_16x16x32_bf16 v[88:91], v[178:181], v[216:219], v[88:91]
	v_mfma_f32_16x16x32_bf16 v[80:83], v[186:189], v[216:219], v[80:83]
	v_mfma_f32_16x16x32_bf16 v[72:75], v[178:181], v[224:227], v[72:75]
	v_mfma_f32_16x16x32_bf16 v[64:67], v[186:189], v[224:227], v[64:67]
	s_setprio 0
	s_barrier
	s_add_i32 s92, s92, s11
	v_lshl_add_u64 v[148:149], s[96:97], 0, v[132:133]
	s_mov_b32 m0, s92
	ds_read_b128 v[190:193], v161 offset:16384
	ds_read_b128 v[194:197], v161 offset:17408
	ds_read_b128 v[198:201], v161 offset:18432
	ds_read_b128 v[202:205], v161 offset:19456
	ds_read_b128 v[212:215], v161 offset:20480
	ds_read_b128 v[216:219], v161 offset:21504
	ds_read_b128 v[220:223], v161 offset:22528
	ds_read_b128 v[224:227], v161 offset:23552
	global_load_lds_dwordx4 v[148:149], off
	s_add_i32 m0, s92, 0x2000
	v_lshl_add_u64 v[152:153], s[96:97], 0, v[128:129]
	s_add_u32 s96, s96, s44
	s_addc_u32 s97, s97, s45
	s_add_i32 s85, s85, s11
	global_load_lds_dwordx4 v[152:153], off
	v_lshl_add_u64 v[206:207], s[96:97], 0, v[132:133]
	s_mov_b32 m0, s85
	v_lshl_add_u64 v[228:229], s[96:97], 0, v[128:129]
	global_load_lds_dwordx4 v[206:207], off
	s_add_i32 m0, s85, 0x2000
	v_lshl_add_u64 v[230:231], s[34:35], 0, v[134:135]
	global_load_lds_dwordx4 v[228:229], off
	s_mov_b32 m0, s61
	v_lshl_add_u64 v[232:233], s[34:35], 0, v[130:131]
	global_load_lds_dwordx4 v[230:231], off
	s_mov_b32 m0, s62
	s_nop 0
	global_load_lds_dwordx4 v[232:233], off
	s_waitcnt vmcnt(8)
	s_waitcnt lgkmcnt(0)
	s_barrier
	s_setprio 1
	s_waitcnt lgkmcnt(0)
	v_mfma_f32_16x16x32_bf16 v[60:63], v[142:145], v[190:193], 0
	v_mfma_f32_16x16x32_bf16 v[52:55], v[166:169], v[190:193], 0
	v_mfma_f32_16x16x32_bf16 v[44:47], v[142:145], v[198:201], 0
	v_mfma_f32_16x16x32_bf16 v[36:39], v[166:169], v[198:201], 0
	v_mfma_f32_16x16x32_bf16 v[28:31], v[142:145], v[212:215], 0
	v_mfma_f32_16x16x32_bf16 v[20:23], v[166:169], v[212:215], 0
	v_mfma_f32_16x16x32_bf16 v[12:15], v[142:145], v[220:223], 0
	v_mfma_f32_16x16x32_bf16 v[4:7], v[166:169], v[220:223], 0
	v_mfma_f32_16x16x32_bf16 v[60:63], v[162:165], v[194:197], v[60:63]
	v_mfma_f32_16x16x32_bf16 v[52:55], v[170:173], v[194:197], v[52:55]
	v_mfma_f32_16x16x32_bf16 v[44:47], v[162:165], v[202:205], v[44:47]
	v_mfma_f32_16x16x32_bf16 v[36:39], v[170:173], v[202:205], v[36:39]
	v_mfma_f32_16x16x32_bf16 v[28:31], v[162:165], v[216:219], v[28:31]
	v_mfma_f32_16x16x32_bf16 v[20:23], v[170:173], v[216:219], v[20:23]
	v_mfma_f32_16x16x32_bf16 v[12:15], v[162:165], v[224:227], v[12:15]
	v_mfma_f32_16x16x32_bf16 v[4:7], v[170:173], v[224:227], v[4:7]
	s_setprio 0
	s_setprio 1
	v_mfma_f32_16x16x32_bf16 v[56:59], v[174:177], v[190:193], 0
	v_mfma_f32_16x16x32_bf16 v[48:51], v[182:185], v[190:193], 0
	v_mfma_f32_16x16x32_bf16 v[40:43], v[174:177], v[198:201], 0
	v_mfma_f32_16x16x32_bf16 v[32:35], v[182:185], v[198:201], 0
	v_mfma_f32_16x16x32_bf16 v[24:27], v[174:177], v[212:215], 0
	v_mfma_f32_16x16x32_bf16 v[16:19], v[182:185], v[212:215], 0
	v_mfma_f32_16x16x32_bf16 v[8:11], v[174:177], v[220:223], 0
	v_mfma_f32_16x16x32_bf16 v[0:3], v[182:185], v[220:223], 0
	v_mfma_f32_16x16x32_bf16 v[56:59], v[178:181], v[194:197], v[56:59]
	v_mfma_f32_16x16x32_bf16 v[48:51], v[186:189], v[194:197], v[48:51]
	v_mfma_f32_16x16x32_bf16 v[40:43], v[178:181], v[202:205], v[40:43]
	v_mfma_f32_16x16x32_bf16 v[32:35], v[186:189], v[202:205], v[32:35]
	v_mfma_f32_16x16x32_bf16 v[24:27], v[178:181], v[216:219], v[24:27]
	v_mfma_f32_16x16x32_bf16 v[16:19], v[186:189], v[216:219], v[16:19]
	v_mfma_f32_16x16x32_bf16 v[8:11], v[178:181], v[224:227], v[8:11]
	v_mfma_f32_16x16x32_bf16 v[0:3], v[186:189], v[224:227], v[0:3]
	s_setprio 0
	s_barrier
; #define PG8_STAGE(bufoff, gbase, voff) do { _Pragma("unroll") for (int _i = 0; _i < 2; ++_i) \
;         __builtin_amdgcn_global_load_lds((const unsigned*)((const char*)(gbase) + (voff)[_i]), (PG8_LAS unsigned*)(lds + (bufoff) + ldsw + _i * 8192), 16, 0, 0); } while (0)
; #define PG8_LDA(dst, b, h) do { _Pragma("unroll") for (int m = 0; m < 4; ++m) _Pragma("unroll") for (int k = 0; k < 2; ++k) dst[m][k] = *(const PG8_LAS bf16x8*)(lds + PG8_SA(b, h) + aoff + m * 2048 + k * 1024); } while (0)
; #define PG8_LDB(dst, b, h) do { _Pragma("unroll") for (int n = 0; n < 2; ++n) _Pragma("unroll") for (int k = 0; k < 2; ++k) dst[n][k] = *(const PG8_LAS bf16x8*)(lds + PG8_SB(b, h) + boff + n * 2048 + k * 1024); } while (0)
; #define PG8_MMA(ai, bj, At, Bt) do { __builtin_amdgcn_s_setprio(1); _Pragma("unroll") for (int m = 0; m < 4; ++m) _Pragma("unroll") for (int n = 0; n < 2; ++n) _Pragma("unroll") for (int k = 0; k < 2; ++k) \
;         acc[ai][bj][m][n] = mma16<Epi::F16>(Bt[n][k], At[m][k], acc[ai][bj][m][n]); __builtin_amdgcn_s_setprio(0); } while (0)
; #define PG8_WAIT_V(n) asm volatile("s_waitcnt vmcnt(" #n ")" ::: "memory")
; #define PG8_WAIT_L(n) asm volatile("s_waitcnt lgkmcnt(" #n ")" ::: "memory")
; #define PG8_BAR __builtin_amdgcn_s_barrier()
; #define PG8_SCHED __builtin_amdgcn_sched_barrier(0)
; template <class Epi, class Sched, bool ALIGN_EPI = false, bool SP2 = false>
; __device__ __forceinline__ void gemm_phase(PG8_LAS unsigned char* lds, const Gemm g, const Sched& S, const Epi& E) {
;     ...
;             PG8_LDB(B0, 1, 0); PG8_LDB(B1, 1, 1); PG8_SCHED; PG8_LDA(At, 1, 0); PG8_STAGE(PG8_SA(0, 1), a2 + hstep, voffA);
;             PG8_WAIT_V(8); PG8_WAIT_L(0); PG8_BAR; PG8_MMA(0, 0, At, B0); PG8_MMA(0, 1, At, B1); PG8_BAR; PG8_SCHED;
	s_add_i32 s85, 0, 0x18000
	v_add_u32_e32 v146, s85, v151
	s_add_i32 s92, 0, 0x1c000
	ds_read_b128 v[142:145], v146
	ds_read_b128 v[162:165], v146 offset:1024
	ds_read_b128 v[166:169], v146 offset:2048
	ds_read_b128 v[170:173], v146 offset:3072
	v_add_u32_e32 v146, s92, v151
	ds_read_b128 v[174:177], v146
	ds_read_b128 v[178:181], v146 offset:1024
	ds_read_b128 v[182:185], v146 offset:2048
	ds_read_b128 v[186:189], v146 offset:3072
	s_add_u32 s34, s34, s44
	s_addc_u32 s35, s35, s45
	s_mov_b32 m0, s63
	v_lshl_add_u64 v[234:235], s[34:35], 0, v[134:135]
	ds_read_b128 v[190:193], v161 offset:32768
	ds_read_b128 v[194:197], v161 offset:33792
	ds_read_b128 v[198:201], v161 offset:34816
	ds_read_b128 v[202:205], v161 offset:35840
	ds_read_b128 v[212:215], v161 offset:36864
	ds_read_b128 v[216:219], v161 offset:37888
	ds_read_b128 v[220:223], v161 offset:38912
	ds_read_b128 v[224:227], v161 offset:39936
	global_load_lds_dwordx4 v[234:235], off
	v_lshl_add_u64 v[234:235], s[34:35], 0, v[130:131]
	s_mov_b32 m0, s64
	s_nop 0
	global_load_lds_dwordx4 v[234:235], off
	s_waitcnt vmcnt(8)
	s_waitcnt lgkmcnt(0)
	s_barrier
	s_setprio 1
	s_waitcnt lgkmcnt(0)
	v_mfma_f32_16x16x32_bf16 v[120:123], v[142:145], v[190:193], v[120:123]
	v_mfma_f32_16x16x32_bf16 v[116:119], v[166:169], v[190:193], v[116:119]
	v_mfma_f32_16x16x32_bf16 v[108:111], v[142:145], v[198:201], v[108:111]
	v_mfma_f32_16x16x32_bf16 v[100:103], v[166:169], v[198:201], v[100:103]
	v_mfma_f32_16x16x32_bf16 v[92:95], v[142:145], v[212:215], v[92:95]
	v_mfma_f32_16x16x32_bf16 v[84:87], v[166:169], v[212:215], v[84:87]
	v_mfma_f32_16x16x32_bf16 v[76:79], v[142:145], v[220:223], v[76:79]
	v_mfma_f32_16x16x32_bf16 v[68:71], v[166:169], v[220:223], v[68:71]
	v_mfma_f32_16x16x32_bf16 v[120:123], v[162:165], v[194:197], v[120:123]
	v_mfma_f32_16x16x32_bf16 v[116:119], v[170:173], v[194:197], v[116:119]
	v_mfma_f32_16x16x32_bf16 v[108:111], v[162:165], v[202:205], v[108:111]
	v_mfma_f32_16x16x32_bf16 v[100:103], v[170:173], v[202:205], v[100:103]
	v_mfma_f32_16x16x32_bf16 v[92:95], v[162:165], v[216:219], v[92:95]
	v_mfma_f32_16x16x32_bf16 v[84:87], v[170:173], v[216:219], v[84:87]
	v_mfma_f32_16x16x32_bf16 v[76:79], v[162:165], v[224:227], v[76:79]
	v_mfma_f32_16x16x32_bf16 v[68:71], v[170:173], v[224:227], v[68:71]
	s_setprio 0
	s_setprio 1
	v_mfma_f32_16x16x32_bf16 v[124:127], v[174:177], v[190:193], v[124:127]
	v_mfma_f32_16x16x32_bf16 v[112:115], v[182:185], v[190:193], v[112:115]
	v_mfma_f32_16x16x32_bf16 v[104:107], v[174:177], v[198:201], v[104:107]
	v_mfma_f32_16x16x32_bf16 v[96:99], v[182:185], v[198:201], v[96:99]
	v_mfma_f32_16x16x32_bf16 v[88:91], v[174:177], v[212:215], v[88:91]
	v_mfma_f32_16x16x32_bf16 v[80:83], v[182:185], v[212:215], v[80:83]
	v_mfma_f32_16x16x32_bf16 v[72:75], v[174:177], v[220:223], v[72:75]
	v_mfma_f32_16x16x32_bf16 v[64:67], v[182:185], v[220:223], v[64:67]
	v_mfma_f32_16x16x32_bf16 v[124:127], v[178:181], v[194:197], v[124:127]
	v_mfma_f32_16x16x32_bf16 v[112:115], v[186:189], v[194:197], v[112:115]
	v_mfma_f32_16x16x32_bf16 v[104:107], v[178:181], v[202:205], v[104:107]
	v_mfma_f32_16x16x32_bf16 v[96:99], v[186:189], v[202:205], v[96:99]
	v_mfma_f32_16x16x32_bf16 v[88:91], v[178:181], v[216:219], v[88:91]
	v_mfma_f32_16x16x32_bf16 v[80:83], v[186:189], v[216:219], v[80:83]
	v_mfma_f32_16x16x32_bf16 v[72:75], v[178:181], v[224:227], v[72:75]
	v_mfma_f32_16x16x32_bf16 v[64:67], v[186:189], v[224:227], v[64:67]
	s_setprio 0
	s_barrier
; #define PG8_STAGE(bufoff, gbase, voff) do { _Pragma("unroll") for (int _i = 0; _i < 2; ++_i) \
;         __builtin_amdgcn_global_load_lds((const unsigned*)((const char*)(gbase) + (voff)[_i]), (PG8_LAS unsigned*)(lds + (bufoff) + ldsw + _i * 8192), 16, 0, 0); } while (0)
; #define PG8_LDA(dst, b, h) do { _Pragma("unroll") for (int m = 0; m < 4; ++m) _Pragma("unroll") for (int k = 0; k < 2; ++k) dst[m][k] = *(const PG8_LAS bf16x8*)(lds + PG8_SA(b, h) + aoff + m * 2048 + k * 1024); } while (0)
; #define PG8_MMA(ai, bj, At, Bt) do { __builtin_amdgcn_s_setprio(1); _Pragma("unroll") for (int m = 0; m < 4; ++m) _Pragma("unroll") for (int n = 0; n < 2; ++n) _Pragma("unroll") for (int k = 0; k < 2; ++k) \
;         acc[ai][bj][m][n] = mma16<Epi::F16>(Bt[n][k], At[m][k], acc[ai][bj][m][n]); __builtin_amdgcn_s_setprio(0); } while (0)
; #define PG8_WAIT_V(n) asm volatile("s_waitcnt vmcnt(" #n ")" ::: "memory")
; #define PG8_WAIT_L(n) asm volatile("s_waitcnt lgkmcnt(" #n ")" ::: "memory")
; #define PG8_BAR __builtin_amdgcn_s_barrier()
; #define PG8_SCHED __builtin_amdgcn_sched_barrier(0)
; template <class Epi, class Sched, bool ALIGN_EPI = false, bool SP2 = false>
; __device__ __forceinline__ void gemm_phase(PG8_LAS unsigned char* lds, const Gemm g, const Sched& S, const Epi& E) {
;     ...
;         for (int t = 0; t < nt; t += 2) {
;             const bool last = (t == nt - 2);
;             const char* a1 = cA + (size_t)(t + 1) * kstep;
;             const char* a2 = last ? nA : cA + (size_t)(t + 2) * kstep; const char* b2 = last ? nB : cB + (size_t)(t + 2) * kstep;
;             const char* a3 = a2 + kstep; const char* b3 = b2 + kstep;
;     ...
;             PG8_LDA(At, 1, 1); PG8_STAGE(PG8_SB(1, 0), b3, voffB); PG8_STAGE(PG8_SB(1, 1), b3 + hstep, voffB); PG8_STAGE(PG8_SA(1, 0), a3, voffA);
;             PG8_WAIT_V(8); PG8_WAIT_L(0); PG8_BAR; PG8_MMA(1, 0, At, B0); PG8_MMA(1, 1, At, B1); PG8_BAR; PG8_SCHED;
	s_add_i32 s34, s85, s11
	v_lshl_add_u64 v[148:149], v[148:149], 0, s[20:21]
	s_mov_b32 m0, s34
	ds_read_b128 v[190:193], v161 offset:49152
	ds_read_b128 v[194:197], v161 offset:50176
	ds_read_b128 v[198:201], v161 offset:51200
	ds_read_b128 v[202:205], v161 offset:52224
	ds_read_b128 v[212:215], v161 offset:53248
	ds_read_b128 v[216:219], v161 offset:54272
	ds_read_b128 v[220:223], v161 offset:55296
	ds_read_b128 v[224:227], v161 offset:56320
	global_load_lds_dwordx4 v[148:149], off
	v_lshl_add_u64 v[148:149], v[152:153], 0, s[20:21]
	s_add_i32 m0, s34, 0x2000
	s_add_i32 s34, s92, s11
	global_load_lds_dwordx4 v[148:149], off
	v_lshl_add_u64 v[148:149], v[206:207], 0, s[20:21]
	s_mov_b32 m0, s34
	s_nop 0
	global_load_lds_dwordx4 v[148:149], off
	v_lshl_add_u64 v[148:149], v[228:229], 0, s[20:21]
	s_add_i32 m0, s34, 0x2000
	s_nop 0
	global_load_lds_dwordx4 v[148:149], off
	v_lshl_add_u64 v[148:149], v[230:231], 0, s[20:21]
	s_mov_b32 m0, s65
	s_nop 0
	global_load_lds_dwordx4 v[148:149], off
	v_lshl_add_u64 v[148:149], v[232:233], 0, s[20:21]
	s_mov_b32 m0, s66
	s_nop 0
	global_load_lds_dwordx4 v[148:149], off
	s_waitcnt vmcnt(8)
	s_waitcnt lgkmcnt(0)
	s_barrier
	s_setprio 1
	s_waitcnt lgkmcnt(0)
	v_mfma_f32_16x16x32_bf16 v[60:63], v[142:145], v[190:193], v[60:63]
	v_mfma_f32_16x16x32_bf16 v[52:55], v[166:169], v[190:193], v[52:55]
	v_mfma_f32_16x16x32_bf16 v[44:47], v[142:145], v[198:201], v[44:47]
	v_mfma_f32_16x16x32_bf16 v[36:39], v[166:169], v[198:201], v[36:39]
	v_mfma_f32_16x16x32_bf16 v[28:31], v[142:145], v[212:215], v[28:31]
	v_mfma_f32_16x16x32_bf16 v[20:23], v[166:169], v[212:215], v[20:23]
	v_mfma_f32_16x16x32_bf16 v[12:15], v[142:145], v[220:223], v[12:15]
	v_mfma_f32_16x16x32_bf16 v[4:7], v[166:169], v[220:223], v[4:7]
	v_mfma_f32_16x16x32_bf16 v[60:63], v[162:165], v[194:197], v[60:63]
	v_mfma_f32_16x16x32_bf16 v[52:55], v[170:173], v[194:197], v[52:55]
	v_mfma_f32_16x16x32_bf16 v[44:47], v[162:165], v[202:205], v[44:47]
	v_mfma_f32_16x16x32_bf16 v[36:39], v[170:173], v[202:205], v[36:39]
	v_mfma_f32_16x16x32_bf16 v[28:31], v[162:165], v[216:219], v[28:31]
	v_mfma_f32_16x16x32_bf16 v[20:23], v[170:173], v[216:219], v[20:23]
	v_mfma_f32_16x16x32_bf16 v[12:15], v[162:165], v[224:227], v[12:15]
	v_mfma_f32_16x16x32_bf16 v[4:7], v[170:173], v[224:227], v[4:7]
	s_setprio 0
	s_setprio 1
	v_mfma_f32_16x16x32_bf16 v[56:59], v[174:177], v[190:193], v[56:59]
	v_mfma_f32_16x16x32_bf16 v[48:51], v[182:185], v[190:193], v[48:51]
	v_mfma_f32_16x16x32_bf16 v[40:43], v[174:177], v[198:201], v[40:43]
	v_mfma_f32_16x16x32_bf16 v[32:35], v[182:185], v[198:201], v[32:35]
	v_mfma_f32_16x16x32_bf16 v[24:27], v[174:177], v[212:215], v[24:27]
	v_mfma_f32_16x16x32_bf16 v[16:19], v[182:185], v[212:215], v[16:19]
	v_mfma_f32_16x16x32_bf16 v[8:11], v[174:177], v[220:223], v[8:11]
	v_mfma_f32_16x16x32_bf16 v[0:3], v[182:185], v[220:223], v[0:3]
	v_mfma_f32_16x16x32_bf16 v[56:59], v[178:181], v[194:197], v[56:59]
	v_mfma_f32_16x16x32_bf16 v[48:51], v[186:189], v[194:197], v[48:51]
	v_mfma_f32_16x16x32_bf16 v[40:43], v[178:181], v[202:205], v[40:43]
	v_mfma_f32_16x16x32_bf16 v[32:35], v[186:189], v[202:205], v[32:35]
	v_mfma_f32_16x16x32_bf16 v[24:27], v[178:181], v[216:219], v[24:27]
	v_mfma_f32_16x16x32_bf16 v[16:19], v[186:189], v[216:219], v[16:19]
	v_mfma_f32_16x16x32_bf16 v[8:11], v[178:181], v[224:227], v[8:11]
	v_mfma_f32_16x16x32_bf16 v[0:3], v[186:189], v[224:227], v[0:3]
	s_setprio 0
	s_barrier
	s_add_u32 s30, s30, 0x100
	s_addc_u32 s31, s31, 0
	s_add_u32 s77, s77, 0x100
	s_addc_u32 s82, s82, 0
	s_cmp_ge_i32 s84, s67
	s_mov_b32 s34, s84
	s_cbranch_scc0 .LBB0_191
	s_branch .LBB0_192

; #define PG8_STAGE(bufoff, gbase, voff) do { _Pragma("unroll") for (int _i = 0; _i < 2; ++_i) \
;         __builtin_amdgcn_global_load_lds((const unsigned*)((const char*)(gbase) + (voff)[_i]), (PG8_LAS unsigned*)(lds + (bufoff) + ldsw + _i * 8192), 16, 0, 0); } while (0)
; #define PG8_LDA(dst, b, h) do { _Pragma("unroll") for (int m = 0; m < 4; ++m) _Pragma("unroll") for (int k = 0; k < 2; ++k) dst[m][k] = *(const PG8_LAS bf16x8*)(lds + PG8_SA(b, h) + aoff + m * 2048 + k * 1024); } while (0)
; #define PG8_LDB(dst, b, h) do { _Pragma("unroll") for (int n = 0; n < 2; ++n) _Pragma("unroll") for (int k = 0; k < 2; ++k) dst[n][k] = *(const PG8_LAS bf16x8*)(lds + PG8_SB(b, h) + boff + n * 2048 + k * 1024); } while (0)
; #define PG8_SCHED __builtin_amdgcn_sched_barrier(0)
; template <class Epi, class Sched, bool ALIGN_EPI = false, bool SP2 = false>
; __device__ __forceinline__ void gemm_phase(PG8_LAS unsigned char* lds, const Gemm g, const Sched& S, const Epi& E) {
;     ...
;     f32x4 acc[2][2][4][2];
; #pragma unroll
;     for (int a = 0; a < 2; ++a)
; #pragma unroll
;         for (int b = 0; b < 2; ++b)
; #pragma unroll
;             for (int m = 0; m < 4; ++m)
; #pragma unroll
;                 for (int n = 0; n < 2; ++n) acc[a][b][m][n] = (f32x4){0.f, 0.f, 0.f, 0.f};
;     ...
;         const bool has_next = S.next(ui + 1, nxt);
;         const char* nA = has_next ? (const char*)g.A + (size_t)nxt.pm * tstep : cA; const char* nB = has_next ? (const char*)g.Bt + (size_t)nxt.pn * tstep : cB;
;         for (int t = 0; t < nt; t += 2) {
;             const bool last = (t == nt - 2);
;             const char* a1 = cA + (size_t)(t + 1) * kstep;
;             const char* a2 = last ? nA : cA + (size_t)(t + 2) * kstep; const char* b2 = last ? nB : cB + (size_t)(t + 2) * kstep;
;             const char* a3 = a2 + kstep; const char* b3 = b2 + kstep;
;             if (last && has_next) S.a_ready(nxt);
;             if constexpr (SP2) {
;             PG8_LDB(B0, 0, 0); PG8_LDB(B1, 0, 1); PG8_SCHED; PG8_LDA(At, 0, 0); PG8_STAGE(PG8_SA(1, 1), a1 + hstep, voffA);
.LBB0_310:
	s_andn2_b64 vcc, exec, s[56:57]
	s_cbranch_vccz .Lpeel_k2
	v_mov_b32_e32 v123, 0
	v_mov_b32_e32 v122, v123
	v_mov_b32_e32 v121, v123
	v_mov_b32_e32 v120, v123
	v_mov_b32_e32 v127, v123
	v_mov_b32_e32 v126, v123
	v_mov_b32_e32 v125, v123
	v_mov_b32_e32 v124, v123
	v_mov_b32_e32 v111, v123
	v_mov_b32_e32 v110, v123
	v_mov_b32_e32 v109, v123
	v_mov_b32_e32 v108, v123
	v_mov_b32_e32 v107, v123
	v_mov_b32_e32 v106, v123
	v_mov_b32_e32 v105, v123
	v_mov_b32_e32 v104, v123
	v_mov_b32_e32 v95, v123
	v_mov_b32_e32 v94, v123
	v_mov_b32_e32 v93, v123
	v_mov_b32_e32 v92, v123
	v_mov_b32_e32 v91, v123
	v_mov_b32_e32 v90, v123
	v_mov_b32_e32 v89, v123
	v_mov_b32_e32 v88, v123
	v_mov_b32_e32 v79, v123
	v_mov_b32_e32 v78, v123
	v_mov_b32_e32 v77, v123
	v_mov_b32_e32 v76, v123
	v_mov_b32_e32 v75, v123
	v_mov_b32_e32 v74, v123
	v_mov_b32_e32 v73, v123
	v_mov_b32_e32 v72, v123
	v_mov_b32_e32 v119, v123
	v_mov_b32_e32 v118, v123
	v_mov_b32_e32 v117, v123
	v_mov_b32_e32 v116, v123
	v_mov_b32_e32 v115, v123
	v_mov_b32_e32 v114, v123
	v_mov_b32_e32 v113, v123
	v_mov_b32_e32 v112, v123
	v_mov_b32_e32 v103, v123
	v_mov_b32_e32 v102, v123
	v_mov_b32_e32 v101, v123
	v_mov_b32_e32 v100, v123
	v_mov_b32_e32 v99, v123
	v_mov_b32_e32 v98, v123
	v_mov_b32_e32 v97, v123
	v_mov_b32_e32 v96, v123
	v_mov_b32_e32 v87, v123
	v_mov_b32_e32 v86, v123
	v_mov_b32_e32 v85, v123
	v_mov_b32_e32 v84, v123
	v_mov_b32_e32 v83, v123
	v_mov_b32_e32 v82, v123
	v_mov_b32_e32 v81, v123
	v_mov_b32_e32 v80, v123
	v_mov_b32_e32 v71, v123
	v_mov_b32_e32 v70, v123
	v_mov_b32_e32 v69, v123
	v_mov_b32_e32 v68, v123
	v_mov_b32_e32 v67, v123
	v_mov_b32_e32 v66, v123
	v_mov_b32_e32 v65, v123
	v_mov_b32_e32 v64, v123
	v_mov_b32_e32 v63, v123
	v_mov_b32_e32 v62, v123
	v_mov_b32_e32 v61, v123
	v_mov_b32_e32 v60, v123
	v_mov_b32_e32 v59, v123
	v_mov_b32_e32 v58, v123
	v_mov_b32_e32 v57, v123
	v_mov_b32_e32 v56, v123
	v_mov_b32_e32 v47, v123
	v_mov_b32_e32 v46, v123
	v_mov_b32_e32 v45, v123
	v_mov_b32_e32 v44, v123
	v_mov_b32_e32 v43, v123
	v_mov_b32_e32 v42, v123
	v_mov_b32_e32 v41, v123
	v_mov_b32_e32 v40, v123
	v_mov_b32_e32 v31, v123
	v_mov_b32_e32 v30, v123
	v_mov_b32_e32 v29, v123
	v_mov_b32_e32 v28, v123
	v_mov_b32_e32 v27, v123
	v_mov_b32_e32 v26, v123
	v_mov_b32_e32 v25, v123
	v_mov_b32_e32 v24, v123
	v_mov_b32_e32 v15, v123
	v_mov_b32_e32 v14, v123
	v_mov_b32_e32 v13, v123
	v_mov_b32_e32 v12, v123
	v_mov_b32_e32 v11, v123
	v_mov_b32_e32 v10, v123
	v_mov_b32_e32 v9, v123
	v_mov_b32_e32 v8, v123
	v_mov_b32_e32 v55, v123
	v_mov_b32_e32 v54, v123
	v_mov_b32_e32 v53, v123
	v_mov_b32_e32 v52, v123
	v_mov_b32_e32 v51, v123
	v_mov_b32_e32 v50, v123
	v_mov_b32_e32 v49, v123
	v_mov_b32_e32 v48, v123
	v_mov_b32_e32 v39, v123
	v_mov_b32_e32 v38, v123
	v_mov_b32_e32 v37, v123
	v_mov_b32_e32 v36, v123
	v_mov_b32_e32 v35, v123
	v_mov_b32_e32 v34, v123
	v_mov_b32_e32 v33, v123
	v_mov_b32_e32 v32, v123
	v_mov_b32_e32 v23, v123
	v_mov_b32_e32 v22, v123
	v_mov_b32_e32 v21, v123
	v_mov_b32_e32 v20, v123
	v_mov_b32_e32 v19, v123
	v_mov_b32_e32 v18, v123
	v_mov_b32_e32 v17, v123
	v_mov_b32_e32 v16, v123
	v_mov_b32_e32 v7, v123
	v_mov_b32_e32 v6, v123
	v_mov_b32_e32 v5, v123
	v_mov_b32_e32 v4, v123
	v_mov_b32_e32 v3, v123
	v_mov_b32_e32 v2, v123
	v_mov_b32_e32 v1, v123
	v_mov_b32_e32 v0, v123
	s_branch .LBB0_313
.Lpeel_k2:
	s_add_u32 s30, s30, 0x80
	s_addc_u32 s31, s31, 0
	s_add_u32 s29, s34, 0x100
	s_addc_u32 s85, s35, 0
	s_mov_b32 s34, 0
	s_add_i32 s92, s34, 2
	s_add_u32 s96, s30, 0x80
	s_addc_u32 s35, s31, 0
	s_add_i32 vcc_lo, 0, 0x10000
	s_cmp_eq_u32 s65, s34
	s_cselect_b32 s35, s1, s35
	s_cselect_b32 s34, s0, s96
	s_cselect_b32 s97, s61, s85
	s_cselect_b32 s96, s60, s29
	s_add_i32 vcc_hi, 0, 0x14000
	v_add_u32_e32 v150, vcc_lo, v131
	v_add_u32_e32 v166, vcc_hi, v131
	ds_read_b128 v[138:141], v150
	ds_read_b128 v[142:145], v150 offset:1024
	ds_read_b128 v[146:149], v150 offset:2048
	ds_read_b128 v[150:153], v150 offset:3072
	ds_read_b128 v[154:157], v166
	ds_read_b128 v[158:161], v166 offset:1024
	ds_read_b128 v[162:165], v166 offset:2048
	ds_read_b128 v[166:169], v166 offset:3072
	v_lshl_add_u64 v[190:191], s[30:31], 0, v[134:135]
	s_add_i32 m0, s8, 0xc000
	ds_read_b128 v[170:173], v199
	ds_read_b128 v[174:177], v199 offset:1024
	ds_read_b128 v[178:181], v199 offset:2048
	ds_read_b128 v[182:185], v199 offset:3072
	ds_read_b128 v[186:189], v199 offset:4096
	ds_read_b128 v[200:203], v199 offset:5120
	ds_read_b128 v[204:207], v199 offset:6144
	ds_read_b128 v[212:215], v199 offset:7168
	global_load_lds_dwordx4 v[190:191], off
	v_lshl_add_u64 v[190:191], s[30:31], 0, v[136:137]
	s_add_i32 m0, s8, 0xe000
	s_nop 0
	global_load_lds_dwordx4 v[190:191], off
	s_waitcnt vmcnt(8)
	s_waitcnt lgkmcnt(0)
	s_barrier
; #define PG8_STAGE(bufoff, gbase, voff) do { _Pragma("unroll") for (int _i = 0; _i < 2; ++_i) \
;         __builtin_amdgcn_global_load_lds((const unsigned*)((const char*)(gbase) + (voff)[_i]), (PG8_LAS unsigned*)(lds + (bufoff) + ldsw + _i * 8192), 16, 0, 0); } while (0)
; #define PG8_LDA(dst, b, h) do { _Pragma("unroll") for (int m = 0; m < 4; ++m) _Pragma("unroll") for (int k = 0; k < 2; ++k) dst[m][k] = *(const PG8_LAS bf16x8*)(lds + PG8_SA(b, h) + aoff + m * 2048 + k * 1024); } while (0)
; #define PG8_MMA(ai, bj, At, Bt) do { __builtin_amdgcn_s_setprio(1); _Pragma("unroll") for (int m = 0; m < 4; ++m) _Pragma("unroll") for (int n = 0; n < 2; ++n) _Pragma("unroll") for (int k = 0; k < 2; ++k) \
;         acc[ai][bj][m][n] = mma16<Epi::F16>(Bt[n][k], At[m][k], acc[ai][bj][m][n]); __builtin_amdgcn_s_setprio(0); } while (0)
; #define PG8_WAIT_V(n) asm volatile("s_waitcnt vmcnt(" #n ")" ::: "memory")
; #define PG8_WAIT_L(n) asm volatile("s_waitcnt lgkmcnt(" #n ")" ::: "memory")
; #define PG8_BAR __builtin_amdgcn_s_barrier()
; #define PG8_SCHED __builtin_amdgcn_sched_barrier(0)
; template <class Epi, class Sched, bool ALIGN_EPI = false, bool SP2 = false>
; __device__ __forceinline__ void gemm_phase(PG8_LAS unsigned char* lds, const Gemm g, const Sched& S, const Epi& E) {
;     ...
;             PG8_WAIT_V(8); PG8_WAIT_L(0); PG8_BAR; PG8_MMA(0, 0, At, B0); PG8_MMA(0, 1, At, B1); PG8_BAR; PG8_SCHED;
;             PG8_LDA(At, 0, 1); PG8_STAGE(PG8_SB(0, 0), b2, voffB); PG8_STAGE(PG8_SB(0, 1), b2 + hstep, voffB); PG8_STAGE(PG8_SA(0, 0), a2, voffA);
;             PG8_WAIT_V(8); PG8_WAIT_L(0); PG8_BAR; PG8_MMA(1, 0, At, B0); PG8_MMA(1, 1, At, B1); PG8_BAR; PG8_SCHED;
	s_setprio 1
	s_waitcnt lgkmcnt(0)
	v_mfma_f32_16x16x32_bf16 v[120:123], v[138:141], v[170:173], 0
	v_mfma_f32_16x16x32_bf16 v[124:127], v[146:149], v[170:173], 0
	v_mfma_f32_16x16x32_bf16 v[108:111], v[138:141], v[178:181], 0
	v_mfma_f32_16x16x32_bf16 v[104:107], v[146:149], v[178:181], 0
	v_mfma_f32_16x16x32_bf16 v[92:95], v[138:141], v[186:189], 0
	v_mfma_f32_16x16x32_bf16 v[88:91], v[146:149], v[186:189], 0
	v_mfma_f32_16x16x32_bf16 v[76:79], v[138:141], v[204:207], 0
	v_mfma_f32_16x16x32_bf16 v[72:75], v[146:149], v[204:207], 0
	v_mfma_f32_16x16x32_bf16 v[120:123], v[142:145], v[174:177], v[120:123]
	v_mfma_f32_16x16x32_bf16 v[124:127], v[150:153], v[174:177], v[124:127]
	v_mfma_f32_16x16x32_bf16 v[108:111], v[142:145], v[182:185], v[108:111]
	v_mfma_f32_16x16x32_bf16 v[104:107], v[150:153], v[182:185], v[104:107]
	v_mfma_f32_16x16x32_bf16 v[92:95], v[142:145], v[200:203], v[92:95]
	v_mfma_f32_16x16x32_bf16 v[88:91], v[150:153], v[200:203], v[88:91]
	v_mfma_f32_16x16x32_bf16 v[76:79], v[142:145], v[212:215], v[76:79]
	v_mfma_f32_16x16x32_bf16 v[72:75], v[150:153], v[212:215], v[72:75]
	s_setprio 0
	s_setprio 1
	v_mfma_f32_16x16x32_bf16 v[116:119], v[154:157], v[170:173], 0
	v_mfma_f32_16x16x32_bf16 v[112:115], v[162:165], v[170:173], 0
	v_mfma_f32_16x16x32_bf16 v[100:103], v[154:157], v[178:181], 0
	v_mfma_f32_16x16x32_bf16 v[96:99], v[162:165], v[178:181], 0
	v_mfma_f32_16x16x32_bf16 v[84:87], v[154:157], v[186:189], 0
	v_mfma_f32_16x16x32_bf16 v[80:83], v[162:165], v[186:189], 0
	v_mfma_f32_16x16x32_bf16 v[68:71], v[154:157], v[204:207], 0
	v_mfma_f32_16x16x32_bf16 v[64:67], v[162:165], v[204:207], 0
	v_mfma_f32_16x16x32_bf16 v[116:119], v[158:161], v[174:177], v[116:119]
	v_mfma_f32_16x16x32_bf16 v[112:115], v[166:169], v[174:177], v[112:115]
	v_mfma_f32_16x16x32_bf16 v[100:103], v[158:161], v[182:185], v[100:103]
	v_mfma_f32_16x16x32_bf16 v[96:99], v[166:169], v[182:185], v[96:99]
	v_mfma_f32_16x16x32_bf16 v[84:87], v[158:161], v[200:203], v[84:87]
	v_mfma_f32_16x16x32_bf16 v[80:83], v[166:169], v[200:203], v[80:83]
	v_mfma_f32_16x16x32_bf16 v[68:71], v[158:161], v[212:215], v[68:71]
	v_mfma_f32_16x16x32_bf16 v[64:67], v[166:169], v[212:215], v[64:67]
	s_setprio 0
	s_barrier
	s_add_i32 vcc_lo, vcc_lo, s3
	v_lshl_add_u64 v[190:191], s[96:97], 0, v[208:209]
	s_mov_b32 m0, vcc_lo
	ds_read_b128 v[170:173], v199 offset:16384
	ds_read_b128 v[174:177], v199 offset:17408
	ds_read_b128 v[178:181], v199 offset:18432
	ds_read_b128 v[182:185], v199 offset:19456
	ds_read_b128 v[186:189], v199 offset:20480
	ds_read_b128 v[200:203], v199 offset:21504
	ds_read_b128 v[204:207], v199 offset:22528
	ds_read_b128 v[212:215], v199 offset:23552
	global_load_lds_dwordx4 v[190:191], off
	s_add_i32 m0, vcc_lo, 0x2000
	v_lshl_add_u64 v[194:195], s[96:97], 0, v[128:129]
	s_add_u32 s96, s96, s50
	s_addc_u32 s97, s97, s51
	s_add_i32 vcc_lo, vcc_hi, s3
	global_load_lds_dwordx4 v[194:195], off
	v_lshl_add_u64 v[216:217], s[96:97], 0, v[208:209]
	s_mov_b32 m0, vcc_lo
	v_lshl_add_u64 v[218:219], s[96:97], 0, v[128:129]
	global_load_lds_dwordx4 v[216:217], off
	s_add_i32 m0, vcc_lo, 0x2000
	v_lshl_add_u64 v[220:221], s[34:35], 0, v[208:209]
	global_load_lds_dwordx4 v[218:219], off
	s_mov_b32 m0, s8
	v_lshl_add_u64 v[222:223], s[34:35], 0, v[128:129]
	global_load_lds_dwordx4 v[220:221], off
	s_mov_b32 m0, s9
	s_nop 0
	global_load_lds_dwordx4 v[222:223], off
	s_waitcnt vmcnt(8)
	s_waitcnt lgkmcnt(0)
	s_barrier
	s_setprio 1
	s_waitcnt lgkmcnt(0)
	v_mfma_f32_16x16x32_bf16 v[60:63], v[138:141], v[170:173], 0
	v_mfma_f32_16x16x32_bf16 v[56:59], v[146:149], v[170:173], 0
	v_mfma_f32_16x16x32_bf16 v[44:47], v[138:141], v[178:181], 0
	v_mfma_f32_16x16x32_bf16 v[40:43], v[146:149], v[178:181], 0
	v_mfma_f32_16x16x32_bf16 v[28:31], v[138:141], v[186:189], 0
	v_mfma_f32_16x16x32_bf16 v[24:27], v[146:149], v[186:189], 0
	v_mfma_f32_16x16x32_bf16 v[12:15], v[138:141], v[204:207], 0
	v_mfma_f32_16x16x32_bf16 v[8:11], v[146:149], v[204:207], 0
	v_mfma_f32_16x16x32_bf16 v[60:63], v[142:145], v[174:177], v[60:63]
	v_mfma_f32_16x16x32_bf16 v[56:59], v[150:153], v[174:177], v[56:59]
	v_mfma_f32_16x16x32_bf16 v[44:47], v[142:145], v[182:185], v[44:47]
	v_mfma_f32_16x16x32_bf16 v[40:43], v[150:153], v[182:185], v[40:43]
	v_mfma_f32_16x16x32_bf16 v[28:31], v[142:145], v[200:203], v[28:31]
	v_mfma_f32_16x16x32_bf16 v[24:27], v[150:153], v[200:203], v[24:27]
	v_mfma_f32_16x16x32_bf16 v[12:15], v[142:145], v[212:215], v[12:15]
	v_mfma_f32_16x16x32_bf16 v[8:11], v[150:153], v[212:215], v[8:11]
	s_setprio 0
	s_setprio 1
	v_mfma_f32_16x16x32_bf16 v[52:55], v[154:157], v[170:173], 0
	v_mfma_f32_16x16x32_bf16 v[48:51], v[162:165], v[170:173], 0
	v_mfma_f32_16x16x32_bf16 v[36:39], v[154:157], v[178:181], 0
	v_mfma_f32_16x16x32_bf16 v[32:35], v[162:165], v[178:181], 0
	v_mfma_f32_16x16x32_bf16 v[20:23], v[154:157], v[186:189], 0
	v_mfma_f32_16x16x32_bf16 v[16:19], v[162:165], v[186:189], 0
	v_mfma_f32_16x16x32_bf16 v[4:7], v[154:157], v[204:207], 0
	v_mfma_f32_16x16x32_bf16 v[0:3], v[162:165], v[204:207], 0
	v_mfma_f32_16x16x32_bf16 v[52:55], v[158:161], v[174:177], v[52:55]
	v_mfma_f32_16x16x32_bf16 v[48:51], v[166:169], v[174:177], v[48:51]
	v_mfma_f32_16x16x32_bf16 v[36:39], v[158:161], v[182:185], v[36:39]
	v_mfma_f32_16x16x32_bf16 v[32:35], v[166:169], v[182:185], v[32:35]
	v_mfma_f32_16x16x32_bf16 v[20:23], v[158:161], v[200:203], v[20:23]
	v_mfma_f32_16x16x32_bf16 v[16:19], v[166:169], v[200:203], v[16:19]
	v_mfma_f32_16x16x32_bf16 v[4:7], v[158:161], v[212:215], v[4:7]
	v_mfma_f32_16x16x32_bf16 v[0:3], v[166:169], v[212:215], v[0:3]
	s_setprio 0
	s_barrier
; #define PG8_STAGE(bufoff, gbase, voff) do { _Pragma("unroll") for (int _i = 0; _i < 2; ++_i) \
;         __builtin_amdgcn_global_load_lds((const unsigned*)((const char*)(gbase) + (voff)[_i]), (PG8_LAS unsigned*)(lds + (bufoff) + ldsw + _i * 8192), 16, 0, 0); } while (0)
; #define PG8_LDA(dst, b, h) do { _Pragma("unroll") for (int m = 0; m < 4; ++m) _Pragma("unroll") for (int k = 0; k < 2; ++k) dst[m][k] = *(const PG8_LAS bf16x8*)(lds + PG8_SA(b, h) + aoff + m * 2048 + k * 1024); } while (0)
; #define PG8_LDB(dst, b, h) do { _Pragma("unroll") for (int n = 0; n < 2; ++n) _Pragma("unroll") for (int k = 0; k < 2; ++k) dst[n][k] = *(const PG8_LAS bf16x8*)(lds + PG8_SB(b, h) + boff + n * 2048 + k * 1024); } while (0)
; #define PG8_MMA(ai, bj, At, Bt) do { __builtin_amdgcn_s_setprio(1); _Pragma("unroll") for (int m = 0; m < 4; ++m) _Pragma("unroll") for (int n = 0; n < 2; ++n) _Pragma("unroll") for (int k = 0; k < 2; ++k) \
;         acc[ai][bj][m][n] = mma16<Epi::F16>(Bt[n][k], At[m][k], acc[ai][bj][m][n]); __builtin_amdgcn_s_setprio(0); } while (0)
; #define PG8_WAIT_V(n) asm volatile("s_waitcnt vmcnt(" #n ")" ::: "memory")
; #define PG8_WAIT_L(n) asm volatile("s_waitcnt lgkmcnt(" #n ")" ::: "memory")
; #define PG8_BAR __builtin_amdgcn_s_barrier()
; #define PG8_SCHED __builtin_amdgcn_sched_barrier(0)
; template <class Epi, class Sched, bool ALIGN_EPI = false, bool SP2 = false>
; __device__ __forceinline__ void gemm_phase(PG8_LAS unsigned char* lds, const Gemm g, const Sched& S, const Epi& E) {
;     ...
;             PG8_LDB(B0, 1, 0); PG8_LDB(B1, 1, 1); PG8_SCHED; PG8_LDA(At, 1, 0); PG8_STAGE(PG8_SA(0, 1), a2 + hstep, voffA);
;             PG8_WAIT_V(8); PG8_WAIT_L(0); PG8_BAR; PG8_MMA(0, 0, At, B0); PG8_MMA(0, 1, At, B1); PG8_BAR; PG8_SCHED;
	s_add_i32 s96, 0, 0x18000
	s_add_i32 s97, 0, 0x1c000
	v_add_u32_e32 v150, s96, v131
	v_add_u32_e32 v166, s97, v131
	ds_read_b128 v[138:141], v150
	ds_read_b128 v[142:145], v150 offset:1024
	ds_read_b128 v[146:149], v150 offset:2048
	ds_read_b128 v[150:153], v150 offset:3072
	ds_read_b128 v[154:157], v166
	ds_read_b128 v[158:161], v166 offset:1024
	ds_read_b128 v[162:165], v166 offset:2048
	ds_read_b128 v[166:169], v166 offset:3072
	s_add_u32 s34, s34, s50
	s_addc_u32 s35, s35, s51
	s_mov_b32 m0, s11
	v_lshl_add_u64 v[224:225], s[34:35], 0, v[208:209]
	ds_read_b128 v[170:173], v199 offset:32768
	ds_read_b128 v[174:177], v199 offset:33792
	ds_read_b128 v[178:181], v199 offset:34816
	ds_read_b128 v[182:185], v199 offset:35840
	ds_read_b128 v[186:189], v199 offset:36864
	ds_read_b128 v[200:203], v199 offset:37888
	ds_read_b128 v[204:207], v199 offset:38912
	ds_read_b128 v[212:215], v199 offset:39936
	global_load_lds_dwordx4 v[224:225], off
	v_lshl_add_u64 v[224:225], s[34:35], 0, v[128:129]
	s_mov_b32 m0, s36
	s_nop 0
	global_load_lds_dwordx4 v[224:225], off
	s_waitcnt vmcnt(8)
	s_waitcnt lgkmcnt(0)
	s_barrier
	s_setprio 1
	s_waitcnt lgkmcnt(0)
	v_mfma_f32_16x16x32_bf16 v[120:123], v[138:141], v[170:173], v[120:123]
	v_mfma_f32_16x16x32_bf16 v[124:127], v[146:149], v[170:173], v[124:127]
	v_mfma_f32_16x16x32_bf16 v[108:111], v[138:141], v[178:181], v[108:111]
	v_mfma_f32_16x16x32_bf16 v[104:107], v[146:149], v[178:181], v[104:107]
	v_mfma_f32_16x16x32_bf16 v[92:95], v[138:141], v[186:189], v[92:95]
	v_mfma_f32_16x16x32_bf16 v[88:91], v[146:149], v[186:189], v[88:91]
	v_mfma_f32_16x16x32_bf16 v[76:79], v[138:141], v[204:207], v[76:79]
	v_mfma_f32_16x16x32_bf16 v[72:75], v[146:149], v[204:207], v[72:75]
	v_mfma_f32_16x16x32_bf16 v[120:123], v[142:145], v[174:177], v[120:123]
	v_mfma_f32_16x16x32_bf16 v[124:127], v[150:153], v[174:177], v[124:127]
	v_mfma_f32_16x16x32_bf16 v[108:111], v[142:145], v[182:185], v[108:111]
	v_mfma_f32_16x16x32_bf16 v[104:107], v[150:153], v[182:185], v[104:107]
	v_mfma_f32_16x16x32_bf16 v[92:95], v[142:145], v[200:203], v[92:95]
	v_mfma_f32_16x16x32_bf16 v[88:91], v[150:153], v[200:203], v[88:91]
	v_mfma_f32_16x16x32_bf16 v[76:79], v[142:145], v[212:215], v[76:79]
	v_mfma_f32_16x16x32_bf16 v[72:75], v[150:153], v[212:215], v[72:75]
	s_setprio 0
	s_setprio 1
	v_mfma_f32_16x16x32_bf16 v[116:119], v[154:157], v[170:173], v[116:119]
	v_mfma_f32_16x16x32_bf16 v[112:115], v[162:165], v[170:173], v[112:115]
	v_mfma_f32_16x16x32_bf16 v[100:103], v[154:157], v[178:181], v[100:103]
	v_mfma_f32_16x16x32_bf16 v[96:99], v[162:165], v[178:181], v[96:99]
	v_mfma_f32_16x16x32_bf16 v[84:87], v[154:157], v[186:189], v[84:87]
	v_mfma_f32_16x16x32_bf16 v[80:83], v[162:165], v[186:189], v[80:83]
	v_mfma_f32_16x16x32_bf16 v[68:71], v[154:157], v[204:207], v[68:71]
	v_mfma_f32_16x16x32_bf16 v[64:67], v[162:165], v[204:207], v[64:67]
	v_mfma_f32_16x16x32_bf16 v[116:119], v[158:161], v[174:177], v[116:119]
	v_mfma_f32_16x16x32_bf16 v[112:115], v[166:169], v[174:177], v[112:115]
	v_mfma_f32_16x16x32_bf16 v[100:103], v[158:161], v[182:185], v[100:103]
	v_mfma_f32_16x16x32_bf16 v[96:99], v[166:169], v[182:185], v[96:99]
	v_mfma_f32_16x16x32_bf16 v[84:87], v[158:161], v[200:203], v[84:87]
	v_mfma_f32_16x16x32_bf16 v[80:83], v[166:169], v[200:203], v[80:83]
	v_mfma_f32_16x16x32_bf16 v[68:71], v[158:161], v[212:215], v[68:71]
	v_mfma_f32_16x16x32_bf16 v[64:67], v[166:169], v[212:215], v[64:67]
	s_setprio 0
	s_barrier
; #define PG8_STAGE(bufoff, gbase, voff) do { _Pragma("unroll") for (int _i = 0; _i < 2; ++_i) \
;         __builtin_amdgcn_global_load_lds((const unsigned*)((const char*)(gbase) + (voff)[_i]), (PG8_LAS unsigned*)(lds + (bufoff) + ldsw + _i * 8192), 16, 0, 0); } while (0)
; #define PG8_LDA(dst, b, h) do { _Pragma("unroll") for (int m = 0; m < 4; ++m) _Pragma("unroll") for (int k = 0; k < 2; ++k) dst[m][k] = *(const PG8_LAS bf16x8*)(lds + PG8_SA(b, h) + aoff + m * 2048 + k * 1024); } while (0)
; #define PG8_MMA(ai, bj, At, Bt) do { __builtin_amdgcn_s_setprio(1); _Pragma("unroll") for (int m = 0; m < 4; ++m) _Pragma("unroll") for (int n = 0; n < 2; ++n) _Pragma("unroll") for (int k = 0; k < 2; ++k) \
;         acc[ai][bj][m][n] = mma16<Epi::F16>(Bt[n][k], At[m][k], acc[ai][bj][m][n]); __builtin_amdgcn_s_setprio(0); } while (0)
; #define PG8_WAIT_V(n) asm volatile("s_waitcnt vmcnt(" #n ")" ::: "memory")
; #define PG8_WAIT_L(n) asm volatile("s_waitcnt lgkmcnt(" #n ")" ::: "memory")
; #define PG8_BAR __builtin_amdgcn_s_barrier()
; #define PG8_SCHED __builtin_amdgcn_sched_barrier(0)
; template <class Epi, class Sched, bool ALIGN_EPI = false, bool SP2 = false>
; __device__ __forceinline__ void gemm_phase(PG8_LAS unsigned char* lds, const Gemm g, const Sched& S, const Epi& E) {
;     ...
;         for (int t = 0; t < nt; t += 2) {
;             const bool last = (t == nt - 2);
;             const char* a1 = cA + (size_t)(t + 1) * kstep;
;             const char* a2 = last ? nA : cA + (size_t)(t + 2) * kstep; const char* b2 = last ? nB : cB + (size_t)(t + 2) * kstep;
;             const char* a3 = a2 + kstep; const char* b3 = b2 + kstep;
;     ...
;             PG8_LDA(At, 1, 1); PG8_STAGE(PG8_SB(1, 0), b3, voffB); PG8_STAGE(PG8_SB(1, 1), b3 + hstep, voffB); PG8_STAGE(PG8_SA(1, 0), a3, voffA);
;             PG8_WAIT_V(8); PG8_WAIT_L(0); PG8_BAR; PG8_MMA(1, 0, At, B0); PG8_MMA(1, 1, At, B1); PG8_BAR; PG8_SCHED;
	s_add_i32 s34, s96, s3
	v_lshl_add_u64 v[190:191], v[190:191], 0, s[20:21]
	s_mov_b32 m0, s34
	ds_read_b128 v[170:173], v199 offset:49152
	ds_read_b128 v[174:177], v199 offset:50176
	ds_read_b128 v[178:181], v199 offset:51200
	ds_read_b128 v[182:185], v199 offset:52224
	ds_read_b128 v[186:189], v199 offset:53248
	ds_read_b128 v[200:203], v199 offset:54272
	ds_read_b128 v[204:207], v199 offset:55296
	ds_read_b128 v[212:215], v199 offset:56320
	global_load_lds_dwordx4 v[190:191], off
	v_lshl_add_u64 v[190:191], v[194:195], 0, s[20:21]
	s_add_i32 m0, s34, 0x2000
	s_add_i32 s34, s97, s3
	global_load_lds_dwordx4 v[190:191], off
	v_lshl_add_u64 v[190:191], v[216:217], 0, s[20:21]
	s_mov_b32 m0, s34
	s_nop 0
	global_load_lds_dwordx4 v[190:191], off
	v_lshl_add_u64 v[190:191], v[218:219], 0, s[20:21]
	s_add_i32 m0, s34, 0x2000
	s_nop 0
	global_load_lds_dwordx4 v[190:191], off
	v_lshl_add_u64 v[190:191], v[220:221], 0, s[20:21]
	s_mov_b32 m0, s48
	s_nop 0
	global_load_lds_dwordx4 v[190:191], off
	v_lshl_add_u64 v[190:191], v[222:223], 0, s[20:21]
	s_mov_b32 m0, s64
	s_nop 0
	global_load_lds_dwordx4 v[190:191], off
	s_waitcnt vmcnt(8)
	s_waitcnt lgkmcnt(0)
	s_barrier
	s_setprio 1
	s_waitcnt lgkmcnt(0)
	v_mfma_f32_16x16x32_bf16 v[60:63], v[138:141], v[170:173], v[60:63]
	v_mfma_f32_16x16x32_bf16 v[56:59], v[146:149], v[170:173], v[56:59]
	v_mfma_f32_16x16x32_bf16 v[44:47], v[138:141], v[178:181], v[44:47]
	v_mfma_f32_16x16x32_bf16 v[40:43], v[146:149], v[178:181], v[40:43]
	v_mfma_f32_16x16x32_bf16 v[28:31], v[138:141], v[186:189], v[28:31]
	v_mfma_f32_16x16x32_bf16 v[24:27], v[146:149], v[186:189], v[24:27]
	v_mfma_f32_16x16x32_bf16 v[12:15], v[138:141], v[204:207], v[12:15]
	v_mfma_f32_16x16x32_bf16 v[8:11], v[146:149], v[204:207], v[8:11]
	v_mfma_f32_16x16x32_bf16 v[60:63], v[142:145], v[174:177], v[60:63]
	v_mfma_f32_16x16x32_bf16 v[56:59], v[150:153], v[174:177], v[56:59]
	v_mfma_f32_16x16x32_bf16 v[44:47], v[142:145], v[182:185], v[44:47]
	v_mfma_f32_16x16x32_bf16 v[40:43], v[150:153], v[182:185], v[40:43]
	v_mfma_f32_16x16x32_bf16 v[28:31], v[142:145], v[200:203], v[28:31]
	v_mfma_f32_16x16x32_bf16 v[24:27], v[150:153], v[200:203], v[24:27]
	v_mfma_f32_16x16x32_bf16 v[12:15], v[142:145], v[212:215], v[12:15]
	v_mfma_f32_16x16x32_bf16 v[8:11], v[150:153], v[212:215], v[8:11]
	s_setprio 0
	s_setprio 1
	v_mfma_f32_16x16x32_bf16 v[52:55], v[154:157], v[170:173], v[52:55]
	v_mfma_f32_16x16x32_bf16 v[48:51], v[162:165], v[170:173], v[48:51]
	v_mfma_f32_16x16x32_bf16 v[36:39], v[154:157], v[178:181], v[36:39]
	v_mfma_f32_16x16x32_bf16 v[32:35], v[162:165], v[178:181], v[32:35]
	v_mfma_f32_16x16x32_bf16 v[20:23], v[154:157], v[186:189], v[20:23]
	v_mfma_f32_16x16x32_bf16 v[16:19], v[162:165], v[186:189], v[16:19]
	v_mfma_f32_16x16x32_bf16 v[4:7], v[154:157], v[204:207], v[4:7]
	v_mfma_f32_16x16x32_bf16 v[0:3], v[162:165], v[204:207], v[0:3]
	v_mfma_f32_16x16x32_bf16 v[52:55], v[158:161], v[174:177], v[52:55]
	v_mfma_f32_16x16x32_bf16 v[48:51], v[166:169], v[174:177], v[48:51]
	v_mfma_f32_16x16x32_bf16 v[36:39], v[158:161], v[182:185], v[36:39]
	v_mfma_f32_16x16x32_bf16 v[32:35], v[166:169], v[182:185], v[32:35]
	v_mfma_f32_16x16x32_bf16 v[20:23], v[158:161], v[200:203], v[20:23]
	v_mfma_f32_16x16x32_bf16 v[16:19], v[166:169], v[200:203], v[16:19]
	v_mfma_f32_16x16x32_bf16 v[4:7], v[158:161], v[212:215], v[4:7]
	v_mfma_f32_16x16x32_bf16 v[0:3], v[166:169], v[212:215], v[0:3]
	s_setprio 0
	s_barrier
	s_add_u32 s30, s30, 0x100
	s_addc_u32 s31, s31, 0
	s_add_u32 s29, s29, 0x100
	s_addc_u32 s85, s85, 0
	s_cmp_ge_i32 s92, s37
	s_mov_b32 s34, s92
	s_cbranch_scc0 .LBB0_312
	s_branch .LBB0_313

; #define PG8_STAGE(bufoff, gbase, voff) do { _Pragma("unroll") for (int _i = 0; _i < 2; ++_i) \
;         __builtin_amdgcn_global_load_lds((const unsigned*)((const char*)(gbase) + (voff)[_i]), (PG8_LAS unsigned*)(lds + (bufoff) + ldsw + _i * 8192), 16, 0, 0); } while (0)
; #define PG8_LDA(dst, b, h) do { _Pragma("unroll") for (int m = 0; m < 4; ++m) _Pragma("unroll") for (int k = 0; k < 2; ++k) dst[m][k] = *(const PG8_LAS bf16x8*)(lds + PG8_SA(b, h) + aoff + m * 2048 + k * 1024); } while (0)
; #define PG8_LDB(dst, b, h) do { _Pragma("unroll") for (int n = 0; n < 2; ++n) _Pragma("unroll") for (int k = 0; k < 2; ++k) dst[n][k] = *(const PG8_LAS bf16x8*)(lds + PG8_SB(b, h) + boff + n * 2048 + k * 1024); } while (0)
; #define PG8_SCHED __builtin_amdgcn_sched_barrier(0)
; template <class Epi, class Sched, bool ALIGN_EPI = false, bool SP2 = false>
; __device__ __forceinline__ void gemm_phase(PG8_LAS unsigned char* lds, const Gemm g, const Sched& S, const Epi& E) {
;     ...
;     f32x4 acc[2][2][4][2];
; #pragma unroll
;     for (int a = 0; a < 2; ++a)
; #pragma unroll
;         for (int b = 0; b < 2; ++b)
; #pragma unroll
;             for (int m = 0; m < 4; ++m)
; #pragma unroll
;                 for (int n = 0; n < 2; ++n) acc[a][b][m][n] = (f32x4){0.f, 0.f, 0.f, 0.f};
;     ...
;         const bool has_next = S.next(ui + 1, nxt);
;         const char* nA = has_next ? (const char*)g.A + (size_t)nxt.pm * tstep : cA; const char* nB = has_next ? (const char*)g.Bt + (size_t)nxt.pn * tstep : cB;
;         for (int t = 0; t < nt; t += 2) {
;             const bool last = (t == nt - 2);
;             const char* a1 = cA + (size_t)(t + 1) * kstep;
;             const char* a2 = last ? nA : cA + (size_t)(t + 2) * kstep; const char* b2 = last ? nB : cB + (size_t)(t + 2) * kstep;
;             const char* a3 = a2 + kstep; const char* b3 = b2 + kstep;
;             if (last && has_next) S.a_ready(nxt);
;             if constexpr (SP2) {
;             PG8_LDB(B0, 0, 0); PG8_LDB(B1, 0, 1); PG8_SCHED; PG8_LDA(At, 0, 0); PG8_STAGE(PG8_SA(1, 1), a1 + hstep, voffA);
.LBB0_367:
	s_waitcnt vmcnt(0)
	s_andn2_b64 vcc, exec, s[16:17]
	s_cbranch_vccz .Lpeel_k3
	v_mov_b32_e32 v127, 0
	v_mov_b32_e32 v126, v127
	v_mov_b32_e32 v125, v127
	v_mov_b32_e32 v124, v127
	v_mov_b32_e32 v123, v127
	v_mov_b32_e32 v122, v127
	v_mov_b32_e32 v121, v127
	v_mov_b32_e32 v120, v127
	v_mov_b32_e32 v111, v127
	v_mov_b32_e32 v110, v127
	v_mov_b32_e32 v109, v127
	v_mov_b32_e32 v108, v127
	v_mov_b32_e32 v107, v127
	v_mov_b32_e32 v106, v127
	v_mov_b32_e32 v105, v127
	v_mov_b32_e32 v104, v127
	v_mov_b32_e32 v95, v127
	v_mov_b32_e32 v94, v127
	v_mov_b32_e32 v93, v127
	v_mov_b32_e32 v92, v127
	v_mov_b32_e32 v91, v127
	v_mov_b32_e32 v90, v127
	v_mov_b32_e32 v89, v127
	v_mov_b32_e32 v88, v127
	v_mov_b32_e32 v79, v127
	v_mov_b32_e32 v78, v127
	v_mov_b32_e32 v77, v127
	v_mov_b32_e32 v76, v127
	v_mov_b32_e32 v75, v127
	v_mov_b32_e32 v74, v127
	v_mov_b32_e32 v73, v127
	v_mov_b32_e32 v72, v127
	v_mov_b32_e32 v119, v127
	v_mov_b32_e32 v118, v127
	v_mov_b32_e32 v117, v127
	v_mov_b32_e32 v116, v127
	v_mov_b32_e32 v115, v127
	v_mov_b32_e32 v114, v127
	v_mov_b32_e32 v113, v127
	v_mov_b32_e32 v112, v127
	v_mov_b32_e32 v103, v127
	v_mov_b32_e32 v102, v127
	v_mov_b32_e32 v101, v127
	v_mov_b32_e32 v100, v127
	v_mov_b32_e32 v99, v127
	v_mov_b32_e32 v98, v127
	v_mov_b32_e32 v97, v127
	v_mov_b32_e32 v96, v127
	v_mov_b32_e32 v87, v127
	v_mov_b32_e32 v86, v127
	v_mov_b32_e32 v85, v127
	v_mov_b32_e32 v84, v127
	v_mov_b32_e32 v83, v127
	v_mov_b32_e32 v82, v127
	v_mov_b32_e32 v81, v127
	v_mov_b32_e32 v80, v127
	v_mov_b32_e32 v71, v127
	v_mov_b32_e32 v70, v127
	v_mov_b32_e32 v69, v127
	v_mov_b32_e32 v68, v127
	v_mov_b32_e32 v67, v127
	v_mov_b32_e32 v66, v127
	v_mov_b32_e32 v65, v127
	v_mov_b32_e32 v64, v127
	v_mov_b32_e32 v63, v127
	v_mov_b32_e32 v62, v127
	v_mov_b32_e32 v61, v127
	v_mov_b32_e32 v60, v127
	v_mov_b32_e32 v59, v127
	v_mov_b32_e32 v58, v127
	v_mov_b32_e32 v57, v127
	v_mov_b32_e32 v56, v127
	v_mov_b32_e32 v47, v127
	v_mov_b32_e32 v46, v127
	v_mov_b32_e32 v45, v127
	v_mov_b32_e32 v44, v127
	v_mov_b32_e32 v43, v127
	v_mov_b32_e32 v42, v127
	v_mov_b32_e32 v41, v127
	v_mov_b32_e32 v40, v127
	v_mov_b32_e32 v31, v127
	v_mov_b32_e32 v30, v127
	v_mov_b32_e32 v29, v127
	v_mov_b32_e32 v28, v127
	v_mov_b32_e32 v27, v127
	v_mov_b32_e32 v26, v127
	v_mov_b32_e32 v25, v127
	v_mov_b32_e32 v24, v127
	v_mov_b32_e32 v15, v127
	v_mov_b32_e32 v14, v127
	v_mov_b32_e32 v13, v127
	v_mov_b32_e32 v12, v127
	v_mov_b32_e32 v11, v127
	v_mov_b32_e32 v10, v127
	v_mov_b32_e32 v9, v127
	v_mov_b32_e32 v8, v127
	v_mov_b32_e32 v55, v127
	v_mov_b32_e32 v54, v127
	v_mov_b32_e32 v53, v127
	v_mov_b32_e32 v52, v127
	v_mov_b32_e32 v51, v127
	v_mov_b32_e32 v50, v127
	v_mov_b32_e32 v49, v127
	v_mov_b32_e32 v48, v127
	v_mov_b32_e32 v39, v127
	v_mov_b32_e32 v38, v127
	v_mov_b32_e32 v37, v127
	v_mov_b32_e32 v36, v127
	v_mov_b32_e32 v35, v127
	v_mov_b32_e32 v34, v127
	v_mov_b32_e32 v33, v127
	v_mov_b32_e32 v32, v127
	v_mov_b32_e32 v23, v127
	v_mov_b32_e32 v22, v127
	v_mov_b32_e32 v21, v127
	v_mov_b32_e32 v20, v127
	v_mov_b32_e32 v19, v127
	v_mov_b32_e32 v18, v127
	v_mov_b32_e32 v17, v127
	v_mov_b32_e32 v16, v127
	v_mov_b32_e32 v7, v127
	v_mov_b32_e32 v6, v127
	v_mov_b32_e32 v5, v127
	v_mov_b32_e32 v4, v127
	v_mov_b32_e32 v3, v127
	v_mov_b32_e32 v2, v127
	v_mov_b32_e32 v1, v127
	v_mov_b32_e32 v0, v127
	s_branch .LBB0_370
.Lpeel_k3:
	s_add_u32 s30, s30, 0x80
	s_addc_u32 s31, s31, 0
	s_add_u32 s29, s34, 0x100
	s_addc_u32 s85, s35, 0
	s_mov_b32 s34, 0
	s_add_i32 s92, s34, 2
	s_add_u32 s96, s30, 0x80
	s_addc_u32 s35, s31, 0
	s_add_i32 vcc_lo, 0, 0x10000
	s_cmp_eq_u32 s37, s34
	s_cselect_b32 s35, s1, s35
	s_cselect_b32 s34, s0, s96
	s_cselect_b32 s97, s27, s85
	s_cselect_b32 s96, s26, s29
	s_add_i32 vcc_hi, 0, 0x14000
	v_add_u32_e32 v140, vcc_lo, v197
	v_add_u32_e32 v156, vcc_hi, v197
	ds_read_b128 v[128:131], v140
	ds_read_b128 v[132:135], v140 offset:1024
	ds_read_b128 v[136:139], v140 offset:2048
	ds_read_b128 v[140:143], v140 offset:3072
	ds_read_b128 v[144:147], v156
	ds_read_b128 v[148:151], v156 offset:1024
	ds_read_b128 v[152:155], v156 offset:2048
	ds_read_b128 v[156:159], v156 offset:3072
	v_lshl_add_u64 v[204:205], s[30:31], 0, v[200:201]
	s_add_i32 m0, s8, 0xc000
	ds_read_b128 v[160:163], v230
	ds_read_b128 v[164:167], v230 offset:1024
	ds_read_b128 v[168:171], v230 offset:2048
	ds_read_b128 v[172:175], v230 offset:3072
	ds_read_b128 v[176:179], v230 offset:4096
	ds_read_b128 v[180:183], v230 offset:5120
	ds_read_b128 v[184:187], v230 offset:6144
	ds_read_b128 v[188:191], v230 offset:7168
	global_load_lds_dwordx4 v[204:205], off
	v_lshl_add_u64 v[204:205], s[30:31], 0, v[202:203]
	s_add_i32 m0, s8, 0xe000
	s_nop 0
	global_load_lds_dwordx4 v[204:205], off
	s_waitcnt vmcnt(8)
	s_waitcnt lgkmcnt(0)
	s_barrier
; #define PG8_STAGE(bufoff, gbase, voff) do { _Pragma("unroll") for (int _i = 0; _i < 2; ++_i) \
;         __builtin_amdgcn_global_load_lds((const unsigned*)((const char*)(gbase) + (voff)[_i]), (PG8_LAS unsigned*)(lds + (bufoff) + ldsw + _i * 8192), 16, 0, 0); } while (0)
; #define PG8_LDA(dst, b, h) do { _Pragma("unroll") for (int m = 0; m < 4; ++m) _Pragma("unroll") for (int k = 0; k < 2; ++k) dst[m][k] = *(const PG8_LAS bf16x8*)(lds + PG8_SA(b, h) + aoff + m * 2048 + k * 1024); } while (0)
; #define PG8_MMA(ai, bj, At, Bt) do { __builtin_amdgcn_s_setprio(1); _Pragma("unroll") for (int m = 0; m < 4; ++m) _Pragma("unroll") for (int n = 0; n < 2; ++n) _Pragma("unroll") for (int k = 0; k < 2; ++k) \
;         acc[ai][bj][m][n] = mma16<Epi::F16>(Bt[n][k], At[m][k], acc[ai][bj][m][n]); __builtin_amdgcn_s_setprio(0); } while (0)
; #define PG8_WAIT_V(n) asm volatile("s_waitcnt vmcnt(" #n ")" ::: "memory")
; #define PG8_WAIT_L(n) asm volatile("s_waitcnt lgkmcnt(" #n ")" ::: "memory")
; #define PG8_BAR __builtin_amdgcn_s_barrier()
; #define PG8_SCHED __builtin_amdgcn_sched_barrier(0)
; template <class Epi, class Sched, bool ALIGN_EPI = false, bool SP2 = false>
; __device__ __forceinline__ void gemm_phase(PG8_LAS unsigned char* lds, const Gemm g, const Sched& S, const Epi& E) {
;     ...
;             PG8_WAIT_V(8); PG8_WAIT_L(0); PG8_BAR; PG8_MMA(0, 0, At, B0); PG8_MMA(0, 1, At, B1); PG8_BAR; PG8_SCHED;
;             PG8_LDA(At, 0, 1); PG8_STAGE(PG8_SB(0, 0), b2, voffB); PG8_STAGE(PG8_SB(0, 1), b2 + hstep, voffB); PG8_STAGE(PG8_SA(0, 0), a2, voffA);
;             PG8_WAIT_V(8); PG8_WAIT_L(0); PG8_BAR; PG8_MMA(1, 0, At, B0); PG8_MMA(1, 1, At, B1); PG8_BAR; PG8_SCHED;
	s_setprio 1
	s_waitcnt lgkmcnt(0)
	v_mfma_f32_16x16x32_bf16 v[124:127], v[128:131], v[160:163], 0
	v_mfma_f32_16x16x32_bf16 v[120:123], v[136:139], v[160:163], 0
	v_mfma_f32_16x16x32_bf16 v[108:111], v[128:131], v[168:171], 0
	v_mfma_f32_16x16x32_bf16 v[104:107], v[136:139], v[168:171], 0
	v_mfma_f32_16x16x32_bf16 v[92:95], v[128:131], v[176:179], 0
	v_mfma_f32_16x16x32_bf16 v[88:91], v[136:139], v[176:179], 0
	v_mfma_f32_16x16x32_bf16 v[76:79], v[128:131], v[184:187], 0
	v_mfma_f32_16x16x32_bf16 v[72:75], v[136:139], v[184:187], 0
	v_mfma_f32_16x16x32_bf16 v[124:127], v[132:135], v[164:167], v[124:127]
	v_mfma_f32_16x16x32_bf16 v[120:123], v[140:143], v[164:167], v[120:123]
	v_mfma_f32_16x16x32_bf16 v[108:111], v[132:135], v[172:175], v[108:111]
	v_mfma_f32_16x16x32_bf16 v[104:107], v[140:143], v[172:175], v[104:107]
	v_mfma_f32_16x16x32_bf16 v[92:95], v[132:135], v[180:183], v[92:95]
	v_mfma_f32_16x16x32_bf16 v[88:91], v[140:143], v[180:183], v[88:91]
	v_mfma_f32_16x16x32_bf16 v[76:79], v[132:135], v[188:191], v[76:79]
	v_mfma_f32_16x16x32_bf16 v[72:75], v[140:143], v[188:191], v[72:75]
	s_setprio 0
	s_setprio 1
	v_mfma_f32_16x16x32_bf16 v[116:119], v[144:147], v[160:163], 0
	v_mfma_f32_16x16x32_bf16 v[112:115], v[152:155], v[160:163], 0
	v_mfma_f32_16x16x32_bf16 v[100:103], v[144:147], v[168:171], 0
	v_mfma_f32_16x16x32_bf16 v[96:99], v[152:155], v[168:171], 0
	v_mfma_f32_16x16x32_bf16 v[84:87], v[144:147], v[176:179], 0
	v_mfma_f32_16x16x32_bf16 v[80:83], v[152:155], v[176:179], 0
	v_mfma_f32_16x16x32_bf16 v[68:71], v[144:147], v[184:187], 0
	v_mfma_f32_16x16x32_bf16 v[64:67], v[152:155], v[184:187], 0
	v_mfma_f32_16x16x32_bf16 v[116:119], v[148:151], v[164:167], v[116:119]
	v_mfma_f32_16x16x32_bf16 v[112:115], v[156:159], v[164:167], v[112:115]
	v_mfma_f32_16x16x32_bf16 v[100:103], v[148:151], v[172:175], v[100:103]
	v_mfma_f32_16x16x32_bf16 v[96:99], v[156:159], v[172:175], v[96:99]
	v_mfma_f32_16x16x32_bf16 v[84:87], v[148:151], v[180:183], v[84:87]
	v_mfma_f32_16x16x32_bf16 v[80:83], v[156:159], v[180:183], v[80:83]
	v_mfma_f32_16x16x32_bf16 v[68:71], v[148:151], v[188:191], v[68:71]
	v_mfma_f32_16x16x32_bf16 v[64:67], v[156:159], v[188:191], v[64:67]
	s_setprio 0
	s_barrier
	s_add_i32 vcc_lo, vcc_lo, s3
	v_lshl_add_u64 v[204:205], s[96:97], 0, v[208:209]
	s_mov_b32 m0, vcc_lo
	ds_read_b128 v[160:163], v230 offset:16384
	ds_read_b128 v[164:167], v230 offset:17408
	ds_read_b128 v[168:171], v230 offset:18432
	ds_read_b128 v[172:175], v230 offset:19456
	ds_read_b128 v[176:179], v230 offset:20480
	ds_read_b128 v[180:183], v230 offset:21504
	ds_read_b128 v[184:187], v230 offset:22528
	ds_read_b128 v[188:191], v230 offset:23552
	global_load_lds_dwordx4 v[204:205], off
	s_add_i32 m0, vcc_lo, 0x2000
	v_lshl_add_u64 v[206:207], s[96:97], 0, v[194:195]
	s_add_u32 s96, s96, s50
	s_addc_u32 s97, s97, s51
	s_add_i32 vcc_lo, vcc_hi, s3
	global_load_lds_dwordx4 v[206:207], off
	v_lshl_add_u64 v[212:213], s[96:97], 0, v[208:209]
	s_mov_b32 m0, vcc_lo
	v_lshl_add_u64 v[214:215], s[96:97], 0, v[194:195]
	global_load_lds_dwordx4 v[212:213], off
	s_add_i32 m0, vcc_lo, 0x2000
	v_lshl_add_u64 v[216:217], s[34:35], 0, v[208:209]
	global_load_lds_dwordx4 v[214:215], off
	s_mov_b32 m0, s8
	v_lshl_add_u64 v[218:219], s[34:35], 0, v[194:195]
	global_load_lds_dwordx4 v[216:217], off
	s_mov_b32 m0, s9
	s_nop 0
	global_load_lds_dwordx4 v[218:219], off
	s_waitcnt vmcnt(8)
	s_waitcnt lgkmcnt(0)
	s_barrier
	s_setprio 1
	s_waitcnt lgkmcnt(0)
	v_mfma_f32_16x16x32_bf16 v[60:63], v[128:131], v[160:163], 0
	v_mfma_f32_16x16x32_bf16 v[56:59], v[136:139], v[160:163], 0
	v_mfma_f32_16x16x32_bf16 v[44:47], v[128:131], v[168:171], 0
	v_mfma_f32_16x16x32_bf16 v[40:43], v[136:139], v[168:171], 0
	v_mfma_f32_16x16x32_bf16 v[28:31], v[128:131], v[176:179], 0
	v_mfma_f32_16x16x32_bf16 v[24:27], v[136:139], v[176:179], 0
	v_mfma_f32_16x16x32_bf16 v[12:15], v[128:131], v[184:187], 0
	v_mfma_f32_16x16x32_bf16 v[8:11], v[136:139], v[184:187], 0
	v_mfma_f32_16x16x32_bf16 v[60:63], v[132:135], v[164:167], v[60:63]
	v_mfma_f32_16x16x32_bf16 v[56:59], v[140:143], v[164:167], v[56:59]
	v_mfma_f32_16x16x32_bf16 v[44:47], v[132:135], v[172:175], v[44:47]
	v_mfma_f32_16x16x32_bf16 v[40:43], v[140:143], v[172:175], v[40:43]
	v_mfma_f32_16x16x32_bf16 v[28:31], v[132:135], v[180:183], v[28:31]
	v_mfma_f32_16x16x32_bf16 v[24:27], v[140:143], v[180:183], v[24:27]
	v_mfma_f32_16x16x32_bf16 v[12:15], v[132:135], v[188:191], v[12:15]
	v_mfma_f32_16x16x32_bf16 v[8:11], v[140:143], v[188:191], v[8:11]
	s_setprio 0
	s_setprio 1
	v_mfma_f32_16x16x32_bf16 v[52:55], v[144:147], v[160:163], 0
	v_mfma_f32_16x16x32_bf16 v[48:51], v[152:155], v[160:163], 0
	v_mfma_f32_16x16x32_bf16 v[36:39], v[144:147], v[168:171], 0
	v_mfma_f32_16x16x32_bf16 v[32:35], v[152:155], v[168:171], 0
	v_mfma_f32_16x16x32_bf16 v[20:23], v[144:147], v[176:179], 0
	v_mfma_f32_16x16x32_bf16 v[16:19], v[152:155], v[176:179], 0
	v_mfma_f32_16x16x32_bf16 v[4:7], v[144:147], v[184:187], 0
	v_mfma_f32_16x16x32_bf16 v[0:3], v[152:155], v[184:187], 0
	v_mfma_f32_16x16x32_bf16 v[52:55], v[148:151], v[164:167], v[52:55]
	v_mfma_f32_16x16x32_bf16 v[48:51], v[156:159], v[164:167], v[48:51]
	v_mfma_f32_16x16x32_bf16 v[36:39], v[148:151], v[172:175], v[36:39]
	v_mfma_f32_16x16x32_bf16 v[32:35], v[156:159], v[172:175], v[32:35]
	v_mfma_f32_16x16x32_bf16 v[20:23], v[148:151], v[180:183], v[20:23]
	v_mfma_f32_16x16x32_bf16 v[16:19], v[156:159], v[180:183], v[16:19]
	v_mfma_f32_16x16x32_bf16 v[4:7], v[148:151], v[188:191], v[4:7]
	v_mfma_f32_16x16x32_bf16 v[0:3], v[156:159], v[188:191], v[0:3]
	s_setprio 0
	s_barrier
; #define PG8_STAGE(bufoff, gbase, voff) do { _Pragma("unroll") for (int _i = 0; _i < 2; ++_i) \
;         __builtin_amdgcn_global_load_lds((const unsigned*)((const char*)(gbase) + (voff)[_i]), (PG8_LAS unsigned*)(lds + (bufoff) + ldsw + _i * 8192), 16, 0, 0); } while (0)
; #define PG8_LDA(dst, b, h) do { _Pragma("unroll") for (int m = 0; m < 4; ++m) _Pragma("unroll") for (int k = 0; k < 2; ++k) dst[m][k] = *(const PG8_LAS bf16x8*)(lds + PG8_SA(b, h) + aoff + m * 2048 + k * 1024); } while (0)
; #define PG8_LDB(dst, b, h) do { _Pragma("unroll") for (int n = 0; n < 2; ++n) _Pragma("unroll") for (int k = 0; k < 2; ++k) dst[n][k] = *(const PG8_LAS bf16x8*)(lds + PG8_SB(b, h) + boff + n * 2048 + k * 1024); } while (0)
; #define PG8_MMA(ai, bj, At, Bt) do { __builtin_amdgcn_s_setprio(1); _Pragma("unroll") for (int m = 0; m < 4; ++m) _Pragma("unroll") for (int n = 0; n < 2; ++n) _Pragma("unroll") for (int k = 0; k < 2; ++k) \
;         acc[ai][bj][m][n] = mma16<Epi::F16>(Bt[n][k], At[m][k], acc[ai][bj][m][n]); __builtin_amdgcn_s_setprio(0); } while (0)
; #define PG8_WAIT_V(n) asm volatile("s_waitcnt vmcnt(" #n ")" ::: "memory")
; #define PG8_WAIT_L(n) asm volatile("s_waitcnt lgkmcnt(" #n ")" ::: "memory")
; #define PG8_BAR __builtin_amdgcn_s_barrier()
; #define PG8_SCHED __builtin_amdgcn_sched_barrier(0)
; template <class Epi, class Sched, bool ALIGN_EPI = false, bool SP2 = false>
; __device__ __forceinline__ void gemm_phase(PG8_LAS unsigned char* lds, const Gemm g, const Sched& S, const Epi& E) {
;     ...
;             PG8_LDB(B0, 1, 0); PG8_LDB(B1, 1, 1); PG8_SCHED; PG8_LDA(At, 1, 0); PG8_STAGE(PG8_SA(0, 1), a2 + hstep, voffA);
;             PG8_WAIT_V(8); PG8_WAIT_L(0); PG8_BAR; PG8_MMA(0, 0, At, B0); PG8_MMA(0, 1, At, B1); PG8_BAR; PG8_SCHED;
	s_add_i32 s96, 0, 0x18000
	s_add_i32 s97, 0, 0x1c000
	v_add_u32_e32 v140, s96, v197
	v_add_u32_e32 v156, s97, v197
	ds_read_b128 v[128:131], v140
	ds_read_b128 v[132:135], v140 offset:1024
	ds_read_b128 v[136:139], v140 offset:2048
	ds_read_b128 v[140:143], v140 offset:3072
	ds_read_b128 v[144:147], v156
	ds_read_b128 v[148:151], v156 offset:1024
	ds_read_b128 v[152:155], v156 offset:2048
	ds_read_b128 v[156:159], v156 offset:3072
	s_add_u32 s34, s34, s50
	s_addc_u32 s35, s35, s51
	s_mov_b32 m0, s11
	v_lshl_add_u64 v[220:221], s[34:35], 0, v[208:209]
	ds_read_b128 v[160:163], v230 offset:32768
	ds_read_b128 v[164:167], v230 offset:33792
	ds_read_b128 v[168:171], v230 offset:34816
	ds_read_b128 v[172:175], v230 offset:35840
	ds_read_b128 v[176:179], v230 offset:36864
	ds_read_b128 v[180:183], v230 offset:37888
	ds_read_b128 v[184:187], v230 offset:38912
	ds_read_b128 v[188:191], v230 offset:39936
	global_load_lds_dwordx4 v[220:221], off
	v_lshl_add_u64 v[220:221], s[34:35], 0, v[194:195]
	s_mov_b32 m0, s36
	s_nop 0
	global_load_lds_dwordx4 v[220:221], off
	s_waitcnt vmcnt(8)
	s_waitcnt lgkmcnt(0)
	s_barrier
	s_setprio 1
	s_waitcnt lgkmcnt(0)
	v_mfma_f32_16x16x32_bf16 v[124:127], v[128:131], v[160:163], v[124:127]
	v_mfma_f32_16x16x32_bf16 v[120:123], v[136:139], v[160:163], v[120:123]
	v_mfma_f32_16x16x32_bf16 v[108:111], v[128:131], v[168:171], v[108:111]
	v_mfma_f32_16x16x32_bf16 v[104:107], v[136:139], v[168:171], v[104:107]
	v_mfma_f32_16x16x32_bf16 v[92:95], v[128:131], v[176:179], v[92:95]
	v_mfma_f32_16x16x32_bf16 v[88:91], v[136:139], v[176:179], v[88:91]
	v_mfma_f32_16x16x32_bf16 v[76:79], v[128:131], v[184:187], v[76:79]
	v_mfma_f32_16x16x32_bf16 v[72:75], v[136:139], v[184:187], v[72:75]
	v_mfma_f32_16x16x32_bf16 v[124:127], v[132:135], v[164:167], v[124:127]
	v_mfma_f32_16x16x32_bf16 v[120:123], v[140:143], v[164:167], v[120:123]
	v_mfma_f32_16x16x32_bf16 v[108:111], v[132:135], v[172:175], v[108:111]
	v_mfma_f32_16x16x32_bf16 v[104:107], v[140:143], v[172:175], v[104:107]
	v_mfma_f32_16x16x32_bf16 v[92:95], v[132:135], v[180:183], v[92:95]
	v_mfma_f32_16x16x32_bf16 v[88:91], v[140:143], v[180:183], v[88:91]
	v_mfma_f32_16x16x32_bf16 v[76:79], v[132:135], v[188:191], v[76:79]
	v_mfma_f32_16x16x32_bf16 v[72:75], v[140:143], v[188:191], v[72:75]
	s_setprio 0
	s_setprio 1
	v_mfma_f32_16x16x32_bf16 v[116:119], v[144:147], v[160:163], v[116:119]
	v_mfma_f32_16x16x32_bf16 v[112:115], v[152:155], v[160:163], v[112:115]
	v_mfma_f32_16x16x32_bf16 v[100:103], v[144:147], v[168:171], v[100:103]
	v_mfma_f32_16x16x32_bf16 v[96:99], v[152:155], v[168:171], v[96:99]
	v_mfma_f32_16x16x32_bf16 v[84:87], v[144:147], v[176:179], v[84:87]
	v_mfma_f32_16x16x32_bf16 v[80:83], v[152:155], v[176:179], v[80:83]
	v_mfma_f32_16x16x32_bf16 v[68:71], v[144:147], v[184:187], v[68:71]
	v_mfma_f32_16x16x32_bf16 v[64:67], v[152:155], v[184:187], v[64:67]
	v_mfma_f32_16x16x32_bf16 v[116:119], v[148:151], v[164:167], v[116:119]
	v_mfma_f32_16x16x32_bf16 v[112:115], v[156:159], v[164:167], v[112:115]
	v_mfma_f32_16x16x32_bf16 v[100:103], v[148:151], v[172:175], v[100:103]
	v_mfma_f32_16x16x32_bf16 v[96:99], v[156:159], v[172:175], v[96:99]
	v_mfma_f32_16x16x32_bf16 v[84:87], v[148:151], v[180:183], v[84:87]
	v_mfma_f32_16x16x32_bf16 v[80:83], v[156:159], v[180:183], v[80:83]
	v_mfma_f32_16x16x32_bf16 v[68:71], v[148:151], v[188:191], v[68:71]
	v_mfma_f32_16x16x32_bf16 v[64:67], v[156:159], v[188:191], v[64:67]
	s_setprio 0
	s_barrier
; #define PG8_STAGE(bufoff, gbase, voff) do { _Pragma("unroll") for (int _i = 0; _i < 2; ++_i) \
;         __builtin_amdgcn_global_load_lds((const unsigned*)((const char*)(gbase) + (voff)[_i]), (PG8_LAS unsigned*)(lds + (bufoff) + ldsw + _i * 8192), 16, 0, 0); } while (0)
; #define PG8_LDA(dst, b, h) do { _Pragma("unroll") for (int m = 0; m < 4; ++m) _Pragma("unroll") for (int k = 0; k < 2; ++k) dst[m][k] = *(const PG8_LAS bf16x8*)(lds + PG8_SA(b, h) + aoff + m * 2048 + k * 1024); } while (0)
; #define PG8_MMA(ai, bj, At, Bt) do { __builtin_amdgcn_s_setprio(1); _Pragma("unroll") for (int m = 0; m < 4; ++m) _Pragma("unroll") for (int n = 0; n < 2; ++n) _Pragma("unroll") for (int k = 0; k < 2; ++k) \
;         acc[ai][bj][m][n] = mma16<Epi::F16>(Bt[n][k], At[m][k], acc[ai][bj][m][n]); __builtin_amdgcn_s_setprio(0); } while (0)
; #define PG8_WAIT_V(n) asm volatile("s_waitcnt vmcnt(" #n ")" ::: "memory")
; #define PG8_WAIT_L(n) asm volatile("s_waitcnt lgkmcnt(" #n ")" ::: "memory")
; #define PG8_BAR __builtin_amdgcn_s_barrier()
; #define PG8_SCHED __builtin_amdgcn_sched_barrier(0)
; template <class Epi, class Sched, bool ALIGN_EPI = false, bool SP2 = false>
; __device__ __forceinline__ void gemm_phase(PG8_LAS unsigned char* lds, const Gemm g, const Sched& S, const Epi& E) {
;     ...
;         for (int t = 0; t < nt; t += 2) {
;             const bool last = (t == nt - 2);
;             const char* a1 = cA + (size_t)(t + 1) * kstep;
;             const char* a2 = last ? nA : cA + (size_t)(t + 2) * kstep; const char* b2 = last ? nB : cB + (size_t)(t + 2) * kstep;
;             const char* a3 = a2 + kstep; const char* b3 = b2 + kstep;
;     ...
;             PG8_LDA(At, 1, 1); PG8_STAGE(PG8_SB(1, 0), b3, voffB); PG8_STAGE(PG8_SB(1, 1), b3 + hstep, voffB); PG8_STAGE(PG8_SA(1, 0), a3, voffA);
;             PG8_WAIT_V(8); PG8_WAIT_L(0); PG8_BAR; PG8_MMA(1, 0, At, B0); PG8_MMA(1, 1, At, B1); PG8_BAR; PG8_SCHED;
	s_add_i32 s34, s96, s3
	v_lshl_add_u64 v[204:205], v[204:205], 0, s[20:21]
	s_mov_b32 m0, s34
	ds_read_b128 v[160:163], v230 offset:49152
	ds_read_b128 v[164:167], v230 offset:50176
	ds_read_b128 v[168:171], v230 offset:51200
	ds_read_b128 v[172:175], v230 offset:52224
	ds_read_b128 v[176:179], v230 offset:53248
	ds_read_b128 v[180:183], v230 offset:54272
	ds_read_b128 v[184:187], v230 offset:55296
	ds_read_b128 v[188:191], v230 offset:56320
	global_load_lds_dwordx4 v[204:205], off
	v_lshl_add_u64 v[204:205], v[206:207], 0, s[20:21]
	s_add_i32 m0, s34, 0x2000
	s_add_i32 s34, s97, s3
	global_load_lds_dwordx4 v[204:205], off
	v_lshl_add_u64 v[204:205], v[212:213], 0, s[20:21]
	s_mov_b32 m0, s34
	s_nop 0
	global_load_lds_dwordx4 v[204:205], off
	v_lshl_add_u64 v[204:205], v[214:215], 0, s[20:21]
	s_add_i32 m0, s34, 0x2000
	s_nop 0
	global_load_lds_dwordx4 v[204:205], off
	v_lshl_add_u64 v[204:205], v[216:217], 0, s[20:21]
	s_mov_b32 m0, s48
	s_nop 0
	global_load_lds_dwordx4 v[204:205], off
	v_lshl_add_u64 v[204:205], v[218:219], 0, s[20:21]
	s_mov_b32 m0, s49
	s_nop 0
	global_load_lds_dwordx4 v[204:205], off
	s_waitcnt vmcnt(8)
	s_waitcnt lgkmcnt(0)
	s_barrier
	s_setprio 1
	s_waitcnt lgkmcnt(0)
	v_mfma_f32_16x16x32_bf16 v[60:63], v[128:131], v[160:163], v[60:63]
	v_mfma_f32_16x16x32_bf16 v[56:59], v[136:139], v[160:163], v[56:59]
	v_mfma_f32_16x16x32_bf16 v[44:47], v[128:131], v[168:171], v[44:47]
	v_mfma_f32_16x16x32_bf16 v[40:43], v[136:139], v[168:171], v[40:43]
	v_mfma_f32_16x16x32_bf16 v[28:31], v[128:131], v[176:179], v[28:31]
	v_mfma_f32_16x16x32_bf16 v[24:27], v[136:139], v[176:179], v[24:27]
	v_mfma_f32_16x16x32_bf16 v[12:15], v[128:131], v[184:187], v[12:15]
	v_mfma_f32_16x16x32_bf16 v[8:11], v[136:139], v[184:187], v[8:11]
	v_mfma_f32_16x16x32_bf16 v[60:63], v[132:135], v[164:167], v[60:63]
	v_mfma_f32_16x16x32_bf16 v[56:59], v[140:143], v[164:167], v[56:59]
	v_mfma_f32_16x16x32_bf16 v[44:47], v[132:135], v[172:175], v[44:47]
	v_mfma_f32_16x16x32_bf16 v[40:43], v[140:143], v[172:175], v[40:43]
	v_mfma_f32_16x16x32_bf16 v[28:31], v[132:135], v[180:183], v[28:31]
	v_mfma_f32_16x16x32_bf16 v[24:27], v[140:143], v[180:183], v[24:27]
	v_mfma_f32_16x16x32_bf16 v[12:15], v[132:135], v[188:191], v[12:15]
	v_mfma_f32_16x16x32_bf16 v[8:11], v[140:143], v[188:191], v[8:11]
	s_setprio 0
	s_setprio 1
	v_mfma_f32_16x16x32_bf16 v[52:55], v[144:147], v[160:163], v[52:55]
	v_mfma_f32_16x16x32_bf16 v[48:51], v[152:155], v[160:163], v[48:51]
	v_mfma_f32_16x16x32_bf16 v[36:39], v[144:147], v[168:171], v[36:39]
	v_mfma_f32_16x16x32_bf16 v[32:35], v[152:155], v[168:171], v[32:35]
	v_mfma_f32_16x16x32_bf16 v[20:23], v[144:147], v[176:179], v[20:23]
	v_mfma_f32_16x16x32_bf16 v[16:19], v[152:155], v[176:179], v[16:19]
	v_mfma_f32_16x16x32_bf16 v[4:7], v[144:147], v[184:187], v[4:7]
	v_mfma_f32_16x16x32_bf16 v[0:3], v[152:155], v[184:187], v[0:3]
	v_mfma_f32_16x16x32_bf16 v[52:55], v[148:151], v[164:167], v[52:55]
	v_mfma_f32_16x16x32_bf16 v[48:51], v[156:159], v[164:167], v[48:51]
	v_mfma_f32_16x16x32_bf16 v[36:39], v[148:151], v[172:175], v[36:39]
	v_mfma_f32_16x16x32_bf16 v[32:35], v[156:159], v[172:175], v[32:35]
	v_mfma_f32_16x16x32_bf16 v[20:23], v[148:151], v[180:183], v[20:23]
	v_mfma_f32_16x16x32_bf16 v[16:19], v[156:159], v[180:183], v[16:19]
	v_mfma_f32_16x16x32_bf16 v[4:7], v[148:151], v[188:191], v[4:7]
	v_mfma_f32_16x16x32_bf16 v[0:3], v[156:159], v[188:191], v[0:3]
	s_setprio 0
	s_barrier
	s_add_u32 s30, s30, 0x100
	s_addc_u32 s31, s31, 0
	s_add_u32 s29, s29, 0x100
	s_addc_u32 s85, s85, 0
	s_cmp_ge_i32 s92, s79
	s_mov_b32 s34, s92
	s_cbranch_scc0 .LBB0_369
	s_branch .LBB0_370

; #define PG8_STAGE(bufoff, gbase, voff) do { _Pragma("unroll") for (int _i = 0; _i < 2; ++_i) \
;         __builtin_amdgcn_global_load_lds((const unsigned*)((const char*)(gbase) + (voff)[_i]), (PG8_LAS unsigned*)(lds + (bufoff) + ldsw + _i * 8192), 16, 0, 0); } while (0)
; #define PG8_LDA(dst, b, h) do { _Pragma("unroll") for (int m = 0; m < 4; ++m) _Pragma("unroll") for (int k = 0; k < 2; ++k) dst[m][k] = *(const PG8_LAS bf16x8*)(lds + PG8_SA(b, h) + aoff + m * 2048 + k * 1024); } while (0)
; #define PG8_LDB(dst, b, h) do { _Pragma("unroll") for (int n = 0; n < 2; ++n) _Pragma("unroll") for (int k = 0; k < 2; ++k) dst[n][k] = *(const PG8_LAS bf16x8*)(lds + PG8_SB(b, h) + boff + n * 2048 + k * 1024); } while (0)
; #define PG8_SCHED __builtin_amdgcn_sched_barrier(0)
; template <class Epi, class Sched, bool ALIGN_EPI = false, bool SP2 = false>
; __device__ __forceinline__ void gemm_phase(PG8_LAS unsigned char* lds, const Gemm g, const Sched& S, const Epi& E) {
;     ...
;     f32x4 acc[2][2][4][2];
; #pragma unroll
;     for (int a = 0; a < 2; ++a)
; #pragma unroll
;         for (int b = 0; b < 2; ++b)
; #pragma unroll
;             for (int m = 0; m < 4; ++m)
; #pragma unroll
;                 for (int n = 0; n < 2; ++n) acc[a][b][m][n] = (f32x4){0.f, 0.f, 0.f, 0.f};
;     ...
;         const bool has_next = S.next(ui + 1, nxt);
;         const char* nA = has_next ? (const char*)g.A + (size_t)nxt.pm * tstep : cA; const char* nB = has_next ? (const char*)g.Bt + (size_t)nxt.pn * tstep : cB;
;         for (int t = 0; t < nt; t += 2) {
;             const bool last = (t == nt - 2);
;             const char* a1 = cA + (size_t)(t + 1) * kstep;
;             const char* a2 = last ? nA : cA + (size_t)(t + 2) * kstep; const char* b2 = last ? nB : cB + (size_t)(t + 2) * kstep;
;             const char* a3 = a2 + kstep; const char* b3 = b2 + kstep;
;             if (last && has_next) S.a_ready(nxt);
;             if constexpr (SP2) {
;             PG8_LDB(B0, 0, 0); PG8_LDB(B1, 0, 1); PG8_SCHED; PG8_LDA(At, 0, 0); PG8_STAGE(PG8_SA(1, 1), a1 + hstep, voffA);
.LBB0_509:
	s_andn2_b64 vcc, exec, s[50:51]
	s_cbranch_vccz .Lpeel_k4
	v_mov_b32_e32 v127, 0
	v_mov_b32_e32 v126, v127
	v_mov_b32_e32 v125, v127
	v_mov_b32_e32 v124, v127
	v_mov_b32_e32 v123, v127
	v_mov_b32_e32 v122, v127
	v_mov_b32_e32 v121, v127
	v_mov_b32_e32 v120, v127
	v_mov_b32_e32 v111, v127
	v_mov_b32_e32 v110, v127
	v_mov_b32_e32 v109, v127
	v_mov_b32_e32 v108, v127
	v_mov_b32_e32 v107, v127
	v_mov_b32_e32 v106, v127
	v_mov_b32_e32 v105, v127
	v_mov_b32_e32 v104, v127
	v_mov_b32_e32 v95, v127
	v_mov_b32_e32 v94, v127
	v_mov_b32_e32 v93, v127
	v_mov_b32_e32 v92, v127
	v_mov_b32_e32 v91, v127
	v_mov_b32_e32 v90, v127
	v_mov_b32_e32 v89, v127
	v_mov_b32_e32 v88, v127
	v_mov_b32_e32 v79, v127
	v_mov_b32_e32 v78, v127
	v_mov_b32_e32 v77, v127
	v_mov_b32_e32 v76, v127
	v_mov_b32_e32 v75, v127
	v_mov_b32_e32 v74, v127
	v_mov_b32_e32 v73, v127
	v_mov_b32_e32 v72, v127
	v_mov_b32_e32 v119, v127
	v_mov_b32_e32 v118, v127
	v_mov_b32_e32 v117, v127
	v_mov_b32_e32 v116, v127
	v_mov_b32_e32 v115, v127
	v_mov_b32_e32 v114, v127
	v_mov_b32_e32 v113, v127
	v_mov_b32_e32 v112, v127
	v_mov_b32_e32 v103, v127
	v_mov_b32_e32 v102, v127
	v_mov_b32_e32 v101, v127
	v_mov_b32_e32 v100, v127
	v_mov_b32_e32 v99, v127
	v_mov_b32_e32 v98, v127
	v_mov_b32_e32 v97, v127
	v_mov_b32_e32 v96, v127
	v_mov_b32_e32 v87, v127
	v_mov_b32_e32 v86, v127
	v_mov_b32_e32 v85, v127
	v_mov_b32_e32 v84, v127
	v_mov_b32_e32 v83, v127
	v_mov_b32_e32 v82, v127
	v_mov_b32_e32 v81, v127
	v_mov_b32_e32 v80, v127
	v_mov_b32_e32 v71, v127
	v_mov_b32_e32 v70, v127
	v_mov_b32_e32 v69, v127
	v_mov_b32_e32 v68, v127
	v_mov_b32_e32 v67, v127
	v_mov_b32_e32 v66, v127
	v_mov_b32_e32 v65, v127
	v_mov_b32_e32 v64, v127
	v_mov_b32_e32 v63, v127
	v_mov_b32_e32 v62, v127
	v_mov_b32_e32 v61, v127
	v_mov_b32_e32 v60, v127
	v_mov_b32_e32 v59, v127
	v_mov_b32_e32 v58, v127
	v_mov_b32_e32 v57, v127
	v_mov_b32_e32 v56, v127
	v_mov_b32_e32 v47, v127
	v_mov_b32_e32 v46, v127
	v_mov_b32_e32 v45, v127
	v_mov_b32_e32 v44, v127
	v_mov_b32_e32 v43, v127
	v_mov_b32_e32 v42, v127
	v_mov_b32_e32 v41, v127
	v_mov_b32_e32 v40, v127
	v_mov_b32_e32 v31, v127
	v_mov_b32_e32 v30, v127
	v_mov_b32_e32 v29, v127
	v_mov_b32_e32 v28, v127
	v_mov_b32_e32 v27, v127
	v_mov_b32_e32 v26, v127
	v_mov_b32_e32 v25, v127
	v_mov_b32_e32 v24, v127
	v_mov_b32_e32 v15, v127
	v_mov_b32_e32 v14, v127
	v_mov_b32_e32 v13, v127
	v_mov_b32_e32 v12, v127
	v_mov_b32_e32 v11, v127
	v_mov_b32_e32 v10, v127
	v_mov_b32_e32 v9, v127
	v_mov_b32_e32 v8, v127
	v_mov_b32_e32 v55, v127
	v_mov_b32_e32 v54, v127
	v_mov_b32_e32 v53, v127
	v_mov_b32_e32 v52, v127
	v_mov_b32_e32 v51, v127
	v_mov_b32_e32 v50, v127
	v_mov_b32_e32 v49, v127
	v_mov_b32_e32 v48, v127
	v_mov_b32_e32 v39, v127
	v_mov_b32_e32 v38, v127
	v_mov_b32_e32 v37, v127
	v_mov_b32_e32 v36, v127
	v_mov_b32_e32 v35, v127
	v_mov_b32_e32 v34, v127
	v_mov_b32_e32 v33, v127
	v_mov_b32_e32 v32, v127
	v_mov_b32_e32 v23, v127
	v_mov_b32_e32 v22, v127
	v_mov_b32_e32 v21, v127
	v_mov_b32_e32 v20, v127
	v_mov_b32_e32 v19, v127
	v_mov_b32_e32 v18, v127
	v_mov_b32_e32 v17, v127
	v_mov_b32_e32 v16, v127
	v_mov_b32_e32 v7, v127
	v_mov_b32_e32 v6, v127
	v_mov_b32_e32 v5, v127
	v_mov_b32_e32 v4, v127
	v_mov_b32_e32 v3, v127
	v_mov_b32_e32 v2, v127
	v_mov_b32_e32 v1, v127
	v_mov_b32_e32 v0, v127
	s_branch .LBB0_512
.Lpeel_k4:
	s_add_u32 s30, s30, 0x80
	s_addc_u32 s31, s31, 0
	s_add_u32 s67, s34, 0x100
	s_addc_u32 s68, s35, 0
	s_mov_b32 s34, 0
	s_add_i32 s69, s34, 2
	s_add_u32 s70, s30, 0x80
	s_addc_u32 s35, s31, 0
	s_add_i32 s72, 0, 0x10000
	s_cmp_eq_u32 s61, s34
	s_cselect_b32 s35, s1, s35
	s_cselect_b32 s34, s0, s70
	v_add_u32_e32 v146, s72, v153
	s_cselect_b32 s71, s55, s68
	s_cselect_b32 s70, s54, s67
	s_add_i32 s73, 0, 0x14000
	ds_read_b128 v[142:145], v146
	ds_read_b128 v[158:161], v146 offset:1024
	ds_read_b128 v[162:165], v146 offset:2048
	ds_read_b128 v[166:169], v146 offset:3072
	v_add_u32_e32 v146, s73, v153
	ds_read_b128 v[170:173], v146
	ds_read_b128 v[174:177], v146 offset:1024
	ds_read_b128 v[178:181], v146 offset:2048
	ds_read_b128 v[182:185], v146 offset:3072
	v_lshl_add_u64 v[146:147], s[30:31], 0, v[138:139]
	s_add_i32 m0, s39, 0xc000
	ds_read_b128 v[186:189], v157
	ds_read_b128 v[190:193], v157 offset:1024
	ds_read_b128 v[194:197], v157 offset:2048
	ds_read_b128 v[198:201], v157 offset:3072
	ds_read_b128 v[202:205], v157 offset:4096
	ds_read_b128 v[212:215], v157 offset:5120
	ds_read_b128 v[216:219], v157 offset:6144
	ds_read_b128 v[220:223], v157 offset:7168
	global_load_lds_dwordx4 v[146:147], off
	v_lshl_add_u64 v[146:147], s[30:31], 0, v[140:141]
	s_add_i32 m0, s39, 0xe000
	s_nop 0
	global_load_lds_dwordx4 v[146:147], off
	s_waitcnt vmcnt(8)
	s_waitcnt lgkmcnt(0)
	s_barrier
; #define PG8_STAGE(bufoff, gbase, voff) do { _Pragma("unroll") for (int _i = 0; _i < 2; ++_i) \
;         __builtin_amdgcn_global_load_lds((const unsigned*)((const char*)(gbase) + (voff)[_i]), (PG8_LAS unsigned*)(lds + (bufoff) + ldsw + _i * 8192), 16, 0, 0); } while (0)
; #define PG8_LDA(dst, b, h) do { _Pragma("unroll") for (int m = 0; m < 4; ++m) _Pragma("unroll") for (int k = 0; k < 2; ++k) dst[m][k] = *(const PG8_LAS bf16x8*)(lds + PG8_SA(b, h) + aoff + m * 2048 + k * 1024); } while (0)
; #define PG8_MMA(ai, bj, At, Bt) do { __builtin_amdgcn_s_setprio(1); _Pragma("unroll") for (int m = 0; m < 4; ++m) _Pragma("unroll") for (int n = 0; n < 2; ++n) _Pragma("unroll") for (int k = 0; k < 2; ++k) \
;         acc[ai][bj][m][n] = mma16<Epi::F16>(Bt[n][k], At[m][k], acc[ai][bj][m][n]); __builtin_amdgcn_s_setprio(0); } while (0)
; #define PG8_WAIT_V(n) asm volatile("s_waitcnt vmcnt(" #n ")" ::: "memory")
; #define PG8_WAIT_L(n) asm volatile("s_waitcnt lgkmcnt(" #n ")" ::: "memory")
; #define PG8_BAR __builtin_amdgcn_s_barrier()
; #define PG8_SCHED __builtin_amdgcn_sched_barrier(0)
; template <class Epi, class Sched, bool ALIGN_EPI = false, bool SP2 = false>
; __device__ __forceinline__ void gemm_phase(PG8_LAS unsigned char* lds, const Gemm g, const Sched& S, const Epi& E) {
;     ...
;             PG8_WAIT_V(8); PG8_WAIT_L(0); PG8_BAR; PG8_MMA(0, 0, At, B0); PG8_MMA(0, 1, At, B1); PG8_BAR; PG8_SCHED;
;             PG8_LDA(At, 0, 1); PG8_STAGE(PG8_SB(0, 0), b2, voffB); PG8_STAGE(PG8_SB(0, 1), b2 + hstep, voffB); PG8_STAGE(PG8_SA(0, 0), a2, voffA);
;             PG8_WAIT_V(8); PG8_WAIT_L(0); PG8_BAR; PG8_MMA(1, 0, At, B0); PG8_MMA(1, 1, At, B1); PG8_BAR; PG8_SCHED;
	s_setprio 1
	s_waitcnt lgkmcnt(0)
	v_mfma_f32_16x16x32_bf16 v[124:127], v[142:145], v[186:189], 0
	v_mfma_f32_16x16x32_bf16 v[120:123], v[162:165], v[186:189], 0
	v_mfma_f32_16x16x32_bf16 v[108:111], v[142:145], v[194:197], 0
	v_mfma_f32_16x16x32_bf16 v[104:107], v[162:165], v[194:197], 0
	v_mfma_f32_16x16x32_bf16 v[92:95], v[142:145], v[202:205], 0
	v_mfma_f32_16x16x32_bf16 v[88:91], v[162:165], v[202:205], 0
	v_mfma_f32_16x16x32_bf16 v[76:79], v[142:145], v[216:219], 0
	v_mfma_f32_16x16x32_bf16 v[72:75], v[162:165], v[216:219], 0
	v_mfma_f32_16x16x32_bf16 v[124:127], v[158:161], v[190:193], v[124:127]
	v_mfma_f32_16x16x32_bf16 v[120:123], v[166:169], v[190:193], v[120:123]
	v_mfma_f32_16x16x32_bf16 v[108:111], v[158:161], v[198:201], v[108:111]
	v_mfma_f32_16x16x32_bf16 v[104:107], v[166:169], v[198:201], v[104:107]
	v_mfma_f32_16x16x32_bf16 v[92:95], v[158:161], v[212:215], v[92:95]
	v_mfma_f32_16x16x32_bf16 v[88:91], v[166:169], v[212:215], v[88:91]
	v_mfma_f32_16x16x32_bf16 v[76:79], v[158:161], v[220:223], v[76:79]
	v_mfma_f32_16x16x32_bf16 v[72:75], v[166:169], v[220:223], v[72:75]
	s_setprio 0
	s_setprio 1
	v_mfma_f32_16x16x32_bf16 v[116:119], v[170:173], v[186:189], 0
	v_mfma_f32_16x16x32_bf16 v[112:115], v[178:181], v[186:189], 0
	v_mfma_f32_16x16x32_bf16 v[100:103], v[170:173], v[194:197], 0
	v_mfma_f32_16x16x32_bf16 v[96:99], v[178:181], v[194:197], 0
	v_mfma_f32_16x16x32_bf16 v[84:87], v[170:173], v[202:205], 0
	v_mfma_f32_16x16x32_bf16 v[80:83], v[178:181], v[202:205], 0
	v_mfma_f32_16x16x32_bf16 v[68:71], v[170:173], v[216:219], 0
	v_mfma_f32_16x16x32_bf16 v[64:67], v[178:181], v[216:219], 0
	v_mfma_f32_16x16x32_bf16 v[116:119], v[174:177], v[190:193], v[116:119]
	v_mfma_f32_16x16x32_bf16 v[112:115], v[182:185], v[190:193], v[112:115]
	v_mfma_f32_16x16x32_bf16 v[100:103], v[174:177], v[198:201], v[100:103]
	v_mfma_f32_16x16x32_bf16 v[96:99], v[182:185], v[198:201], v[96:99]
	v_mfma_f32_16x16x32_bf16 v[84:87], v[174:177], v[212:215], v[84:87]
	v_mfma_f32_16x16x32_bf16 v[80:83], v[182:185], v[212:215], v[80:83]
	v_mfma_f32_16x16x32_bf16 v[68:71], v[174:177], v[220:223], v[68:71]
	v_mfma_f32_16x16x32_bf16 v[64:67], v[182:185], v[220:223], v[64:67]
	s_setprio 0
	s_barrier
	s_add_i32 s72, s72, s7
	v_lshl_add_u64 v[146:147], s[70:71], 0, v[132:133]
	s_mov_b32 m0, s72
	ds_read_b128 v[186:189], v157 offset:16384
	ds_read_b128 v[190:193], v157 offset:17408
	ds_read_b128 v[194:197], v157 offset:18432
	ds_read_b128 v[198:201], v157 offset:19456
	ds_read_b128 v[202:205], v157 offset:20480
	ds_read_b128 v[212:215], v157 offset:21504
	ds_read_b128 v[216:219], v157 offset:22528
	ds_read_b128 v[220:223], v157 offset:23552
	global_load_lds_dwordx4 v[146:147], off
	s_add_i32 m0, s72, 0x2000
	v_lshl_add_u64 v[150:151], s[70:71], 0, v[128:129]
	s_add_u32 s70, s70, s28
	s_addc_u32 s71, s71, s29
	s_add_i32 s72, s73, s7
	global_load_lds_dwordx4 v[150:151], off
	v_lshl_add_u64 v[154:155], s[70:71], 0, v[132:133]
	s_mov_b32 m0, s72
	v_lshl_add_u64 v[206:207], s[70:71], 0, v[128:129]
	global_load_lds_dwordx4 v[154:155], off
	s_add_i32 m0, s72, 0x2000
	v_lshl_add_u64 v[224:225], s[34:35], 0, v[134:135]
	global_load_lds_dwordx4 v[206:207], off
	s_mov_b32 m0, s39
	v_lshl_add_u64 v[226:227], s[34:35], 0, v[130:131]
	global_load_lds_dwordx4 v[224:225], off
	s_mov_b32 m0, s48
	s_nop 0
	global_load_lds_dwordx4 v[226:227], off
	s_waitcnt vmcnt(8)
	s_waitcnt lgkmcnt(0)
	s_barrier
	s_setprio 1
	s_waitcnt lgkmcnt(0)
	v_mfma_f32_16x16x32_bf16 v[60:63], v[142:145], v[186:189], 0
	v_mfma_f32_16x16x32_bf16 v[56:59], v[162:165], v[186:189], 0
	v_mfma_f32_16x16x32_bf16 v[44:47], v[142:145], v[194:197], 0
	v_mfma_f32_16x16x32_bf16 v[40:43], v[162:165], v[194:197], 0
	v_mfma_f32_16x16x32_bf16 v[28:31], v[142:145], v[202:205], 0
	v_mfma_f32_16x16x32_bf16 v[24:27], v[162:165], v[202:205], 0
	v_mfma_f32_16x16x32_bf16 v[12:15], v[142:145], v[216:219], 0
	v_mfma_f32_16x16x32_bf16 v[8:11], v[162:165], v[216:219], 0
	v_mfma_f32_16x16x32_bf16 v[60:63], v[158:161], v[190:193], v[60:63]
	v_mfma_f32_16x16x32_bf16 v[56:59], v[166:169], v[190:193], v[56:59]
	v_mfma_f32_16x16x32_bf16 v[44:47], v[158:161], v[198:201], v[44:47]
	v_mfma_f32_16x16x32_bf16 v[40:43], v[166:169], v[198:201], v[40:43]
	v_mfma_f32_16x16x32_bf16 v[28:31], v[158:161], v[212:215], v[28:31]
	v_mfma_f32_16x16x32_bf16 v[24:27], v[166:169], v[212:215], v[24:27]
	v_mfma_f32_16x16x32_bf16 v[12:15], v[158:161], v[220:223], v[12:15]
	v_mfma_f32_16x16x32_bf16 v[8:11], v[166:169], v[220:223], v[8:11]
	s_setprio 0
	s_setprio 1
	v_mfma_f32_16x16x32_bf16 v[52:55], v[170:173], v[186:189], 0
	v_mfma_f32_16x16x32_bf16 v[48:51], v[178:181], v[186:189], 0
	v_mfma_f32_16x16x32_bf16 v[36:39], v[170:173], v[194:197], 0
	v_mfma_f32_16x16x32_bf16 v[32:35], v[178:181], v[194:197], 0
	v_mfma_f32_16x16x32_bf16 v[20:23], v[170:173], v[202:205], 0
	v_mfma_f32_16x16x32_bf16 v[16:19], v[178:181], v[202:205], 0
	v_mfma_f32_16x16x32_bf16 v[4:7], v[170:173], v[216:219], 0
	v_mfma_f32_16x16x32_bf16 v[0:3], v[178:181], v[216:219], 0
	v_mfma_f32_16x16x32_bf16 v[52:55], v[174:177], v[190:193], v[52:55]
	v_mfma_f32_16x16x32_bf16 v[48:51], v[182:185], v[190:193], v[48:51]
	v_mfma_f32_16x16x32_bf16 v[36:39], v[174:177], v[198:201], v[36:39]
	v_mfma_f32_16x16x32_bf16 v[32:35], v[182:185], v[198:201], v[32:35]
	v_mfma_f32_16x16x32_bf16 v[20:23], v[174:177], v[212:215], v[20:23]
	v_mfma_f32_16x16x32_bf16 v[16:19], v[182:185], v[212:215], v[16:19]
	v_mfma_f32_16x16x32_bf16 v[4:7], v[174:177], v[220:223], v[4:7]
	v_mfma_f32_16x16x32_bf16 v[0:3], v[182:185], v[220:223], v[0:3]
	s_setprio 0
	s_barrier
; #define PG8_STAGE(bufoff, gbase, voff) do { _Pragma("unroll") for (int _i = 0; _i < 2; ++_i) \
;         __builtin_amdgcn_global_load_lds((const unsigned*)((const char*)(gbase) + (voff)[_i]), (PG8_LAS unsigned*)(lds + (bufoff) + ldsw + _i * 8192), 16, 0, 0); } while (0)
; #define PG8_LDA(dst, b, h) do { _Pragma("unroll") for (int m = 0; m < 4; ++m) _Pragma("unroll") for (int k = 0; k < 2; ++k) dst[m][k] = *(const PG8_LAS bf16x8*)(lds + PG8_SA(b, h) + aoff + m * 2048 + k * 1024); } while (0)
; #define PG8_LDB(dst, b, h) do { _Pragma("unroll") for (int n = 0; n < 2; ++n) _Pragma("unroll") for (int k = 0; k < 2; ++k) dst[n][k] = *(const PG8_LAS bf16x8*)(lds + PG8_SB(b, h) + boff + n * 2048 + k * 1024); } while (0)
; #define PG8_MMA(ai, bj, At, Bt) do { __builtin_amdgcn_s_setprio(1); _Pragma("unroll") for (int m = 0; m < 4; ++m) _Pragma("unroll") for (int n = 0; n < 2; ++n) _Pragma("unroll") for (int k = 0; k < 2; ++k) \
;         acc[ai][bj][m][n] = mma16<Epi::F16>(Bt[n][k], At[m][k], acc[ai][bj][m][n]); __builtin_amdgcn_s_setprio(0); } while (0)
; #define PG8_WAIT_V(n) asm volatile("s_waitcnt vmcnt(" #n ")" ::: "memory")
; #define PG8_WAIT_L(n) asm volatile("s_waitcnt lgkmcnt(" #n ")" ::: "memory")
; #define PG8_BAR __builtin_amdgcn_s_barrier()
; #define PG8_SCHED __builtin_amdgcn_sched_barrier(0)
; template <class Epi, class Sched, bool ALIGN_EPI = false, bool SP2 = false>
; __device__ __forceinline__ void gemm_phase(PG8_LAS unsigned char* lds, const Gemm g, const Sched& S, const Epi& E) {
;     ...
;             PG8_LDB(B0, 1, 0); PG8_LDB(B1, 1, 1); PG8_SCHED; PG8_LDA(At, 1, 0); PG8_STAGE(PG8_SA(0, 1), a2 + hstep, voffA);
;             PG8_WAIT_V(8); PG8_WAIT_L(0); PG8_BAR; PG8_MMA(0, 0, At, B0); PG8_MMA(0, 1, At, B1); PG8_BAR; PG8_SCHED;
	s_add_i32 s70, 0, 0x18000
	v_add_u32_e32 v148, s70, v153
	s_add_i32 s71, 0, 0x1c000
	ds_read_b128 v[142:145], v148
	ds_read_b128 v[158:161], v148 offset:1024
	ds_read_b128 v[162:165], v148 offset:2048
	ds_read_b128 v[166:169], v148 offset:3072
	v_add_u32_e32 v148, s71, v153
	ds_read_b128 v[170:173], v148
	ds_read_b128 v[174:177], v148 offset:1024
	ds_read_b128 v[178:181], v148 offset:2048
	ds_read_b128 v[182:185], v148 offset:3072
	s_add_u32 s34, s34, s28
	s_addc_u32 s35, s35, s29
	s_mov_b32 m0, s56
	v_lshl_add_u64 v[228:229], s[34:35], 0, v[134:135]
	ds_read_b128 v[186:189], v157 offset:32768
	ds_read_b128 v[190:193], v157 offset:33792
	ds_read_b128 v[194:197], v157 offset:34816
	ds_read_b128 v[198:201], v157 offset:35840
	ds_read_b128 v[202:205], v157 offset:36864
	ds_read_b128 v[212:215], v157 offset:37888
	ds_read_b128 v[216:219], v157 offset:38912
	ds_read_b128 v[220:223], v157 offset:39936
	global_load_lds_dwordx4 v[228:229], off
	v_lshl_add_u64 v[228:229], s[34:35], 0, v[130:131]
	s_mov_b32 m0, s57
	s_nop 0
	global_load_lds_dwordx4 v[228:229], off
	s_waitcnt vmcnt(8)
	s_waitcnt lgkmcnt(0)
	s_barrier
	s_setprio 1
	s_waitcnt lgkmcnt(0)
	v_mfma_f32_16x16x32_bf16 v[124:127], v[142:145], v[186:189], v[124:127]
	v_mfma_f32_16x16x32_bf16 v[120:123], v[162:165], v[186:189], v[120:123]
	v_mfma_f32_16x16x32_bf16 v[108:111], v[142:145], v[194:197], v[108:111]
	v_mfma_f32_16x16x32_bf16 v[104:107], v[162:165], v[194:197], v[104:107]
	v_mfma_f32_16x16x32_bf16 v[92:95], v[142:145], v[202:205], v[92:95]
	v_mfma_f32_16x16x32_bf16 v[88:91], v[162:165], v[202:205], v[88:91]
	v_mfma_f32_16x16x32_bf16 v[76:79], v[142:145], v[216:219], v[76:79]
	v_mfma_f32_16x16x32_bf16 v[72:75], v[162:165], v[216:219], v[72:75]
	v_mfma_f32_16x16x32_bf16 v[124:127], v[158:161], v[190:193], v[124:127]
	v_mfma_f32_16x16x32_bf16 v[120:123], v[166:169], v[190:193], v[120:123]
	v_mfma_f32_16x16x32_bf16 v[108:111], v[158:161], v[198:201], v[108:111]
	v_mfma_f32_16x16x32_bf16 v[104:107], v[166:169], v[198:201], v[104:107]
	v_mfma_f32_16x16x32_bf16 v[92:95], v[158:161], v[212:215], v[92:95]
	v_mfma_f32_16x16x32_bf16 v[88:91], v[166:169], v[212:215], v[88:91]
	v_mfma_f32_16x16x32_bf16 v[76:79], v[158:161], v[220:223], v[76:79]
	v_mfma_f32_16x16x32_bf16 v[72:75], v[166:169], v[220:223], v[72:75]
	s_setprio 0
	s_setprio 1
	v_mfma_f32_16x16x32_bf16 v[116:119], v[170:173], v[186:189], v[116:119]
	v_mfma_f32_16x16x32_bf16 v[112:115], v[178:181], v[186:189], v[112:115]
	v_mfma_f32_16x16x32_bf16 v[100:103], v[170:173], v[194:197], v[100:103]
	v_mfma_f32_16x16x32_bf16 v[96:99], v[178:181], v[194:197], v[96:99]
	v_mfma_f32_16x16x32_bf16 v[84:87], v[170:173], v[202:205], v[84:87]
	v_mfma_f32_16x16x32_bf16 v[80:83], v[178:181], v[202:205], v[80:83]
	v_mfma_f32_16x16x32_bf16 v[68:71], v[170:173], v[216:219], v[68:71]
	v_mfma_f32_16x16x32_bf16 v[64:67], v[178:181], v[216:219], v[64:67]
	v_mfma_f32_16x16x32_bf16 v[116:119], v[174:177], v[190:193], v[116:119]
	v_mfma_f32_16x16x32_bf16 v[112:115], v[182:185], v[190:193], v[112:115]
	v_mfma_f32_16x16x32_bf16 v[100:103], v[174:177], v[198:201], v[100:103]
	v_mfma_f32_16x16x32_bf16 v[96:99], v[182:185], v[198:201], v[96:99]
	v_mfma_f32_16x16x32_bf16 v[84:87], v[174:177], v[212:215], v[84:87]
	v_mfma_f32_16x16x32_bf16 v[80:83], v[182:185], v[212:215], v[80:83]
	v_mfma_f32_16x16x32_bf16 v[68:71], v[174:177], v[220:223], v[68:71]
	v_mfma_f32_16x16x32_bf16 v[64:67], v[182:185], v[220:223], v[64:67]
	s_setprio 0
	s_barrier
; #define PG8_STAGE(bufoff, gbase, voff) do { _Pragma("unroll") for (int _i = 0; _i < 2; ++_i) \
;         __builtin_amdgcn_global_load_lds((const unsigned*)((const char*)(gbase) + (voff)[_i]), (PG8_LAS unsigned*)(lds + (bufoff) + ldsw + _i * 8192), 16, 0, 0); } while (0)
; #define PG8_LDA(dst, b, h) do { _Pragma("unroll") for (int m = 0; m < 4; ++m) _Pragma("unroll") for (int k = 0; k < 2; ++k) dst[m][k] = *(const PG8_LAS bf16x8*)(lds + PG8_SA(b, h) + aoff + m * 2048 + k * 1024); } while (0)
; #define PG8_MMA(ai, bj, At, Bt) do { __builtin_amdgcn_s_setprio(1); _Pragma("unroll") for (int m = 0; m < 4; ++m) _Pragma("unroll") for (int n = 0; n < 2; ++n) _Pragma("unroll") for (int k = 0; k < 2; ++k) \
;         acc[ai][bj][m][n] = mma16<Epi::F16>(Bt[n][k], At[m][k], acc[ai][bj][m][n]); __builtin_amdgcn_s_setprio(0); } while (0)
; #define PG8_WAIT_V(n) asm volatile("s_waitcnt vmcnt(" #n ")" ::: "memory")
; #define PG8_WAIT_L(n) asm volatile("s_waitcnt lgkmcnt(" #n ")" ::: "memory")
; #define PG8_BAR __builtin_amdgcn_s_barrier()
; #define PG8_SCHED __builtin_amdgcn_sched_barrier(0)
; template <class Epi, class Sched, bool ALIGN_EPI = false, bool SP2 = false>
; __device__ __forceinline__ void gemm_phase(PG8_LAS unsigned char* lds, const Gemm g, const Sched& S, const Epi& E) {
;     ...
;         for (int t = 0; t < nt; t += 2) {
;             const bool last = (t == nt - 2);
;             const char* a1 = cA + (size_t)(t + 1) * kstep;
;             const char* a2 = last ? nA : cA + (size_t)(t + 2) * kstep; const char* b2 = last ? nB : cB + (size_t)(t + 2) * kstep;
;             const char* a3 = a2 + kstep; const char* b3 = b2 + kstep;
;     ...
;             PG8_LDA(At, 1, 1); PG8_STAGE(PG8_SB(1, 0), b3, voffB); PG8_STAGE(PG8_SB(1, 1), b3 + hstep, voffB); PG8_STAGE(PG8_SA(1, 0), a3, voffA);
;             PG8_WAIT_V(8); PG8_WAIT_L(0); PG8_BAR; PG8_MMA(1, 0, At, B0); PG8_MMA(1, 1, At, B1); PG8_BAR; PG8_SCHED;
	s_add_i32 s34, s70, s7
	v_lshl_add_u64 v[146:147], v[146:147], 0, s[20:21]
	s_mov_b32 m0, s34
	ds_read_b128 v[186:189], v157 offset:49152
	ds_read_b128 v[190:193], v157 offset:50176
	ds_read_b128 v[194:197], v157 offset:51200
	ds_read_b128 v[198:201], v157 offset:52224
	ds_read_b128 v[202:205], v157 offset:53248
	ds_read_b128 v[212:215], v157 offset:54272
	ds_read_b128 v[216:219], v157 offset:55296
	ds_read_b128 v[220:223], v157 offset:56320
	global_load_lds_dwordx4 v[146:147], off
	v_lshl_add_u64 v[146:147], v[150:151], 0, s[20:21]
	s_add_i32 m0, s34, 0x2000
	s_add_i32 s34, s71, s7
	global_load_lds_dwordx4 v[146:147], off
	v_lshl_add_u64 v[146:147], v[154:155], 0, s[20:21]
	s_mov_b32 m0, s34
	s_nop 0
	global_load_lds_dwordx4 v[146:147], off
	v_lshl_add_u64 v[146:147], v[206:207], 0, s[20:21]
	s_add_i32 m0, s34, 0x2000
	s_nop 0
	global_load_lds_dwordx4 v[146:147], off
	v_lshl_add_u64 v[146:147], v[224:225], 0, s[20:21]
	s_mov_b32 m0, s58
	s_nop 0
	global_load_lds_dwordx4 v[146:147], off
	v_lshl_add_u64 v[146:147], v[226:227], 0, s[20:21]
	s_mov_b32 m0, s59
	s_nop 0
	global_load_lds_dwordx4 v[146:147], off
	s_waitcnt vmcnt(8)
	s_waitcnt lgkmcnt(0)
	s_barrier
	s_setprio 1
	s_waitcnt lgkmcnt(0)
	v_mfma_f32_16x16x32_bf16 v[60:63], v[142:145], v[186:189], v[60:63]
	v_mfma_f32_16x16x32_bf16 v[56:59], v[162:165], v[186:189], v[56:59]
	v_mfma_f32_16x16x32_bf16 v[44:47], v[142:145], v[194:197], v[44:47]
	v_mfma_f32_16x16x32_bf16 v[40:43], v[162:165], v[194:197], v[40:43]
	v_mfma_f32_16x16x32_bf16 v[28:31], v[142:145], v[202:205], v[28:31]
	v_mfma_f32_16x16x32_bf16 v[24:27], v[162:165], v[202:205], v[24:27]
	v_mfma_f32_16x16x32_bf16 v[12:15], v[142:145], v[216:219], v[12:15]
	v_mfma_f32_16x16x32_bf16 v[8:11], v[162:165], v[216:219], v[8:11]
	v_mfma_f32_16x16x32_bf16 v[60:63], v[158:161], v[190:193], v[60:63]
	v_mfma_f32_16x16x32_bf16 v[56:59], v[166:169], v[190:193], v[56:59]
	v_mfma_f32_16x16x32_bf16 v[44:47], v[158:161], v[198:201], v[44:47]
	v_mfma_f32_16x16x32_bf16 v[40:43], v[166:169], v[198:201], v[40:43]
	v_mfma_f32_16x16x32_bf16 v[28:31], v[158:161], v[212:215], v[28:31]
	v_mfma_f32_16x16x32_bf16 v[24:27], v[166:169], v[212:215], v[24:27]
	v_mfma_f32_16x16x32_bf16 v[12:15], v[158:161], v[220:223], v[12:15]
	v_mfma_f32_16x16x32_bf16 v[8:11], v[166:169], v[220:223], v[8:11]
	s_setprio 0
	s_setprio 1
	v_mfma_f32_16x16x32_bf16 v[52:55], v[170:173], v[186:189], v[52:55]
	v_mfma_f32_16x16x32_bf16 v[48:51], v[178:181], v[186:189], v[48:51]
	v_mfma_f32_16x16x32_bf16 v[36:39], v[170:173], v[194:197], v[36:39]
	v_mfma_f32_16x16x32_bf16 v[32:35], v[178:181], v[194:197], v[32:35]
	v_mfma_f32_16x16x32_bf16 v[20:23], v[170:173], v[202:205], v[20:23]
	v_mfma_f32_16x16x32_bf16 v[16:19], v[178:181], v[202:205], v[16:19]
	v_mfma_f32_16x16x32_bf16 v[4:7], v[170:173], v[216:219], v[4:7]
	v_mfma_f32_16x16x32_bf16 v[0:3], v[178:181], v[216:219], v[0:3]
	v_mfma_f32_16x16x32_bf16 v[52:55], v[174:177], v[190:193], v[52:55]
	v_mfma_f32_16x16x32_bf16 v[48:51], v[182:185], v[190:193], v[48:51]
	v_mfma_f32_16x16x32_bf16 v[36:39], v[174:177], v[198:201], v[36:39]
	v_mfma_f32_16x16x32_bf16 v[32:35], v[182:185], v[198:201], v[32:35]
	v_mfma_f32_16x16x32_bf16 v[20:23], v[174:177], v[212:215], v[20:23]
	v_mfma_f32_16x16x32_bf16 v[16:19], v[182:185], v[212:215], v[16:19]
	v_mfma_f32_16x16x32_bf16 v[4:7], v[174:177], v[220:223], v[4:7]
	v_mfma_f32_16x16x32_bf16 v[0:3], v[182:185], v[220:223], v[0:3]
	s_setprio 0
	s_barrier
	s_add_u32 s30, s30, 0x100
	s_addc_u32 s31, s31, 0
	s_add_u32 s67, s67, 0x100
	s_addc_u32 s68, s68, 0
	s_cmp_ge_i32 s69, s60
	s_mov_b32 s34, s69
	s_cbranch_scc0 .LBB0_511
	s_branch .LBB0_512

; #define PG8_STAGE(bufoff, gbase, voff) do { _Pragma("unroll") for (int _i = 0; _i < 2; ++_i) \
;         __builtin_amdgcn_global_load_lds((const unsigned*)((const char*)(gbase) + (voff)[_i]), (PG8_LAS unsigned*)(lds + (bufoff) + ldsw + _i * 8192), 16, 0, 0); } while (0)
; #define PG8_LDA(dst, b, h) do { _Pragma("unroll") for (int m = 0; m < 4; ++m) _Pragma("unroll") for (int k = 0; k < 2; ++k) dst[m][k] = *(const PG8_LAS bf16x8*)(lds + PG8_SA(b, h) + aoff + m * 2048 + k * 1024); } while (0)
; #define PG8_LDB(dst, b, h) do { _Pragma("unroll") for (int n = 0; n < 2; ++n) _Pragma("unroll") for (int k = 0; k < 2; ++k) dst[n][k] = *(const PG8_LAS bf16x8*)(lds + PG8_SB(b, h) + boff + n * 2048 + k * 1024); } while (0)
; #define PG8_WAIT_V(n) asm volatile("s_waitcnt vmcnt(" #n ")" ::: "memory")
; #define PG8_WAIT_L(n) asm volatile("s_waitcnt lgkmcnt(" #n ")" ::: "memory")
; #define PG8_BAR __builtin_amdgcn_s_barrier()
; #define PG8_SCHED __builtin_amdgcn_sched_barrier(0)
; template <class Epi, class Sched, bool ALIGN_EPI = false, bool SP2 = false>
; __device__ __forceinline__ void gemm_phase(PG8_LAS unsigned char* lds, const Gemm g, const Sched& S, const Epi& E) {
;     ...
;         const bool has_next = S.next(ui + 1, nxt);
;         const char* nA = has_next ? (const char*)g.A + (size_t)nxt.pm * tstep : cA; const char* nB = has_next ? (const char*)g.Bt + (size_t)nxt.pn * tstep : cB;
;         for (int t = 0; t < nt; t += 2) {
;             const bool last = (t == nt - 2);
;             const char* a1 = cA + (size_t)(t + 1) * kstep;
;             const char* a2 = last ? nA : cA + (size_t)(t + 2) * kstep; const char* b2 = last ? nB : cB + (size_t)(t + 2) * kstep;
;             const char* a3 = a2 + kstep; const char* b3 = b2 + kstep;
;             if (last && has_next) S.a_ready(nxt);
;             if constexpr (SP2) {
;             PG8_LDB(B0, 0, 0); PG8_LDB(B1, 0, 1); PG8_SCHED; PG8_LDA(At, 0, 0); PG8_STAGE(PG8_SA(1, 1), a1 + hstep, voffA);
;             PG8_WAIT_V(8); PG8_WAIT_L(0); PG8_BAR; PG8_MMA(0, 0, At, B0); PG8_MMA(0, 1, At, B1); PG8_BAR; PG8_SCHED;
;             PG8_LDA(At, 0, 1); PG8_STAGE(PG8_SB(0, 0), b2, voffB); PG8_STAGE(PG8_SB(0, 1), b2 + hstep, voffB); PG8_STAGE(PG8_SA(0, 0), a2, voffA);
;             PG8_WAIT_V(8); PG8_WAIT_L(0); PG8_BAR; PG8_MMA(1, 0, At, B0); PG8_MMA(1, 1, At, B1); PG8_BAR; PG8_SCHED;
.Lpeel_k5:
	s_add_u32 s30, s30, 0x80
	s_addc_u32 s31, s31, 0
	s_add_u32 s29, s34, 0x100
	s_addc_u32 s73, s35, 0
	s_mov_b32 s34, 0
	s_add_i32 s77, s34, 2
	s_add_u32 s82, s30, 0x80
	s_addc_u32 s35, s31, 0
	s_add_i32 s92, 0, 0x10000
	s_cmp_eq_u32 s48, s34
	s_cselect_b32 s35, s1, s35
	s_cselect_b32 s34, s0, s82
	v_add_u32_e32 v131, s92, v133
	s_cselect_b32 s85, s61, s73
	s_cselect_b32 s84, s60, s29
	s_add_i32 s82, 0, 0x14000
	ds_read_b128 v[140:143], v131
	ds_read_b128 v[144:147], v131 offset:1024
	ds_read_b128 v[148:151], v131 offset:2048
	ds_read_b128 v[152:155], v131 offset:3072
	v_add_u32_e32 v131, s82, v133
	ds_read_b128 v[156:159], v131
	ds_read_b128 v[160:163], v131 offset:1024
	ds_read_b128 v[164:167], v131 offset:2048
	ds_read_b128 v[168:171], v131 offset:3072
	v_lshl_add_u64 v[212:213], s[30:31], 0, v[136:137]
	s_add_i32 m0, s8, 0xc000
	ds_read_b128 v[172:175], v199
	ds_read_b128 v[176:179], v199 offset:1024
	ds_read_b128 v[180:183], v199 offset:2048
	ds_read_b128 v[184:187], v199 offset:3072
	ds_read_b128 v[188:191], v199 offset:4096
	ds_read_b128 v[192:195], v199 offset:5120
	ds_read_b128 v[200:203], v199 offset:6144
	ds_read_b128 v[204:207], v199 offset:7168
	global_load_lds_dwordx4 v[212:213], off
	v_lshl_add_u64 v[212:213], s[30:31], 0, v[138:139]
	s_add_i32 m0, s8, 0xe000
	s_nop 0
	global_load_lds_dwordx4 v[212:213], off
	s_waitcnt vmcnt(8)
	s_waitcnt lgkmcnt(0)
	s_barrier
	s_setprio 1
	s_waitcnt lgkmcnt(0)
	v_mfma_f32_16x16x32_bf16 v[120:123], v[140:143], v[172:175], 0
	v_mfma_f32_16x16x32_bf16 v[124:127], v[148:151], v[172:175], 0
	v_mfma_f32_16x16x32_bf16 v[108:111], v[140:143], v[180:183], 0
	v_mfma_f32_16x16x32_bf16 v[104:107], v[148:151], v[180:183], 0
	v_mfma_f32_16x16x32_bf16 v[92:95], v[140:143], v[188:191], 0
	v_mfma_f32_16x16x32_bf16 v[88:91], v[148:151], v[188:191], 0
	v_mfma_f32_16x16x32_bf16 v[76:79], v[140:143], v[200:203], 0
	v_mfma_f32_16x16x32_bf16 v[72:75], v[148:151], v[200:203], 0
	v_mfma_f32_16x16x32_bf16 v[120:123], v[144:147], v[176:179], v[120:123]
	v_mfma_f32_16x16x32_bf16 v[124:127], v[152:155], v[176:179], v[124:127]
	v_mfma_f32_16x16x32_bf16 v[108:111], v[144:147], v[184:187], v[108:111]
	v_mfma_f32_16x16x32_bf16 v[104:107], v[152:155], v[184:187], v[104:107]
	v_mfma_f32_16x16x32_bf16 v[92:95], v[144:147], v[192:195], v[92:95]
	v_mfma_f32_16x16x32_bf16 v[88:91], v[152:155], v[192:195], v[88:91]
	v_mfma_f32_16x16x32_bf16 v[76:79], v[144:147], v[204:207], v[76:79]
	v_mfma_f32_16x16x32_bf16 v[72:75], v[152:155], v[204:207], v[72:75]
	s_setprio 0
	s_setprio 1
	v_mfma_f32_16x16x32_bf16 v[116:119], v[156:159], v[172:175], 0
	v_mfma_f32_16x16x32_bf16 v[112:115], v[164:167], v[172:175], 0
	v_mfma_f32_16x16x32_bf16 v[100:103], v[156:159], v[180:183], 0
	v_mfma_f32_16x16x32_bf16 v[96:99], v[164:167], v[180:183], 0
	v_mfma_f32_16x16x32_bf16 v[84:87], v[156:159], v[188:191], 0
	v_mfma_f32_16x16x32_bf16 v[80:83], v[164:167], v[188:191], 0
	v_mfma_f32_16x16x32_bf16 v[68:71], v[156:159], v[200:203], 0
	v_mfma_f32_16x16x32_bf16 v[64:67], v[164:167], v[200:203], 0
	v_mfma_f32_16x16x32_bf16 v[116:119], v[160:163], v[176:179], v[116:119]
	v_mfma_f32_16x16x32_bf16 v[112:115], v[168:171], v[176:179], v[112:115]
	v_mfma_f32_16x16x32_bf16 v[100:103], v[160:163], v[184:187], v[100:103]
	v_mfma_f32_16x16x32_bf16 v[96:99], v[168:171], v[184:187], v[96:99]
	v_mfma_f32_16x16x32_bf16 v[84:87], v[160:163], v[192:195], v[84:87]
	v_mfma_f32_16x16x32_bf16 v[80:83], v[168:171], v[192:195], v[80:83]
	v_mfma_f32_16x16x32_bf16 v[68:71], v[160:163], v[204:207], v[68:71]
	v_mfma_f32_16x16x32_bf16 v[64:67], v[168:171], v[204:207], v[64:67]
	s_setprio 0
	s_barrier
	s_add_i32 s92, s92, s7
	v_lshl_add_u64 v[212:213], s[84:85], 0, v[208:209]
	s_mov_b32 m0, s92
	ds_read_b128 v[172:175], v199 offset:16384
	ds_read_b128 v[176:179], v199 offset:17408
	ds_read_b128 v[180:183], v199 offset:18432
	ds_read_b128 v[184:187], v199 offset:19456
	ds_read_b128 v[188:191], v199 offset:20480
	ds_read_b128 v[192:195], v199 offset:21504
	ds_read_b128 v[200:203], v199 offset:22528
	ds_read_b128 v[204:207], v199 offset:23552
	global_load_lds_dwordx4 v[212:213], off
	s_add_i32 m0, s92, 0x2000
	v_lshl_add_u64 v[214:215], s[84:85], 0, v[128:129]
	s_add_u32 s84, s84, s50
	s_addc_u32 s85, s85, s51
	s_add_i32 s82, s82, s7
	global_load_lds_dwordx4 v[214:215], off
	v_lshl_add_u64 v[216:217], s[84:85], 0, v[208:209]
	s_mov_b32 m0, s82
	v_lshl_add_u64 v[218:219], s[84:85], 0, v[128:129]
	global_load_lds_dwordx4 v[216:217], off
	s_add_i32 m0, s82, 0x2000
	v_lshl_add_u64 v[220:221], s[34:35], 0, v[208:209]
	global_load_lds_dwordx4 v[218:219], off
	s_mov_b32 m0, s8
	v_lshl_add_u64 v[222:223], s[34:35], 0, v[128:129]
	global_load_lds_dwordx4 v[220:221], off
	s_mov_b32 m0, s9
	s_nop 0
	global_load_lds_dwordx4 v[222:223], off
	s_waitcnt vmcnt(8)
	s_waitcnt lgkmcnt(0)
	s_barrier
; #define PG8_STAGE(bufoff, gbase, voff) do { _Pragma("unroll") for (int _i = 0; _i < 2; ++_i) \
;         __builtin_amdgcn_global_load_lds((const unsigned*)((const char*)(gbase) + (voff)[_i]), (PG8_LAS unsigned*)(lds + (bufoff) + ldsw + _i * 8192), 16, 0, 0); } while (0)
; #define PG8_LDA(dst, b, h) do { _Pragma("unroll") for (int m = 0; m < 4; ++m) _Pragma("unroll") for (int k = 0; k < 2; ++k) dst[m][k] = *(const PG8_LAS bf16x8*)(lds + PG8_SA(b, h) + aoff + m * 2048 + k * 1024); } while (0)
; #define PG8_LDB(dst, b, h) do { _Pragma("unroll") for (int n = 0; n < 2; ++n) _Pragma("unroll") for (int k = 0; k < 2; ++k) dst[n][k] = *(const PG8_LAS bf16x8*)(lds + PG8_SB(b, h) + boff + n * 2048 + k * 1024); } while (0)
; #define PG8_MMA(ai, bj, At, Bt) do { __builtin_amdgcn_s_setprio(1); _Pragma("unroll") for (int m = 0; m < 4; ++m) _Pragma("unroll") for (int n = 0; n < 2; ++n) _Pragma("unroll") for (int k = 0; k < 2; ++k) \
;         acc[ai][bj][m][n] = mma16<Epi::F16>(Bt[n][k], At[m][k], acc[ai][bj][m][n]); __builtin_amdgcn_s_setprio(0); } while (0)
; #define PG8_WAIT_V(n) asm volatile("s_waitcnt vmcnt(" #n ")" ::: "memory")
; #define PG8_WAIT_L(n) asm volatile("s_waitcnt lgkmcnt(" #n ")" ::: "memory")
; #define PG8_BAR __builtin_amdgcn_s_barrier()
; #define PG8_SCHED __builtin_amdgcn_sched_barrier(0)
; template <class Epi, class Sched, bool ALIGN_EPI = false, bool SP2 = false>
; __device__ __forceinline__ void gemm_phase(PG8_LAS unsigned char* lds, const Gemm g, const Sched& S, const Epi& E) {
;     ...
;             PG8_WAIT_V(8); PG8_WAIT_L(0); PG8_BAR; PG8_MMA(0, 0, At, B0); PG8_MMA(0, 1, At, B1); PG8_BAR; PG8_SCHED;
;             PG8_LDA(At, 0, 1); PG8_STAGE(PG8_SB(0, 0), b2, voffB); PG8_STAGE(PG8_SB(0, 1), b2 + hstep, voffB); PG8_STAGE(PG8_SA(0, 0), a2, voffA);
;             PG8_WAIT_V(8); PG8_WAIT_L(0); PG8_BAR; PG8_MMA(1, 0, At, B0); PG8_MMA(1, 1, At, B1); PG8_BAR; PG8_SCHED;
;             PG8_LDB(B0, 1, 0); PG8_LDB(B1, 1, 1); PG8_SCHED; PG8_LDA(At, 1, 0); PG8_STAGE(PG8_SA(0, 1), a2 + hstep, voffA);
;             PG8_WAIT_V(8); PG8_WAIT_L(0); PG8_BAR; PG8_MMA(0, 0, At, B0); PG8_MMA(0, 1, At, B1); PG8_BAR; PG8_SCHED;
	s_setprio 1
	s_waitcnt lgkmcnt(0)
	v_mfma_f32_16x16x32_bf16 v[60:63], v[140:143], v[172:175], 0
	v_mfma_f32_16x16x32_bf16 v[56:59], v[148:151], v[172:175], 0
	v_mfma_f32_16x16x32_bf16 v[44:47], v[140:143], v[180:183], 0
	v_mfma_f32_16x16x32_bf16 v[40:43], v[148:151], v[180:183], 0
	v_mfma_f32_16x16x32_bf16 v[28:31], v[140:143], v[188:191], 0
	v_mfma_f32_16x16x32_bf16 v[24:27], v[148:151], v[188:191], 0
	v_mfma_f32_16x16x32_bf16 v[12:15], v[140:143], v[200:203], 0
	v_mfma_f32_16x16x32_bf16 v[8:11], v[148:151], v[200:203], 0
	v_mfma_f32_16x16x32_bf16 v[60:63], v[144:147], v[176:179], v[60:63]
	v_mfma_f32_16x16x32_bf16 v[56:59], v[152:155], v[176:179], v[56:59]
	v_mfma_f32_16x16x32_bf16 v[44:47], v[144:147], v[184:187], v[44:47]
	v_mfma_f32_16x16x32_bf16 v[40:43], v[152:155], v[184:187], v[40:43]
	v_mfma_f32_16x16x32_bf16 v[28:31], v[144:147], v[192:195], v[28:31]
	v_mfma_f32_16x16x32_bf16 v[24:27], v[152:155], v[192:195], v[24:27]
	v_mfma_f32_16x16x32_bf16 v[12:15], v[144:147], v[204:207], v[12:15]
	v_mfma_f32_16x16x32_bf16 v[8:11], v[152:155], v[204:207], v[8:11]
	s_setprio 0
	s_setprio 1
	v_mfma_f32_16x16x32_bf16 v[52:55], v[156:159], v[172:175], 0
	v_mfma_f32_16x16x32_bf16 v[48:51], v[164:167], v[172:175], 0
	v_mfma_f32_16x16x32_bf16 v[36:39], v[156:159], v[180:183], 0
	v_mfma_f32_16x16x32_bf16 v[32:35], v[164:167], v[180:183], 0
	v_mfma_f32_16x16x32_bf16 v[20:23], v[156:159], v[188:191], 0
	v_mfma_f32_16x16x32_bf16 v[16:19], v[164:167], v[188:191], 0
	v_mfma_f32_16x16x32_bf16 v[4:7], v[156:159], v[200:203], 0
	v_mfma_f32_16x16x32_bf16 v[0:3], v[164:167], v[200:203], 0
	v_mfma_f32_16x16x32_bf16 v[52:55], v[160:163], v[176:179], v[52:55]
	v_mfma_f32_16x16x32_bf16 v[48:51], v[168:171], v[176:179], v[48:51]
	v_mfma_f32_16x16x32_bf16 v[36:39], v[160:163], v[184:187], v[36:39]
	v_mfma_f32_16x16x32_bf16 v[32:35], v[168:171], v[184:187], v[32:35]
	v_mfma_f32_16x16x32_bf16 v[20:23], v[160:163], v[192:195], v[20:23]
	v_mfma_f32_16x16x32_bf16 v[16:19], v[168:171], v[192:195], v[16:19]
	v_mfma_f32_16x16x32_bf16 v[4:7], v[160:163], v[204:207], v[4:7]
	v_mfma_f32_16x16x32_bf16 v[0:3], v[168:171], v[204:207], v[0:3]
	s_setprio 0
	s_barrier
	s_add_i32 s82, 0, 0x18000
	v_add_u32_e32 v131, s82, v133
	s_add_i32 s84, 0, 0x1c000
	ds_read_b128 v[140:143], v131
	ds_read_b128 v[144:147], v131 offset:1024
	ds_read_b128 v[148:151], v131 offset:2048
	ds_read_b128 v[152:155], v131 offset:3072
	v_add_u32_e32 v131, s84, v133
	ds_read_b128 v[156:159], v131
	ds_read_b128 v[160:163], v131 offset:1024
	ds_read_b128 v[164:167], v131 offset:2048
	ds_read_b128 v[168:171], v131 offset:3072
	s_add_u32 s34, s34, s50
	s_addc_u32 s35, s35, s51
	s_mov_b32 m0, s11
	v_lshl_add_u64 v[224:225], s[34:35], 0, v[208:209]
	ds_read_b128 v[172:175], v199 offset:32768
	ds_read_b128 v[176:179], v199 offset:33792
	ds_read_b128 v[180:183], v199 offset:34816
	ds_read_b128 v[184:187], v199 offset:35840
	ds_read_b128 v[188:191], v199 offset:36864
	ds_read_b128 v[192:195], v199 offset:37888
	ds_read_b128 v[200:203], v199 offset:38912
	ds_read_b128 v[204:207], v199 offset:39936
	global_load_lds_dwordx4 v[224:225], off
	v_lshl_add_u64 v[224:225], s[34:35], 0, v[128:129]
	s_mov_b32 m0, s36
	s_nop 0
	global_load_lds_dwordx4 v[224:225], off
	s_waitcnt vmcnt(8)
	s_waitcnt lgkmcnt(0)
	s_barrier
	s_setprio 1
	s_waitcnt lgkmcnt(0)
	v_mfma_f32_16x16x32_bf16 v[120:123], v[140:143], v[172:175], v[120:123]
	v_mfma_f32_16x16x32_bf16 v[124:127], v[148:151], v[172:175], v[124:127]
	v_mfma_f32_16x16x32_bf16 v[108:111], v[140:143], v[180:183], v[108:111]
	v_mfma_f32_16x16x32_bf16 v[104:107], v[148:151], v[180:183], v[104:107]
	v_mfma_f32_16x16x32_bf16 v[92:95], v[140:143], v[188:191], v[92:95]
	v_mfma_f32_16x16x32_bf16 v[88:91], v[148:151], v[188:191], v[88:91]
	v_mfma_f32_16x16x32_bf16 v[76:79], v[140:143], v[200:203], v[76:79]
	v_mfma_f32_16x16x32_bf16 v[72:75], v[148:151], v[200:203], v[72:75]
	v_mfma_f32_16x16x32_bf16 v[120:123], v[144:147], v[176:179], v[120:123]
	v_mfma_f32_16x16x32_bf16 v[124:127], v[152:155], v[176:179], v[124:127]
	v_mfma_f32_16x16x32_bf16 v[108:111], v[144:147], v[184:187], v[108:111]
	v_mfma_f32_16x16x32_bf16 v[104:107], v[152:155], v[184:187], v[104:107]
	v_mfma_f32_16x16x32_bf16 v[92:95], v[144:147], v[192:195], v[92:95]
	v_mfma_f32_16x16x32_bf16 v[88:91], v[152:155], v[192:195], v[88:91]
	v_mfma_f32_16x16x32_bf16 v[76:79], v[144:147], v[204:207], v[76:79]
	v_mfma_f32_16x16x32_bf16 v[72:75], v[152:155], v[204:207], v[72:75]
	s_setprio 0
	s_setprio 1
	v_mfma_f32_16x16x32_bf16 v[116:119], v[156:159], v[172:175], v[116:119]
	v_mfma_f32_16x16x32_bf16 v[112:115], v[164:167], v[172:175], v[112:115]
	v_mfma_f32_16x16x32_bf16 v[100:103], v[156:159], v[180:183], v[100:103]
	v_mfma_f32_16x16x32_bf16 v[96:99], v[164:167], v[180:183], v[96:99]
	v_mfma_f32_16x16x32_bf16 v[84:87], v[156:159], v[188:191], v[84:87]
	v_mfma_f32_16x16x32_bf16 v[80:83], v[164:167], v[188:191], v[80:83]
	v_mfma_f32_16x16x32_bf16 v[68:71], v[156:159], v[200:203], v[68:71]
	v_mfma_f32_16x16x32_bf16 v[64:67], v[164:167], v[200:203], v[64:67]
	v_mfma_f32_16x16x32_bf16 v[116:119], v[160:163], v[176:179], v[116:119]
	v_mfma_f32_16x16x32_bf16 v[112:115], v[168:171], v[176:179], v[112:115]
	v_mfma_f32_16x16x32_bf16 v[100:103], v[160:163], v[184:187], v[100:103]
	v_mfma_f32_16x16x32_bf16 v[96:99], v[168:171], v[184:187], v[96:99]
	v_mfma_f32_16x16x32_bf16 v[84:87], v[160:163], v[192:195], v[84:87]
	v_mfma_f32_16x16x32_bf16 v[80:83], v[168:171], v[192:195], v[80:83]
	v_mfma_f32_16x16x32_bf16 v[68:71], v[160:163], v[204:207], v[68:71]
	v_mfma_f32_16x16x32_bf16 v[64:67], v[168:171], v[204:207], v[64:67]
	s_setprio 0
	s_barrier
; #define PG8_STAGE(bufoff, gbase, voff) do { _Pragma("unroll") for (int _i = 0; _i < 2; ++_i) \
;         __builtin_amdgcn_global_load_lds((const unsigned*)((const char*)(gbase) + (voff)[_i]), (PG8_LAS unsigned*)(lds + (bufoff) + ldsw + _i * 8192), 16, 0, 0); } while (0)
; #define PG8_LDA(dst, b, h) do { _Pragma("unroll") for (int m = 0; m < 4; ++m) _Pragma("unroll") for (int k = 0; k < 2; ++k) dst[m][k] = *(const PG8_LAS bf16x8*)(lds + PG8_SA(b, h) + aoff + m * 2048 + k * 1024); } while (0)
; #define PG8_MMA(ai, bj, At, Bt) do { __builtin_amdgcn_s_setprio(1); _Pragma("unroll") for (int m = 0; m < 4; ++m) _Pragma("unroll") for (int n = 0; n < 2; ++n) _Pragma("unroll") for (int k = 0; k < 2; ++k) \
;         acc[ai][bj][m][n] = mma16<Epi::F16>(Bt[n][k], At[m][k], acc[ai][bj][m][n]); __builtin_amdgcn_s_setprio(0); } while (0)
; #define PG8_WAIT_V(n) asm volatile("s_waitcnt vmcnt(" #n ")" ::: "memory")
; #define PG8_WAIT_L(n) asm volatile("s_waitcnt lgkmcnt(" #n ")" ::: "memory")
; #define PG8_BAR __builtin_amdgcn_s_barrier()
; #define PG8_SCHED __builtin_amdgcn_sched_barrier(0)
; template <class Epi, class Sched, bool ALIGN_EPI = false, bool SP2 = false>
; __device__ __forceinline__ void gemm_phase(PG8_LAS unsigned char* lds, const Gemm g, const Sched& S, const Epi& E) {
;     ...
;         for (int t = 0; t < nt; t += 2) {
;             const bool last = (t == nt - 2);
;             const char* a1 = cA + (size_t)(t + 1) * kstep;
;             const char* a2 = last ? nA : cA + (size_t)(t + 2) * kstep; const char* b2 = last ? nB : cB + (size_t)(t + 2) * kstep;
;             const char* a3 = a2 + kstep; const char* b3 = b2 + kstep;
;     ...
;             PG8_LDA(At, 1, 1); PG8_STAGE(PG8_SB(1, 0), b3, voffB); PG8_STAGE(PG8_SB(1, 1), b3 + hstep, voffB); PG8_STAGE(PG8_SA(1, 0), a3, voffA);
;             PG8_WAIT_V(8); PG8_WAIT_L(0); PG8_BAR; PG8_MMA(1, 0, At, B0); PG8_MMA(1, 1, At, B1); PG8_BAR; PG8_SCHED;
	s_add_i32 s34, s82, s7
	v_lshl_add_u64 v[212:213], v[212:213], 0, s[20:21]
	s_mov_b32 m0, s34
	ds_read_b128 v[172:175], v199 offset:49152
	ds_read_b128 v[176:179], v199 offset:50176
	ds_read_b128 v[180:183], v199 offset:51200
	ds_read_b128 v[184:187], v199 offset:52224
	ds_read_b128 v[188:191], v199 offset:53248
	ds_read_b128 v[192:195], v199 offset:54272
	ds_read_b128 v[200:203], v199 offset:55296
	ds_read_b128 v[204:207], v199 offset:56320
	global_load_lds_dwordx4 v[212:213], off
	v_lshl_add_u64 v[212:213], v[214:215], 0, s[20:21]
	s_add_i32 m0, s34, 0x2000
	s_add_i32 s34, s84, s7
	global_load_lds_dwordx4 v[212:213], off
	v_lshl_add_u64 v[212:213], v[216:217], 0, s[20:21]
	s_mov_b32 m0, s34
	s_nop 0
	global_load_lds_dwordx4 v[212:213], off
	v_lshl_add_u64 v[212:213], v[218:219], 0, s[20:21]
	s_add_i32 m0, s34, 0x2000
	s_nop 0
	global_load_lds_dwordx4 v[212:213], off
	v_lshl_add_u64 v[212:213], v[220:221], 0, s[20:21]
	s_mov_b32 m0, s37
	s_nop 0
	global_load_lds_dwordx4 v[212:213], off
	v_lshl_add_u64 v[212:213], v[222:223], 0, s[20:21]
	s_mov_b32 m0, s38
	s_nop 0
	global_load_lds_dwordx4 v[212:213], off
	s_waitcnt vmcnt(8)
	s_waitcnt lgkmcnt(0)
	s_barrier
	s_setprio 1
	s_waitcnt lgkmcnt(0)
	v_mfma_f32_16x16x32_bf16 v[60:63], v[140:143], v[172:175], v[60:63]
	v_mfma_f32_16x16x32_bf16 v[56:59], v[148:151], v[172:175], v[56:59]
	v_mfma_f32_16x16x32_bf16 v[44:47], v[140:143], v[180:183], v[44:47]
	v_mfma_f32_16x16x32_bf16 v[40:43], v[148:151], v[180:183], v[40:43]
	v_mfma_f32_16x16x32_bf16 v[28:31], v[140:143], v[188:191], v[28:31]
	v_mfma_f32_16x16x32_bf16 v[24:27], v[148:151], v[188:191], v[24:27]
	v_mfma_f32_16x16x32_bf16 v[12:15], v[140:143], v[200:203], v[12:15]
	v_mfma_f32_16x16x32_bf16 v[8:11], v[148:151], v[200:203], v[8:11]
	v_mfma_f32_16x16x32_bf16 v[60:63], v[144:147], v[176:179], v[60:63]
	v_mfma_f32_16x16x32_bf16 v[56:59], v[152:155], v[176:179], v[56:59]
	v_mfma_f32_16x16x32_bf16 v[44:47], v[144:147], v[184:187], v[44:47]
	v_mfma_f32_16x16x32_bf16 v[40:43], v[152:155], v[184:187], v[40:43]
	v_mfma_f32_16x16x32_bf16 v[28:31], v[144:147], v[192:195], v[28:31]
	v_mfma_f32_16x16x32_bf16 v[24:27], v[152:155], v[192:195], v[24:27]
	v_mfma_f32_16x16x32_bf16 v[12:15], v[144:147], v[204:207], v[12:15]
	v_mfma_f32_16x16x32_bf16 v[8:11], v[152:155], v[204:207], v[8:11]
	s_setprio 0
	s_setprio 1
	v_mfma_f32_16x16x32_bf16 v[52:55], v[156:159], v[172:175], v[52:55]
	v_mfma_f32_16x16x32_bf16 v[48:51], v[164:167], v[172:175], v[48:51]
	v_mfma_f32_16x16x32_bf16 v[36:39], v[156:159], v[180:183], v[36:39]
	v_mfma_f32_16x16x32_bf16 v[32:35], v[164:167], v[180:183], v[32:35]
	v_mfma_f32_16x16x32_bf16 v[20:23], v[156:159], v[188:191], v[20:23]
	v_mfma_f32_16x16x32_bf16 v[16:19], v[164:167], v[188:191], v[16:19]
	v_mfma_f32_16x16x32_bf16 v[4:7], v[156:159], v[200:203], v[4:7]
	v_mfma_f32_16x16x32_bf16 v[0:3], v[164:167], v[200:203], v[0:3]
	v_mfma_f32_16x16x32_bf16 v[52:55], v[160:163], v[176:179], v[52:55]
	v_mfma_f32_16x16x32_bf16 v[48:51], v[168:171], v[176:179], v[48:51]
	v_mfma_f32_16x16x32_bf16 v[36:39], v[160:163], v[184:187], v[36:39]
	v_mfma_f32_16x16x32_bf16 v[32:35], v[168:171], v[184:187], v[32:35]
	v_mfma_f32_16x16x32_bf16 v[20:23], v[160:163], v[192:195], v[20:23]
	v_mfma_f32_16x16x32_bf16 v[16:19], v[168:171], v[192:195], v[16:19]
	v_mfma_f32_16x16x32_bf16 v[4:7], v[160:163], v[204:207], v[4:7]
	v_mfma_f32_16x16x32_bf16 v[0:3], v[168:171], v[204:207], v[0:3]
	s_setprio 0
	s_barrier
	s_add_u32 s30, s30, 0x100
	s_addc_u32 s31, s31, 0
	s_add_u32 s29, s29, 0x100
	s_addc_u32 s73, s73, 0
	s_cmp_ge_i32 s77, s39
	s_mov_b32 s34, s77
	s_cbranch_scc0 .LBB0_757
	s_branch .LBB0_758

; #define PG8_STAGE(bufoff, gbase, voff) do { _Pragma("unroll") for (int _i = 0; _i < 2; ++_i) \
;         __builtin_amdgcn_global_load_lds((const unsigned*)((const char*)(gbase) + (voff)[_i]), (PG8_LAS unsigned*)(lds + (bufoff) + ldsw + _i * 8192), 16, 0, 0); } while (0)
; #define PG8_LDA(dst, b, h) do { _Pragma("unroll") for (int m = 0; m < 4; ++m) _Pragma("unroll") for (int k = 0; k < 2; ++k) dst[m][k] = *(const PG8_LAS bf16x8*)(lds + PG8_SA(b, h) + aoff + m * 2048 + k * 1024); } while (0)
; #define PG8_LDB(dst, b, h) do { _Pragma("unroll") for (int n = 0; n < 2; ++n) _Pragma("unroll") for (int k = 0; k < 2; ++k) dst[n][k] = *(const PG8_LAS bf16x8*)(lds + PG8_SB(b, h) + boff + n * 2048 + k * 1024); } while (0)
; #define PG8_MMA(ai, bj, At, Bt) do { __builtin_amdgcn_s_setprio(1); _Pragma("unroll") for (int m = 0; m < 4; ++m) _Pragma("unroll") for (int n = 0; n < 2; ++n) _Pragma("unroll") for (int k = 0; k < 2; ++k) \
;         acc[ai][bj][m][n] = mma16<Epi::F16>(Bt[n][k], At[m][k], acc[ai][bj][m][n]); __builtin_amdgcn_s_setprio(0); } while (0)
; #define PG8_WAIT_V(n) asm volatile("s_waitcnt vmcnt(" #n ")" ::: "memory")
; #define PG8_WAIT_L(n) asm volatile("s_waitcnt lgkmcnt(" #n ")" ::: "memory")
; template <class Epi, class Sched, bool ALIGN_EPI = false, bool SP2 = false>
; __device__ __forceinline__ void gemm_phase(PG8_LAS unsigned char* lds, const Gemm g, const Sched& S, const Epi& E) {
;     ...
;         for (int t = 0; t < nt; t += 2) {
;             const bool last = (t == nt - 2);
;             const char* a1 = cA + (size_t)(t + 1) * kstep;
;             const char* a2 = last ? nA : cA + (size_t)(t + 2) * kstep; const char* b2 = last ? nB : cB + (size_t)(t + 2) * kstep;
;             const char* a3 = a2 + kstep; const char* b3 = b2 + kstep;
;             if (last && has_next) S.a_ready(nxt);
;             if constexpr (SP2) {
;             PG8_LDB(B0, 0, 0); PG8_LDB(B1, 0, 1); PG8_SCHED; PG8_LDA(At, 0, 0); PG8_STAGE(PG8_SA(1, 1), a1 + hstep, voffA);
;             PG8_WAIT_V(8); PG8_WAIT_L(0); PG8_BAR; PG8_MMA(0, 0, At, B0); PG8_MMA(0, 1, At, B1); PG8_BAR; PG8_SCHED;
;     ...
; #pragma unroll
;         for (int a = 0; a < 2; ++a)
; #pragma unroll
;             for (int b = 0; b < 2; ++b)
; #pragma unroll
;                 for (int m = 0; m < 4; ++m)
; #pragma unroll
;                     for (int n = 0; n < 2; ++n) acc[a][b][m][n] = (f32x4){0.f, 0.f, 0.f, 0.f};
.LBB0_899:
	s_andn2_b64 vcc, exec, s[56:57]
	s_cbranch_vccz .Lpeel_k6
	v_mov_b32_e32 v127, 0
	v_mov_b32_e32 v126, v127
	v_mov_b32_e32 v125, v127
	v_mov_b32_e32 v124, v127
	v_mov_b32_e32 v123, v127
	v_mov_b32_e32 v122, v127
	v_mov_b32_e32 v121, v127
	v_mov_b32_e32 v120, v127
	v_mov_b32_e32 v111, v127
	v_mov_b32_e32 v110, v127
	v_mov_b32_e32 v109, v127
	v_mov_b32_e32 v108, v127
	v_mov_b32_e32 v107, v127
	v_mov_b32_e32 v106, v127
	v_mov_b32_e32 v105, v127
	v_mov_b32_e32 v104, v127
	v_mov_b32_e32 v95, v127
	v_mov_b32_e32 v94, v127
	v_mov_b32_e32 v93, v127
	v_mov_b32_e32 v92, v127
	v_mov_b32_e32 v91, v127
	v_mov_b32_e32 v90, v127
	v_mov_b32_e32 v89, v127
	v_mov_b32_e32 v88, v127
	v_mov_b32_e32 v79, v127
	v_mov_b32_e32 v78, v127
	v_mov_b32_e32 v77, v127
	v_mov_b32_e32 v76, v127
	v_mov_b32_e32 v75, v127
	v_mov_b32_e32 v74, v127
	v_mov_b32_e32 v73, v127
	v_mov_b32_e32 v72, v127
	v_mov_b32_e32 v119, v127
	v_mov_b32_e32 v118, v127
	v_mov_b32_e32 v117, v127
	v_mov_b32_e32 v116, v127
	v_mov_b32_e32 v115, v127
	v_mov_b32_e32 v114, v127
	v_mov_b32_e32 v113, v127
	v_mov_b32_e32 v112, v127
	v_mov_b32_e32 v103, v127
	v_mov_b32_e32 v102, v127
	v_mov_b32_e32 v101, v127
	v_mov_b32_e32 v100, v127
	v_mov_b32_e32 v99, v127
	v_mov_b32_e32 v98, v127
	v_mov_b32_e32 v97, v127
	v_mov_b32_e32 v96, v127
	v_mov_b32_e32 v87, v127
	v_mov_b32_e32 v86, v127
	v_mov_b32_e32 v85, v127
	v_mov_b32_e32 v84, v127
	v_mov_b32_e32 v83, v127
	v_mov_b32_e32 v82, v127
	v_mov_b32_e32 v81, v127
	v_mov_b32_e32 v80, v127
	v_mov_b32_e32 v71, v127
	v_mov_b32_e32 v70, v127
	v_mov_b32_e32 v69, v127
	v_mov_b32_e32 v68, v127
	v_mov_b32_e32 v67, v127
	v_mov_b32_e32 v66, v127
	v_mov_b32_e32 v65, v127
	v_mov_b32_e32 v64, v127
	v_mov_b32_e32 v63, v127
	v_mov_b32_e32 v62, v127
	v_mov_b32_e32 v61, v127
	v_mov_b32_e32 v60, v127
	v_mov_b32_e32 v59, v127
	v_mov_b32_e32 v58, v127
	v_mov_b32_e32 v57, v127
	v_mov_b32_e32 v56, v127
	v_mov_b32_e32 v47, v127
	v_mov_b32_e32 v46, v127
	v_mov_b32_e32 v45, v127
	v_mov_b32_e32 v44, v127
	v_mov_b32_e32 v43, v127
	v_mov_b32_e32 v42, v127
	v_mov_b32_e32 v41, v127
	v_mov_b32_e32 v40, v127
	v_mov_b32_e32 v31, v127
	v_mov_b32_e32 v30, v127
	v_mov_b32_e32 v29, v127
	v_mov_b32_e32 v28, v127
	v_mov_b32_e32 v27, v127
	v_mov_b32_e32 v26, v127
	v_mov_b32_e32 v25, v127
	v_mov_b32_e32 v24, v127
	v_mov_b32_e32 v15, v127
	v_mov_b32_e32 v14, v127
	v_mov_b32_e32 v13, v127
	v_mov_b32_e32 v12, v127
	v_mov_b32_e32 v11, v127
	v_mov_b32_e32 v10, v127
	v_mov_b32_e32 v9, v127
	v_mov_b32_e32 v8, v127
	v_mov_b32_e32 v55, v127
	v_mov_b32_e32 v54, v127
	v_mov_b32_e32 v53, v127
	v_mov_b32_e32 v52, v127
	v_mov_b32_e32 v51, v127
	v_mov_b32_e32 v50, v127
	v_mov_b32_e32 v49, v127
	v_mov_b32_e32 v48, v127
	v_mov_b32_e32 v39, v127
	v_mov_b32_e32 v38, v127
	v_mov_b32_e32 v37, v127
	v_mov_b32_e32 v36, v127
	v_mov_b32_e32 v35, v127
	v_mov_b32_e32 v34, v127
	v_mov_b32_e32 v33, v127
	v_mov_b32_e32 v32, v127
	v_mov_b32_e32 v23, v127
	v_mov_b32_e32 v22, v127
	v_mov_b32_e32 v21, v127
	v_mov_b32_e32 v20, v127
	v_mov_b32_e32 v19, v127
	v_mov_b32_e32 v18, v127
	v_mov_b32_e32 v17, v127
	v_mov_b32_e32 v16, v127
	v_mov_b32_e32 v7, v127
	v_mov_b32_e32 v6, v127
	v_mov_b32_e32 v5, v127
	v_mov_b32_e32 v4, v127
	v_mov_b32_e32 v3, v127
	v_mov_b32_e32 v2, v127
	v_mov_b32_e32 v1, v127
	v_mov_b32_e32 v0, v127
	s_branch .LBB0_902
.Lpeel_k6:
	s_add_u32 s28, s28, 0x80
	s_addc_u32 s29, s29, 0
	s_add_u32 s34, s30, 0x100
	s_addc_u32 s35, s31, 0
	s_mov_b32 s30, 0
	s_add_i32 s43, s30, 2
	s_add_u32 s44, s28, 0x80
	s_addc_u32 s31, s29, 0
	s_add_i32 s68, 0, 0x10000
	s_cmp_eq_u32 s85, s30
	s_cselect_b32 s31, s1, s31
	s_cselect_b32 s30, s0, s44
	s_cselect_b32 s45, s67, s35
	s_cselect_b32 s44, s66, s34
	s_add_i32 s69, 0, 0x14000
	v_add_u32_e32 v160, s68, v170
	v_add_u32_e32 v168, s69, v170
	ds_read_b128 v[148:151], v160
	ds_read_b128 v[152:155], v160 offset:1024
	ds_read_b128 v[156:159], v160 offset:2048
	ds_read_b128 v[160:163], v160 offset:3072
	ds_read_b128 v[164:167], v168
	ds_read_b128 v[172:175], v168 offset:1024
	ds_read_b128 v[176:179], v168 offset:2048
	ds_read_b128 v[180:183], v168 offset:3072
	v_lshl_add_u64 v[168:169], s[28:29], 0, v[144:145]
	s_add_i32 m0, s72, 0xc000
	ds_read_b128 v[184:187], v171
	ds_read_b128 v[188:191], v171 offset:1024
	ds_read_b128 v[192:195], v171 offset:2048
	ds_read_b128 v[196:199], v171 offset:3072
	ds_read_b128 v[200:203], v171 offset:4096
	ds_read_b128 v[204:207], v171 offset:5120
	ds_read_b128 v[212:215], v171 offset:6144
	ds_read_b128 v[216:219], v171 offset:7168
	global_load_lds_dwordx4 v[168:169], off
	v_lshl_add_u64 v[168:169], s[28:29], 0, v[146:147]
	s_add_i32 m0, s72, 0xe000
	s_nop 0
	global_load_lds_dwordx4 v[168:169], off
	s_waitcnt vmcnt(8)
	s_waitcnt lgkmcnt(0)
	s_barrier
; #define PG8_STAGE(bufoff, gbase, voff) do { _Pragma("unroll") for (int _i = 0; _i < 2; ++_i) \
;         __builtin_amdgcn_global_load_lds((const unsigned*)((const char*)(gbase) + (voff)[_i]), (PG8_LAS unsigned*)(lds + (bufoff) + ldsw + _i * 8192), 16, 0, 0); } while (0)
; #define PG8_LDA(dst, b, h) do { _Pragma("unroll") for (int m = 0; m < 4; ++m) _Pragma("unroll") for (int k = 0; k < 2; ++k) dst[m][k] = *(const PG8_LAS bf16x8*)(lds + PG8_SA(b, h) + aoff + m * 2048 + k * 1024); } while (0)
; #define PG8_MMA(ai, bj, At, Bt) do { __builtin_amdgcn_s_setprio(1); _Pragma("unroll") for (int m = 0; m < 4; ++m) _Pragma("unroll") for (int n = 0; n < 2; ++n) _Pragma("unroll") for (int k = 0; k < 2; ++k) \
;         acc[ai][bj][m][n] = mma16<Epi::F16>(Bt[n][k], At[m][k], acc[ai][bj][m][n]); __builtin_amdgcn_s_setprio(0); } while (0)
; #define PG8_WAIT_V(n) asm volatile("s_waitcnt vmcnt(" #n ")" ::: "memory")
; #define PG8_WAIT_L(n) asm volatile("s_waitcnt lgkmcnt(" #n ")" ::: "memory")
; #define PG8_BAR __builtin_amdgcn_s_barrier()
; #define PG8_SCHED __builtin_amdgcn_sched_barrier(0)
; template <class Epi, class Sched, bool ALIGN_EPI = false, bool SP2 = false>
; __device__ __forceinline__ void gemm_phase(PG8_LAS unsigned char* lds, const Gemm g, const Sched& S, const Epi& E) {
;     ...
;             PG8_WAIT_V(8); PG8_WAIT_L(0); PG8_BAR; PG8_MMA(0, 0, At, B0); PG8_MMA(0, 1, At, B1); PG8_BAR; PG8_SCHED;
;             PG8_LDA(At, 0, 1); PG8_STAGE(PG8_SB(0, 0), b2, voffB); PG8_STAGE(PG8_SB(0, 1), b2 + hstep, voffB); PG8_STAGE(PG8_SA(0, 0), a2, voffA);
;             PG8_WAIT_V(8); PG8_WAIT_L(0); PG8_BAR; PG8_MMA(1, 0, At, B0); PG8_MMA(1, 1, At, B1); PG8_BAR; PG8_SCHED;
	s_setprio 1
	s_waitcnt lgkmcnt(0)
	v_mfma_f32_16x16x32_bf16 v[124:127], v[148:151], v[184:187], 0
	v_mfma_f32_16x16x32_bf16 v[120:123], v[156:159], v[184:187], 0
	v_mfma_f32_16x16x32_bf16 v[108:111], v[148:151], v[192:195], 0
	v_mfma_f32_16x16x32_bf16 v[104:107], v[156:159], v[192:195], 0
	v_mfma_f32_16x16x32_bf16 v[92:95], v[148:151], v[200:203], 0
	v_mfma_f32_16x16x32_bf16 v[88:91], v[156:159], v[200:203], 0
	v_mfma_f32_16x16x32_bf16 v[76:79], v[148:151], v[212:215], 0
	v_mfma_f32_16x16x32_bf16 v[72:75], v[156:159], v[212:215], 0
	v_mfma_f32_16x16x32_bf16 v[124:127], v[152:155], v[188:191], v[124:127]
	v_mfma_f32_16x16x32_bf16 v[120:123], v[160:163], v[188:191], v[120:123]
	v_mfma_f32_16x16x32_bf16 v[108:111], v[152:155], v[196:199], v[108:111]
	v_mfma_f32_16x16x32_bf16 v[104:107], v[160:163], v[196:199], v[104:107]
	v_mfma_f32_16x16x32_bf16 v[92:95], v[152:155], v[204:207], v[92:95]
	v_mfma_f32_16x16x32_bf16 v[88:91], v[160:163], v[204:207], v[88:91]
	v_mfma_f32_16x16x32_bf16 v[76:79], v[152:155], v[216:219], v[76:79]
	v_mfma_f32_16x16x32_bf16 v[72:75], v[160:163], v[216:219], v[72:75]
	s_setprio 0
	s_setprio 1
	v_mfma_f32_16x16x32_bf16 v[116:119], v[164:167], v[184:187], 0
	v_mfma_f32_16x16x32_bf16 v[112:115], v[176:179], v[184:187], 0
	v_mfma_f32_16x16x32_bf16 v[100:103], v[164:167], v[192:195], 0
	v_mfma_f32_16x16x32_bf16 v[96:99], v[176:179], v[192:195], 0
	v_mfma_f32_16x16x32_bf16 v[84:87], v[164:167], v[200:203], 0
	v_mfma_f32_16x16x32_bf16 v[80:83], v[176:179], v[200:203], 0
	v_mfma_f32_16x16x32_bf16 v[68:71], v[164:167], v[212:215], 0
	v_mfma_f32_16x16x32_bf16 v[64:67], v[176:179], v[212:215], 0
	v_mfma_f32_16x16x32_bf16 v[116:119], v[172:175], v[188:191], v[116:119]
	v_mfma_f32_16x16x32_bf16 v[112:115], v[180:183], v[188:191], v[112:115]
	v_mfma_f32_16x16x32_bf16 v[100:103], v[172:175], v[196:199], v[100:103]
	v_mfma_f32_16x16x32_bf16 v[96:99], v[180:183], v[196:199], v[96:99]
	v_mfma_f32_16x16x32_bf16 v[84:87], v[172:175], v[204:207], v[84:87]
	v_mfma_f32_16x16x32_bf16 v[80:83], v[180:183], v[204:207], v[80:83]
	v_mfma_f32_16x16x32_bf16 v[68:71], v[172:175], v[216:219], v[68:71]
	v_mfma_f32_16x16x32_bf16 v[64:67], v[180:183], v[216:219], v[64:67]
	s_setprio 0
	s_barrier
	s_add_i32 s68, s68, s71
	v_lshl_add_u64 v[168:169], s[44:45], 0, v[128:129]
	s_mov_b32 m0, s68
	ds_read_b128 v[184:187], v171 offset:16384
	ds_read_b128 v[188:191], v171 offset:17408
	ds_read_b128 v[192:195], v171 offset:18432
	ds_read_b128 v[196:199], v171 offset:19456
	ds_read_b128 v[200:203], v171 offset:20480
	ds_read_b128 v[204:207], v171 offset:21504
	ds_read_b128 v[212:215], v171 offset:22528
	ds_read_b128 v[216:219], v171 offset:23552
	global_load_lds_dwordx4 v[168:169], off
	s_add_i32 m0, s68, 0x2000
	v_lshl_add_u64 v[220:221], s[44:45], 0, v[130:131]
	s_add_u32 s44, s44, s50
	s_addc_u32 s45, s45, s51
	s_add_i32 s68, s69, s71
	global_load_lds_dwordx4 v[220:221], off
	v_lshl_add_u64 v[222:223], s[44:45], 0, v[128:129]
	s_mov_b32 m0, s68
	v_lshl_add_u64 v[224:225], s[44:45], 0, v[130:131]
	global_load_lds_dwordx4 v[222:223], off
	s_add_i32 m0, s68, 0x2000
	v_lshl_add_u64 v[226:227], s[30:31], 0, v[128:129]
	global_load_lds_dwordx4 v[224:225], off
	s_mov_b32 m0, s72
	v_lshl_add_u64 v[228:229], s[30:31], 0, v[130:131]
	global_load_lds_dwordx4 v[226:227], off
	s_mov_b32 m0, s73
	s_nop 0
	global_load_lds_dwordx4 v[228:229], off
	s_waitcnt vmcnt(8)
	s_waitcnt lgkmcnt(0)
	s_barrier
	s_setprio 1
	s_waitcnt lgkmcnt(0)
	v_mfma_f32_16x16x32_bf16 v[60:63], v[148:151], v[184:187], 0
	v_mfma_f32_16x16x32_bf16 v[56:59], v[156:159], v[184:187], 0
	v_mfma_f32_16x16x32_bf16 v[44:47], v[148:151], v[192:195], 0
	v_mfma_f32_16x16x32_bf16 v[40:43], v[156:159], v[192:195], 0
	v_mfma_f32_16x16x32_bf16 v[28:31], v[148:151], v[200:203], 0
	v_mfma_f32_16x16x32_bf16 v[24:27], v[156:159], v[200:203], 0
	v_mfma_f32_16x16x32_bf16 v[12:15], v[148:151], v[212:215], 0
	v_mfma_f32_16x16x32_bf16 v[8:11], v[156:159], v[212:215], 0
	v_mfma_f32_16x16x32_bf16 v[60:63], v[152:155], v[188:191], v[60:63]
	v_mfma_f32_16x16x32_bf16 v[56:59], v[160:163], v[188:191], v[56:59]
	v_mfma_f32_16x16x32_bf16 v[44:47], v[152:155], v[196:199], v[44:47]
	v_mfma_f32_16x16x32_bf16 v[40:43], v[160:163], v[196:199], v[40:43]
	v_mfma_f32_16x16x32_bf16 v[28:31], v[152:155], v[204:207], v[28:31]
	v_mfma_f32_16x16x32_bf16 v[24:27], v[160:163], v[204:207], v[24:27]
	v_mfma_f32_16x16x32_bf16 v[12:15], v[152:155], v[216:219], v[12:15]
	v_mfma_f32_16x16x32_bf16 v[8:11], v[160:163], v[216:219], v[8:11]
	s_setprio 0
	s_setprio 1
	v_mfma_f32_16x16x32_bf16 v[52:55], v[164:167], v[184:187], 0
	v_mfma_f32_16x16x32_bf16 v[48:51], v[176:179], v[184:187], 0
	v_mfma_f32_16x16x32_bf16 v[36:39], v[164:167], v[192:195], 0
	v_mfma_f32_16x16x32_bf16 v[32:35], v[176:179], v[192:195], 0
	v_mfma_f32_16x16x32_bf16 v[20:23], v[164:167], v[200:203], 0
	v_mfma_f32_16x16x32_bf16 v[16:19], v[176:179], v[200:203], 0
	v_mfma_f32_16x16x32_bf16 v[4:7], v[164:167], v[212:215], 0
	v_mfma_f32_16x16x32_bf16 v[0:3], v[176:179], v[212:215], 0
	v_mfma_f32_16x16x32_bf16 v[52:55], v[172:175], v[188:191], v[52:55]
	v_mfma_f32_16x16x32_bf16 v[48:51], v[180:183], v[188:191], v[48:51]
	v_mfma_f32_16x16x32_bf16 v[36:39], v[172:175], v[196:199], v[36:39]
	v_mfma_f32_16x16x32_bf16 v[32:35], v[180:183], v[196:199], v[32:35]
	v_mfma_f32_16x16x32_bf16 v[20:23], v[172:175], v[204:207], v[20:23]
	v_mfma_f32_16x16x32_bf16 v[16:19], v[180:183], v[204:207], v[16:19]
	v_mfma_f32_16x16x32_bf16 v[4:7], v[172:175], v[216:219], v[4:7]
	v_mfma_f32_16x16x32_bf16 v[0:3], v[180:183], v[216:219], v[0:3]
	s_setprio 0
	s_barrier
; #define PG8_STAGE(bufoff, gbase, voff) do { _Pragma("unroll") for (int _i = 0; _i < 2; ++_i) \
;         __builtin_amdgcn_global_load_lds((const unsigned*)((const char*)(gbase) + (voff)[_i]), (PG8_LAS unsigned*)(lds + (bufoff) + ldsw + _i * 8192), 16, 0, 0); } while (0)
; #define PG8_LDA(dst, b, h) do { _Pragma("unroll") for (int m = 0; m < 4; ++m) _Pragma("unroll") for (int k = 0; k < 2; ++k) dst[m][k] = *(const PG8_LAS bf16x8*)(lds + PG8_SA(b, h) + aoff + m * 2048 + k * 1024); } while (0)
; #define PG8_LDB(dst, b, h) do { _Pragma("unroll") for (int n = 0; n < 2; ++n) _Pragma("unroll") for (int k = 0; k < 2; ++k) dst[n][k] = *(const PG8_LAS bf16x8*)(lds + PG8_SB(b, h) + boff + n * 2048 + k * 1024); } while (0)
; #define PG8_MMA(ai, bj, At, Bt) do { __builtin_amdgcn_s_setprio(1); _Pragma("unroll") for (int m = 0; m < 4; ++m) _Pragma("unroll") for (int n = 0; n < 2; ++n) _Pragma("unroll") for (int k = 0; k < 2; ++k) \
;         acc[ai][bj][m][n] = mma16<Epi::F16>(Bt[n][k], At[m][k], acc[ai][bj][m][n]); __builtin_amdgcn_s_setprio(0); } while (0)
; #define PG8_WAIT_V(n) asm volatile("s_waitcnt vmcnt(" #n ")" ::: "memory")
; #define PG8_WAIT_L(n) asm volatile("s_waitcnt lgkmcnt(" #n ")" ::: "memory")
; #define PG8_BAR __builtin_amdgcn_s_barrier()
; #define PG8_SCHED __builtin_amdgcn_sched_barrier(0)
; template <class Epi, class Sched, bool ALIGN_EPI = false, bool SP2 = false>
; __device__ __forceinline__ void gemm_phase(PG8_LAS unsigned char* lds, const Gemm g, const Sched& S, const Epi& E) {
;     ...
;             PG8_LDB(B0, 1, 0); PG8_LDB(B1, 1, 1); PG8_SCHED; PG8_LDA(At, 1, 0); PG8_STAGE(PG8_SA(0, 1), a2 + hstep, voffA);
;             PG8_WAIT_V(8); PG8_WAIT_L(0); PG8_BAR; PG8_MMA(0, 0, At, B0); PG8_MMA(0, 1, At, B1); PG8_BAR; PG8_SCHED;
	s_add_i32 s44, 0, 0x18000
	s_add_i32 s45, 0, 0x1c000
	v_add_u32_e32 v160, s44, v170
	v_add_u32_e32 v180, s45, v170
	ds_read_b128 v[148:151], v160
	ds_read_b128 v[152:155], v160 offset:1024
	ds_read_b128 v[156:159], v160 offset:2048
	ds_read_b128 v[160:163], v160 offset:3072
	ds_read_b128 v[164:167], v180
	ds_read_b128 v[172:175], v180 offset:1024
	ds_read_b128 v[176:179], v180 offset:2048
	ds_read_b128 v[180:183], v180 offset:3072
	s_add_u32 s30, s30, s50
	s_addc_u32 s31, s31, s51
	s_mov_b32 m0, s7
	v_lshl_add_u64 v[230:231], s[30:31], 0, v[128:129]
	ds_read_b128 v[184:187], v171 offset:32768
	ds_read_b128 v[188:191], v171 offset:33792
	ds_read_b128 v[192:195], v171 offset:34816
	ds_read_b128 v[196:199], v171 offset:35840
	ds_read_b128 v[200:203], v171 offset:36864
	ds_read_b128 v[204:207], v171 offset:37888
	ds_read_b128 v[212:215], v171 offset:38912
	ds_read_b128 v[216:219], v171 offset:39936
	global_load_lds_dwordx4 v[230:231], off
	v_lshl_add_u64 v[230:231], s[30:31], 0, v[130:131]
	s_mov_b32 m0, s8
	s_nop 0
	global_load_lds_dwordx4 v[230:231], off
	s_waitcnt vmcnt(8)
	s_waitcnt lgkmcnt(0)
	s_barrier
	s_setprio 1
	s_waitcnt lgkmcnt(0)
	v_mfma_f32_16x16x32_bf16 v[124:127], v[148:151], v[184:187], v[124:127]
	v_mfma_f32_16x16x32_bf16 v[120:123], v[156:159], v[184:187], v[120:123]
	v_mfma_f32_16x16x32_bf16 v[108:111], v[148:151], v[192:195], v[108:111]
	v_mfma_f32_16x16x32_bf16 v[104:107], v[156:159], v[192:195], v[104:107]
	v_mfma_f32_16x16x32_bf16 v[92:95], v[148:151], v[200:203], v[92:95]
	v_mfma_f32_16x16x32_bf16 v[88:91], v[156:159], v[200:203], v[88:91]
	v_mfma_f32_16x16x32_bf16 v[76:79], v[148:151], v[212:215], v[76:79]
	v_mfma_f32_16x16x32_bf16 v[72:75], v[156:159], v[212:215], v[72:75]
	v_mfma_f32_16x16x32_bf16 v[124:127], v[152:155], v[188:191], v[124:127]
	v_mfma_f32_16x16x32_bf16 v[120:123], v[160:163], v[188:191], v[120:123]
	v_mfma_f32_16x16x32_bf16 v[108:111], v[152:155], v[196:199], v[108:111]
	v_mfma_f32_16x16x32_bf16 v[104:107], v[160:163], v[196:199], v[104:107]
	v_mfma_f32_16x16x32_bf16 v[92:95], v[152:155], v[204:207], v[92:95]
	v_mfma_f32_16x16x32_bf16 v[88:91], v[160:163], v[204:207], v[88:91]
	v_mfma_f32_16x16x32_bf16 v[76:79], v[152:155], v[216:219], v[76:79]
	v_mfma_f32_16x16x32_bf16 v[72:75], v[160:163], v[216:219], v[72:75]
	s_setprio 0
	s_setprio 1
	v_mfma_f32_16x16x32_bf16 v[116:119], v[164:167], v[184:187], v[116:119]
	v_mfma_f32_16x16x32_bf16 v[112:115], v[176:179], v[184:187], v[112:115]
	v_mfma_f32_16x16x32_bf16 v[100:103], v[164:167], v[192:195], v[100:103]
	v_mfma_f32_16x16x32_bf16 v[96:99], v[176:179], v[192:195], v[96:99]
	v_mfma_f32_16x16x32_bf16 v[84:87], v[164:167], v[200:203], v[84:87]
	v_mfma_f32_16x16x32_bf16 v[80:83], v[176:179], v[200:203], v[80:83]
	v_mfma_f32_16x16x32_bf16 v[68:71], v[164:167], v[212:215], v[68:71]
	v_mfma_f32_16x16x32_bf16 v[64:67], v[176:179], v[212:215], v[64:67]
	v_mfma_f32_16x16x32_bf16 v[116:119], v[172:175], v[188:191], v[116:119]
	v_mfma_f32_16x16x32_bf16 v[112:115], v[180:183], v[188:191], v[112:115]
	v_mfma_f32_16x16x32_bf16 v[100:103], v[172:175], v[196:199], v[100:103]
	v_mfma_f32_16x16x32_bf16 v[96:99], v[180:183], v[196:199], v[96:99]
	v_mfma_f32_16x16x32_bf16 v[84:87], v[172:175], v[204:207], v[84:87]
	v_mfma_f32_16x16x32_bf16 v[80:83], v[180:183], v[204:207], v[80:83]
	v_mfma_f32_16x16x32_bf16 v[68:71], v[172:175], v[216:219], v[68:71]
	v_mfma_f32_16x16x32_bf16 v[64:67], v[180:183], v[216:219], v[64:67]
	s_setprio 0
	s_barrier
; #define PG8_STAGE(bufoff, gbase, voff) do { _Pragma("unroll") for (int _i = 0; _i < 2; ++_i) \
;         __builtin_amdgcn_global_load_lds((const unsigned*)((const char*)(gbase) + (voff)[_i]), (PG8_LAS unsigned*)(lds + (bufoff) + ldsw + _i * 8192), 16, 0, 0); } while (0)
; #define PG8_LDA(dst, b, h) do { _Pragma("unroll") for (int m = 0; m < 4; ++m) _Pragma("unroll") for (int k = 0; k < 2; ++k) dst[m][k] = *(const PG8_LAS bf16x8*)(lds + PG8_SA(b, h) + aoff + m * 2048 + k * 1024); } while (0)
; #define PG8_MMA(ai, bj, At, Bt) do { __builtin_amdgcn_s_setprio(1); _Pragma("unroll") for (int m = 0; m < 4; ++m) _Pragma("unroll") for (int n = 0; n < 2; ++n) _Pragma("unroll") for (int k = 0; k < 2; ++k) \
;         acc[ai][bj][m][n] = mma16<Epi::F16>(Bt[n][k], At[m][k], acc[ai][bj][m][n]); __builtin_amdgcn_s_setprio(0); } while (0)
; #define PG8_WAIT_V(n) asm volatile("s_waitcnt vmcnt(" #n ")" ::: "memory")
; #define PG8_WAIT_L(n) asm volatile("s_waitcnt lgkmcnt(" #n ")" ::: "memory")
; #define PG8_BAR __builtin_amdgcn_s_barrier()
; #define PG8_SCHED __builtin_amdgcn_sched_barrier(0)
; template <class Epi, class Sched, bool ALIGN_EPI = false, bool SP2 = false>
; __device__ __forceinline__ void gemm_phase(PG8_LAS unsigned char* lds, const Gemm g, const Sched& S, const Epi& E) {
;     ...
;         for (int t = 0; t < nt; t += 2) {
;             const bool last = (t == nt - 2);
;             const char* a1 = cA + (size_t)(t + 1) * kstep;
;             const char* a2 = last ? nA : cA + (size_t)(t + 2) * kstep; const char* b2 = last ? nB : cB + (size_t)(t + 2) * kstep;
;     ...
;             PG8_LDA(At, 1, 1); PG8_STAGE(PG8_SB(1, 0), b3, voffB); PG8_STAGE(PG8_SB(1, 1), b3 + hstep, voffB); PG8_STAGE(PG8_SA(1, 0), a3, voffA);
;             PG8_WAIT_V(8); PG8_WAIT_L(0); PG8_BAR; PG8_MMA(1, 0, At, B0); PG8_MMA(1, 1, At, B1); PG8_BAR; PG8_SCHED;
	s_add_i32 s30, s44, s71
	v_lshl_add_u64 v[168:169], v[168:169], 0, s[20:21]
	s_mov_b32 m0, s30
	ds_read_b128 v[184:187], v171 offset:49152
	ds_read_b128 v[188:191], v171 offset:50176
	ds_read_b128 v[192:195], v171 offset:51200
	ds_read_b128 v[196:199], v171 offset:52224
	ds_read_b128 v[200:203], v171 offset:53248
	ds_read_b128 v[204:207], v171 offset:54272
	ds_read_b128 v[212:215], v171 offset:55296
	ds_read_b128 v[216:219], v171 offset:56320
	global_load_lds_dwordx4 v[168:169], off
	v_lshl_add_u64 v[168:169], v[220:221], 0, s[20:21]
	s_add_i32 m0, s30, 0x2000
	s_add_i32 s30, s45, s71
	global_load_lds_dwordx4 v[168:169], off
	v_lshl_add_u64 v[168:169], v[222:223], 0, s[20:21]
	s_mov_b32 m0, s30
	s_nop 0
	global_load_lds_dwordx4 v[168:169], off
	v_lshl_add_u64 v[168:169], v[224:225], 0, s[20:21]
	s_add_i32 m0, s30, 0x2000
	s_nop 0
	global_load_lds_dwordx4 v[168:169], off
	v_lshl_add_u64 v[168:169], v[226:227], 0, s[20:21]
	s_mov_b32 m0, s9
	s_nop 0
	global_load_lds_dwordx4 v[168:169], off
	v_lshl_add_u64 v[168:169], v[228:229], 0, s[20:21]
	s_mov_b32 m0, s84
	s_nop 0
	global_load_lds_dwordx4 v[168:169], off
	s_waitcnt vmcnt(8)
	s_waitcnt lgkmcnt(0)
	s_barrier
	s_setprio 1
	s_waitcnt lgkmcnt(0)
	v_mfma_f32_16x16x32_bf16 v[60:63], v[148:151], v[184:187], v[60:63]
	v_mfma_f32_16x16x32_bf16 v[56:59], v[156:159], v[184:187], v[56:59]
	v_mfma_f32_16x16x32_bf16 v[44:47], v[148:151], v[192:195], v[44:47]
	v_mfma_f32_16x16x32_bf16 v[40:43], v[156:159], v[192:195], v[40:43]
	v_mfma_f32_16x16x32_bf16 v[28:31], v[148:151], v[200:203], v[28:31]
	v_mfma_f32_16x16x32_bf16 v[24:27], v[156:159], v[200:203], v[24:27]
	v_mfma_f32_16x16x32_bf16 v[12:15], v[148:151], v[212:215], v[12:15]
	v_mfma_f32_16x16x32_bf16 v[8:11], v[156:159], v[212:215], v[8:11]
	v_mfma_f32_16x16x32_bf16 v[60:63], v[152:155], v[188:191], v[60:63]
	v_mfma_f32_16x16x32_bf16 v[56:59], v[160:163], v[188:191], v[56:59]
	v_mfma_f32_16x16x32_bf16 v[44:47], v[152:155], v[196:199], v[44:47]
	v_mfma_f32_16x16x32_bf16 v[40:43], v[160:163], v[196:199], v[40:43]
	v_mfma_f32_16x16x32_bf16 v[28:31], v[152:155], v[204:207], v[28:31]
	v_mfma_f32_16x16x32_bf16 v[24:27], v[160:163], v[204:207], v[24:27]
	v_mfma_f32_16x16x32_bf16 v[12:15], v[152:155], v[216:219], v[12:15]
	v_mfma_f32_16x16x32_bf16 v[8:11], v[160:163], v[216:219], v[8:11]
	s_setprio 0
	s_setprio 1
	v_mfma_f32_16x16x32_bf16 v[52:55], v[164:167], v[184:187], v[52:55]
	v_mfma_f32_16x16x32_bf16 v[48:51], v[176:179], v[184:187], v[48:51]
	v_mfma_f32_16x16x32_bf16 v[36:39], v[164:167], v[192:195], v[36:39]
	v_mfma_f32_16x16x32_bf16 v[32:35], v[176:179], v[192:195], v[32:35]
	v_mfma_f32_16x16x32_bf16 v[20:23], v[164:167], v[200:203], v[20:23]
	v_mfma_f32_16x16x32_bf16 v[16:19], v[176:179], v[200:203], v[16:19]
	v_mfma_f32_16x16x32_bf16 v[4:7], v[164:167], v[212:215], v[4:7]
	v_mfma_f32_16x16x32_bf16 v[0:3], v[176:179], v[212:215], v[0:3]
	v_mfma_f32_16x16x32_bf16 v[52:55], v[172:175], v[188:191], v[52:55]
	v_mfma_f32_16x16x32_bf16 v[48:51], v[180:183], v[188:191], v[48:51]
	v_mfma_f32_16x16x32_bf16 v[36:39], v[172:175], v[196:199], v[36:39]
	v_mfma_f32_16x16x32_bf16 v[32:35], v[180:183], v[196:199], v[32:35]
	v_mfma_f32_16x16x32_bf16 v[20:23], v[172:175], v[204:207], v[20:23]
	v_mfma_f32_16x16x32_bf16 v[16:19], v[180:183], v[204:207], v[16:19]
	v_mfma_f32_16x16x32_bf16 v[4:7], v[172:175], v[216:219], v[4:7]
	v_mfma_f32_16x16x32_bf16 v[0:3], v[180:183], v[216:219], v[0:3]
	s_setprio 0
	s_barrier
	s_add_u32 s28, s28, 0x100
	s_addc_u32 s29, s29, 0
	s_add_u32 s34, s34, 0x100
	s_addc_u32 s35, s35, 0
	s_cmp_ge_i32 s43, s96
	s_mov_b32 s30, s43
	s_cbranch_scc0 .LBB0_901
	s_branch .LBB0_902

; #define PG8_STAGE(bufoff, gbase, voff) do { _Pragma("unroll") for (int _i = 0; _i < 2; ++_i) \
;         __builtin_amdgcn_global_load_lds((const unsigned*)((const char*)(gbase) + (voff)[_i]), (PG8_LAS unsigned*)(lds + (bufoff) + ldsw + _i * 8192), 16, 0, 0); } while (0)
; #define PG8_LDA(dst, b, h) do { _Pragma("unroll") for (int m = 0; m < 4; ++m) _Pragma("unroll") for (int k = 0; k < 2; ++k) dst[m][k] = *(const PG8_LAS bf16x8*)(lds + PG8_SA(b, h) + aoff + m * 2048 + k * 1024); } while (0)
; #define PG8_LDB(dst, b, h) do { _Pragma("unroll") for (int n = 0; n < 2; ++n) _Pragma("unroll") for (int k = 0; k < 2; ++k) dst[n][k] = *(const PG8_LAS bf16x8*)(lds + PG8_SB(b, h) + boff + n * 2048 + k * 1024); } while (0)
; #define PG8_MMA(ai, bj, At, Bt) do { __builtin_amdgcn_s_setprio(1); _Pragma("unroll") for (int m = 0; m < 4; ++m) _Pragma("unroll") for (int n = 0; n < 2; ++n) _Pragma("unroll") for (int k = 0; k < 2; ++k) \
;         acc[ai][bj][m][n] = mma16<Epi::F16>(Bt[n][k], At[m][k], acc[ai][bj][m][n]); __builtin_amdgcn_s_setprio(0); } while (0)
; #define PG8_WAIT_V(n) asm volatile("s_waitcnt vmcnt(" #n ")" ::: "memory")
; #define PG8_WAIT_L(n) asm volatile("s_waitcnt lgkmcnt(" #n ")" ::: "memory")
; template <class Epi, class Sched, bool ALIGN_EPI = false, bool SP2 = false>
; __device__ __forceinline__ void gemm_phase(PG8_LAS unsigned char* lds, const Gemm g, const Sched& S, const Epi& E) {
;     ...
;         for (int t = 0; t < nt; t += 2) {
;             const bool last = (t == nt - 2);
;             const char* a1 = cA + (size_t)(t + 1) * kstep;
;             const char* a2 = last ? nA : cA + (size_t)(t + 2) * kstep; const char* b2 = last ? nB : cB + (size_t)(t + 2) * kstep;
;             const char* a3 = a2 + kstep; const char* b3 = b2 + kstep;
;             if (last && has_next) S.a_ready(nxt);
;             if constexpr (SP2) {
;             PG8_LDB(B0, 0, 0); PG8_LDB(B1, 0, 1); PG8_SCHED; PG8_LDA(At, 0, 0); PG8_STAGE(PG8_SA(1, 1), a1 + hstep, voffA);
;             PG8_WAIT_V(8); PG8_WAIT_L(0); PG8_BAR; PG8_MMA(0, 0, At, B0); PG8_MMA(0, 1, At, B1); PG8_BAR; PG8_SCHED;
;     ...
; #pragma unroll
;         for (int a = 0; a < 2; ++a)
; #pragma unroll
;             for (int b = 0; b < 2; ++b)
; #pragma unroll
;                 for (int m = 0; m < 4; ++m)
; #pragma unroll
;                     for (int n = 0; n < 2; ++n) acc[a][b][m][n] = (f32x4){0.f, 0.f, 0.f, 0.f};
.LBB0_1145:
	s_waitcnt vmcnt(0)
	s_andn2_b64 vcc, exec, s[50:51]
	s_cbranch_vccz .Lpeel_k7
	v_mov_b32_e32 v127, 0
	v_mov_b32_e32 v126, v127
	v_mov_b32_e32 v125, v127
	v_mov_b32_e32 v124, v127
	v_mov_b32_e32 v123, v127
	v_mov_b32_e32 v122, v127
	v_mov_b32_e32 v121, v127
	v_mov_b32_e32 v120, v127
	v_mov_b32_e32 v111, v127
	v_mov_b32_e32 v110, v127
	v_mov_b32_e32 v109, v127
	v_mov_b32_e32 v108, v127
	v_mov_b32_e32 v107, v127
	v_mov_b32_e32 v106, v127
	v_mov_b32_e32 v105, v127
	v_mov_b32_e32 v104, v127
	v_mov_b32_e32 v95, v127
	v_mov_b32_e32 v94, v127
	v_mov_b32_e32 v93, v127
	v_mov_b32_e32 v92, v127
	v_mov_b32_e32 v91, v127
	v_mov_b32_e32 v90, v127
	v_mov_b32_e32 v89, v127
	v_mov_b32_e32 v88, v127
	v_mov_b32_e32 v79, v127
	v_mov_b32_e32 v78, v127
	v_mov_b32_e32 v77, v127
	v_mov_b32_e32 v76, v127
	v_mov_b32_e32 v75, v127
	v_mov_b32_e32 v74, v127
	v_mov_b32_e32 v73, v127
	v_mov_b32_e32 v72, v127
	v_mov_b32_e32 v119, v127
	v_mov_b32_e32 v118, v127
	v_mov_b32_e32 v117, v127
	v_mov_b32_e32 v116, v127
	v_mov_b32_e32 v115, v127
	v_mov_b32_e32 v114, v127
	v_mov_b32_e32 v113, v127
	v_mov_b32_e32 v112, v127
	v_mov_b32_e32 v103, v127
	v_mov_b32_e32 v102, v127
	v_mov_b32_e32 v101, v127
	v_mov_b32_e32 v100, v127
	v_mov_b32_e32 v99, v127
	v_mov_b32_e32 v98, v127
	v_mov_b32_e32 v97, v127
	v_mov_b32_e32 v96, v127
	v_mov_b32_e32 v87, v127
	v_mov_b32_e32 v86, v127
	v_mov_b32_e32 v85, v127
	v_mov_b32_e32 v84, v127
	v_mov_b32_e32 v83, v127
	v_mov_b32_e32 v82, v127
	v_mov_b32_e32 v81, v127
	v_mov_b32_e32 v80, v127
	v_mov_b32_e32 v71, v127
	v_mov_b32_e32 v70, v127
	v_mov_b32_e32 v69, v127
	v_mov_b32_e32 v68, v127
	v_mov_b32_e32 v67, v127
	v_mov_b32_e32 v66, v127
	v_mov_b32_e32 v65, v127
	v_mov_b32_e32 v64, v127
	v_mov_b32_e32 v63, v127
	v_mov_b32_e32 v62, v127
	v_mov_b32_e32 v61, v127
	v_mov_b32_e32 v60, v127
	v_mov_b32_e32 v59, v127
	v_mov_b32_e32 v58, v127
	v_mov_b32_e32 v57, v127
	v_mov_b32_e32 v56, v127
	v_mov_b32_e32 v47, v127
	v_mov_b32_e32 v46, v127
	v_mov_b32_e32 v45, v127
	v_mov_b32_e32 v44, v127
	v_mov_b32_e32 v43, v127
	v_mov_b32_e32 v42, v127
	v_mov_b32_e32 v41, v127
	v_mov_b32_e32 v40, v127
	v_mov_b32_e32 v31, v127
	v_mov_b32_e32 v30, v127
	v_mov_b32_e32 v29, v127
	v_mov_b32_e32 v28, v127
	v_mov_b32_e32 v27, v127
	v_mov_b32_e32 v26, v127
	v_mov_b32_e32 v25, v127
	v_mov_b32_e32 v24, v127
	v_mov_b32_e32 v15, v127
	v_mov_b32_e32 v14, v127
	v_mov_b32_e32 v13, v127
	v_mov_b32_e32 v12, v127
	v_mov_b32_e32 v11, v127
	v_mov_b32_e32 v10, v127
	v_mov_b32_e32 v9, v127
	v_mov_b32_e32 v8, v127
	v_mov_b32_e32 v55, v127
	v_mov_b32_e32 v54, v127
	v_mov_b32_e32 v53, v127
	v_mov_b32_e32 v52, v127
	v_mov_b32_e32 v51, v127
	v_mov_b32_e32 v50, v127
	v_mov_b32_e32 v49, v127
	v_mov_b32_e32 v48, v127
	v_mov_b32_e32 v39, v127
	v_mov_b32_e32 v38, v127
	v_mov_b32_e32 v37, v127
	v_mov_b32_e32 v36, v127
	v_mov_b32_e32 v35, v127
	v_mov_b32_e32 v34, v127
	v_mov_b32_e32 v33, v127
	v_mov_b32_e32 v32, v127
	v_mov_b32_e32 v23, v127
	v_mov_b32_e32 v22, v127
	v_mov_b32_e32 v21, v127
	v_mov_b32_e32 v20, v127
	v_mov_b32_e32 v19, v127
	v_mov_b32_e32 v18, v127
	v_mov_b32_e32 v17, v127
	v_mov_b32_e32 v16, v127
	v_mov_b32_e32 v7, v127
	v_mov_b32_e32 v6, v127
	v_mov_b32_e32 v5, v127
	v_mov_b32_e32 v4, v127
	v_mov_b32_e32 v3, v127
	v_mov_b32_e32 v2, v127
	v_mov_b32_e32 v1, v127
	v_mov_b32_e32 v0, v127
	s_branch .LBB0_1148
.Lpeel_k7:
	s_add_u32 s30, s30, 0x80
	s_addc_u32 s31, s31, 0
	s_add_u32 s69, s34, 0x100
	s_addc_u32 s70, s35, 0
	s_mov_b32 s34, 0
	s_add_i32 s71, s34, 2
	s_add_u32 s72, s30, 0x80
	s_addc_u32 s35, s31, 0
	s_add_i32 s77, 0, 0x10000
	s_cmp_eq_u32 s65, s34
	s_cselect_b32 s35, s1, s35
	s_cselect_b32 s34, s0, s72
	s_cselect_b32 s73, s55, s70
	s_cselect_b32 s72, s54, s69
	s_add_i32 s82, 0, 0x14000
	v_add_u32_e32 v140, s77, v191
	v_add_u32_e32 v156, s82, v191
	ds_read_b128 v[128:131], v140
	ds_read_b128 v[132:135], v140 offset:1024
	ds_read_b128 v[136:139], v140 offset:2048
	ds_read_b128 v[140:143], v140 offset:3072
	ds_read_b128 v[144:147], v156
	ds_read_b128 v[148:151], v156 offset:1024
	ds_read_b128 v[152:155], v156 offset:2048
	ds_read_b128 v[156:159], v156 offset:3072
	v_lshl_add_u64 v[192:193], s[30:31], 0, v[182:183]
	s_add_i32 m0, s48, 0xc000
	ds_read_b128 v[160:163], v195
	ds_read_b128 v[164:167], v195 offset:1024
	ds_read_b128 v[168:171], v195 offset:2048
	ds_read_b128 v[172:175], v195 offset:3072
	ds_read_b128 v[186:189], v195 offset:4096
	ds_read_b128 v[196:199], v195 offset:5120
	ds_read_b128 v[200:203], v195 offset:6144
	ds_read_b128 v[204:207], v195 offset:7168
	global_load_lds_dwordx4 v[192:193], off
	v_lshl_add_u64 v[192:193], s[30:31], 0, v[184:185]
	s_add_i32 m0, s48, 0xe000
	s_nop 0
	global_load_lds_dwordx4 v[192:193], off
	s_waitcnt vmcnt(8)
	s_waitcnt lgkmcnt(0)
	s_barrier
; #define PG8_STAGE(bufoff, gbase, voff) do { _Pragma("unroll") for (int _i = 0; _i < 2; ++_i) \
;         __builtin_amdgcn_global_load_lds((const unsigned*)((const char*)(gbase) + (voff)[_i]), (PG8_LAS unsigned*)(lds + (bufoff) + ldsw + _i * 8192), 16, 0, 0); } while (0)
; #define PG8_LDA(dst, b, h) do { _Pragma("unroll") for (int m = 0; m < 4; ++m) _Pragma("unroll") for (int k = 0; k < 2; ++k) dst[m][k] = *(const PG8_LAS bf16x8*)(lds + PG8_SA(b, h) + aoff + m * 2048 + k * 1024); } while (0)
; #define PG8_MMA(ai, bj, At, Bt) do { __builtin_amdgcn_s_setprio(1); _Pragma("unroll") for (int m = 0; m < 4; ++m) _Pragma("unroll") for (int n = 0; n < 2; ++n) _Pragma("unroll") for (int k = 0; k < 2; ++k) \
;         acc[ai][bj][m][n] = mma16<Epi::F16>(Bt[n][k], At[m][k], acc[ai][bj][m][n]); __builtin_amdgcn_s_setprio(0); } while (0)
; #define PG8_WAIT_V(n) asm volatile("s_waitcnt vmcnt(" #n ")" ::: "memory")
; #define PG8_WAIT_L(n) asm volatile("s_waitcnt lgkmcnt(" #n ")" ::: "memory")
; #define PG8_BAR __builtin_amdgcn_s_barrier()
; #define PG8_SCHED __builtin_amdgcn_sched_barrier(0)
; template <class Epi, class Sched, bool ALIGN_EPI = false, bool SP2 = false>
; __device__ __forceinline__ void gemm_phase(PG8_LAS unsigned char* lds, const Gemm g, const Sched& S, const Epi& E) {
;     ...
;             PG8_WAIT_V(8); PG8_WAIT_L(0); PG8_BAR; PG8_MMA(0, 0, At, B0); PG8_MMA(0, 1, At, B1); PG8_BAR; PG8_SCHED;
;             PG8_LDA(At, 0, 1); PG8_STAGE(PG8_SB(0, 0), b2, voffB); PG8_STAGE(PG8_SB(0, 1), b2 + hstep, voffB); PG8_STAGE(PG8_SA(0, 0), a2, voffA);
;             PG8_WAIT_V(8); PG8_WAIT_L(0); PG8_BAR; PG8_MMA(1, 0, At, B0); PG8_MMA(1, 1, At, B1); PG8_BAR; PG8_SCHED;
	s_setprio 1
	s_waitcnt lgkmcnt(0)
	v_mfma_f32_16x16x32_bf16 v[124:127], v[128:131], v[160:163], 0
	v_mfma_f32_16x16x32_bf16 v[120:123], v[136:139], v[160:163], 0
	v_mfma_f32_16x16x32_bf16 v[108:111], v[128:131], v[168:171], 0
	v_mfma_f32_16x16x32_bf16 v[104:107], v[136:139], v[168:171], 0
	v_mfma_f32_16x16x32_bf16 v[92:95], v[128:131], v[186:189], 0
	v_mfma_f32_16x16x32_bf16 v[88:91], v[136:139], v[186:189], 0
	v_mfma_f32_16x16x32_bf16 v[76:79], v[128:131], v[200:203], 0
	v_mfma_f32_16x16x32_bf16 v[72:75], v[136:139], v[200:203], 0
	v_mfma_f32_16x16x32_bf16 v[124:127], v[132:135], v[164:167], v[124:127]
	v_mfma_f32_16x16x32_bf16 v[120:123], v[140:143], v[164:167], v[120:123]
	v_mfma_f32_16x16x32_bf16 v[108:111], v[132:135], v[172:175], v[108:111]
	v_mfma_f32_16x16x32_bf16 v[104:107], v[140:143], v[172:175], v[104:107]
	v_mfma_f32_16x16x32_bf16 v[92:95], v[132:135], v[196:199], v[92:95]
	v_mfma_f32_16x16x32_bf16 v[88:91], v[140:143], v[196:199], v[88:91]
	v_mfma_f32_16x16x32_bf16 v[76:79], v[132:135], v[204:207], v[76:79]
	v_mfma_f32_16x16x32_bf16 v[72:75], v[140:143], v[204:207], v[72:75]
	s_setprio 0
	s_setprio 1
	v_mfma_f32_16x16x32_bf16 v[116:119], v[144:147], v[160:163], 0
	v_mfma_f32_16x16x32_bf16 v[112:115], v[152:155], v[160:163], 0
	v_mfma_f32_16x16x32_bf16 v[100:103], v[144:147], v[168:171], 0
	v_mfma_f32_16x16x32_bf16 v[96:99], v[152:155], v[168:171], 0
	v_mfma_f32_16x16x32_bf16 v[84:87], v[144:147], v[186:189], 0
	v_mfma_f32_16x16x32_bf16 v[80:83], v[152:155], v[186:189], 0
	v_mfma_f32_16x16x32_bf16 v[68:71], v[144:147], v[200:203], 0
	v_mfma_f32_16x16x32_bf16 v[64:67], v[152:155], v[200:203], 0
	v_mfma_f32_16x16x32_bf16 v[116:119], v[148:151], v[164:167], v[116:119]
	v_mfma_f32_16x16x32_bf16 v[112:115], v[156:159], v[164:167], v[112:115]
	v_mfma_f32_16x16x32_bf16 v[100:103], v[148:151], v[172:175], v[100:103]
	v_mfma_f32_16x16x32_bf16 v[96:99], v[156:159], v[172:175], v[96:99]
	v_mfma_f32_16x16x32_bf16 v[84:87], v[148:151], v[196:199], v[84:87]
	v_mfma_f32_16x16x32_bf16 v[80:83], v[156:159], v[196:199], v[80:83]
	v_mfma_f32_16x16x32_bf16 v[68:71], v[148:151], v[204:207], v[68:71]
	v_mfma_f32_16x16x32_bf16 v[64:67], v[156:159], v[204:207], v[64:67]
	s_setprio 0
	s_barrier
	s_add_i32 s77, s77, s3
	v_lshl_add_u64 v[192:193], s[72:73], 0, v[178:179]
	s_mov_b32 m0, s77
	ds_read_b128 v[160:163], v195 offset:16384
	ds_read_b128 v[164:167], v195 offset:17408
	ds_read_b128 v[168:171], v195 offset:18432
	ds_read_b128 v[172:175], v195 offset:19456
	ds_read_b128 v[186:189], v195 offset:20480
	ds_read_b128 v[196:199], v195 offset:21504
	ds_read_b128 v[200:203], v195 offset:22528
	ds_read_b128 v[204:207], v195 offset:23552
	global_load_lds_dwordx4 v[192:193], off
	s_add_i32 m0, s77, 0x2000
	v_lshl_add_u64 v[212:213], s[72:73], 0, v[176:177]
	s_add_u32 s72, s72, s42
	s_addc_u32 s73, s73, s43
	s_add_i32 s77, s82, s3
	global_load_lds_dwordx4 v[212:213], off
	v_lshl_add_u64 v[214:215], s[72:73], 0, v[178:179]
	s_mov_b32 m0, s77
	v_lshl_add_u64 v[216:217], s[72:73], 0, v[176:177]
	global_load_lds_dwordx4 v[214:215], off
	s_add_i32 m0, s77, 0x2000
	v_lshl_add_u64 v[218:219], s[34:35], 0, v[178:179]
	global_load_lds_dwordx4 v[216:217], off
	s_mov_b32 m0, s48
	v_lshl_add_u64 v[220:221], s[34:35], 0, v[176:177]
	global_load_lds_dwordx4 v[218:219], off
	s_mov_b32 m0, s56
	s_nop 0
	global_load_lds_dwordx4 v[220:221], off
	s_waitcnt vmcnt(8)
	s_waitcnt lgkmcnt(0)
	s_barrier
	s_setprio 1
	s_waitcnt lgkmcnt(0)
	v_mfma_f32_16x16x32_bf16 v[60:63], v[128:131], v[160:163], 0
	v_mfma_f32_16x16x32_bf16 v[56:59], v[136:139], v[160:163], 0
	v_mfma_f32_16x16x32_bf16 v[44:47], v[128:131], v[168:171], 0
	v_mfma_f32_16x16x32_bf16 v[40:43], v[136:139], v[168:171], 0
	v_mfma_f32_16x16x32_bf16 v[28:31], v[128:131], v[186:189], 0
	v_mfma_f32_16x16x32_bf16 v[24:27], v[136:139], v[186:189], 0
	v_mfma_f32_16x16x32_bf16 v[12:15], v[128:131], v[200:203], 0
	v_mfma_f32_16x16x32_bf16 v[8:11], v[136:139], v[200:203], 0
	v_mfma_f32_16x16x32_bf16 v[60:63], v[132:135], v[164:167], v[60:63]
	v_mfma_f32_16x16x32_bf16 v[56:59], v[140:143], v[164:167], v[56:59]
	v_mfma_f32_16x16x32_bf16 v[44:47], v[132:135], v[172:175], v[44:47]
	v_mfma_f32_16x16x32_bf16 v[40:43], v[140:143], v[172:175], v[40:43]
	v_mfma_f32_16x16x32_bf16 v[28:31], v[132:135], v[196:199], v[28:31]
	v_mfma_f32_16x16x32_bf16 v[24:27], v[140:143], v[196:199], v[24:27]
	v_mfma_f32_16x16x32_bf16 v[12:15], v[132:135], v[204:207], v[12:15]
	v_mfma_f32_16x16x32_bf16 v[8:11], v[140:143], v[204:207], v[8:11]
	s_setprio 0
	s_setprio 1
	v_mfma_f32_16x16x32_bf16 v[52:55], v[144:147], v[160:163], 0
	v_mfma_f32_16x16x32_bf16 v[48:51], v[152:155], v[160:163], 0
	v_mfma_f32_16x16x32_bf16 v[36:39], v[144:147], v[168:171], 0
	v_mfma_f32_16x16x32_bf16 v[32:35], v[152:155], v[168:171], 0
	v_mfma_f32_16x16x32_bf16 v[20:23], v[144:147], v[186:189], 0
	v_mfma_f32_16x16x32_bf16 v[16:19], v[152:155], v[186:189], 0
	v_mfma_f32_16x16x32_bf16 v[4:7], v[144:147], v[200:203], 0
	v_mfma_f32_16x16x32_bf16 v[0:3], v[152:155], v[200:203], 0
	v_mfma_f32_16x16x32_bf16 v[52:55], v[148:151], v[164:167], v[52:55]
	v_mfma_f32_16x16x32_bf16 v[48:51], v[156:159], v[164:167], v[48:51]
	v_mfma_f32_16x16x32_bf16 v[36:39], v[148:151], v[172:175], v[36:39]
	v_mfma_f32_16x16x32_bf16 v[32:35], v[156:159], v[172:175], v[32:35]
	v_mfma_f32_16x16x32_bf16 v[20:23], v[148:151], v[196:199], v[20:23]
	v_mfma_f32_16x16x32_bf16 v[16:19], v[156:159], v[196:199], v[16:19]
	v_mfma_f32_16x16x32_bf16 v[4:7], v[148:151], v[204:207], v[4:7]
	v_mfma_f32_16x16x32_bf16 v[0:3], v[156:159], v[204:207], v[0:3]
	s_setprio 0
	s_barrier
; #define PG8_STAGE(bufoff, gbase, voff) do { _Pragma("unroll") for (int _i = 0; _i < 2; ++_i) \
;         __builtin_amdgcn_global_load_lds((const unsigned*)((const char*)(gbase) + (voff)[_i]), (PG8_LAS unsigned*)(lds + (bufoff) + ldsw + _i * 8192), 16, 0, 0); } while (0)
; #define PG8_LDA(dst, b, h) do { _Pragma("unroll") for (int m = 0; m < 4; ++m) _Pragma("unroll") for (int k = 0; k < 2; ++k) dst[m][k] = *(const PG8_LAS bf16x8*)(lds + PG8_SA(b, h) + aoff + m * 2048 + k * 1024); } while (0)
; #define PG8_LDB(dst, b, h) do { _Pragma("unroll") for (int n = 0; n < 2; ++n) _Pragma("unroll") for (int k = 0; k < 2; ++k) dst[n][k] = *(const PG8_LAS bf16x8*)(lds + PG8_SB(b, h) + boff + n * 2048 + k * 1024); } while (0)
; #define PG8_MMA(ai, bj, At, Bt) do { __builtin_amdgcn_s_setprio(1); _Pragma("unroll") for (int m = 0; m < 4; ++m) _Pragma("unroll") for (int n = 0; n < 2; ++n) _Pragma("unroll") for (int k = 0; k < 2; ++k) \
;         acc[ai][bj][m][n] = mma16<Epi::F16>(Bt[n][k], At[m][k], acc[ai][bj][m][n]); __builtin_amdgcn_s_setprio(0); } while (0)
; #define PG8_WAIT_V(n) asm volatile("s_waitcnt vmcnt(" #n ")" ::: "memory")
; #define PG8_WAIT_L(n) asm volatile("s_waitcnt lgkmcnt(" #n ")" ::: "memory")
; #define PG8_BAR __builtin_amdgcn_s_barrier()
; #define PG8_SCHED __builtin_amdgcn_sched_barrier(0)
; template <class Epi, class Sched, bool ALIGN_EPI = false, bool SP2 = false>
; __device__ __forceinline__ void gemm_phase(PG8_LAS unsigned char* lds, const Gemm g, const Sched& S, const Epi& E) {
;     ...
;             PG8_LDB(B0, 1, 0); PG8_LDB(B1, 1, 1); PG8_SCHED; PG8_LDA(At, 1, 0); PG8_STAGE(PG8_SA(0, 1), a2 + hstep, voffA);
;             PG8_WAIT_V(8); PG8_WAIT_L(0); PG8_BAR; PG8_MMA(0, 0, At, B0); PG8_MMA(0, 1, At, B1); PG8_BAR; PG8_SCHED;
	s_add_i32 s72, 0, 0x18000
	s_add_i32 s73, 0, 0x1c000
	v_add_u32_e32 v140, s72, v191
	v_add_u32_e32 v156, s73, v191
	ds_read_b128 v[128:131], v140
	ds_read_b128 v[132:135], v140 offset:1024
	ds_read_b128 v[136:139], v140 offset:2048
	ds_read_b128 v[140:143], v140 offset:3072
	ds_read_b128 v[144:147], v156
	ds_read_b128 v[148:151], v156 offset:1024
	ds_read_b128 v[152:155], v156 offset:2048
	ds_read_b128 v[156:159], v156 offset:3072
	s_add_u32 s34, s34, s42
	s_addc_u32 s35, s35, s43
	s_mov_b32 m0, s57
	v_lshl_add_u64 v[222:223], s[34:35], 0, v[178:179]
	ds_read_b128 v[160:163], v195 offset:32768
	ds_read_b128 v[164:167], v195 offset:33792
	ds_read_b128 v[168:171], v195 offset:34816
	ds_read_b128 v[172:175], v195 offset:35840
	ds_read_b128 v[186:189], v195 offset:36864
	ds_read_b128 v[196:199], v195 offset:37888
	ds_read_b128 v[200:203], v195 offset:38912
	ds_read_b128 v[204:207], v195 offset:39936
	global_load_lds_dwordx4 v[222:223], off
	v_lshl_add_u64 v[222:223], s[34:35], 0, v[176:177]
	s_mov_b32 m0, s59
	s_nop 0
	global_load_lds_dwordx4 v[222:223], off
	s_waitcnt vmcnt(8)
	s_waitcnt lgkmcnt(0)
	s_barrier
	s_setprio 1
	s_waitcnt lgkmcnt(0)
	v_mfma_f32_16x16x32_bf16 v[124:127], v[128:131], v[160:163], v[124:127]
	v_mfma_f32_16x16x32_bf16 v[120:123], v[136:139], v[160:163], v[120:123]
	v_mfma_f32_16x16x32_bf16 v[108:111], v[128:131], v[168:171], v[108:111]
	v_mfma_f32_16x16x32_bf16 v[104:107], v[136:139], v[168:171], v[104:107]
	v_mfma_f32_16x16x32_bf16 v[92:95], v[128:131], v[186:189], v[92:95]
	v_mfma_f32_16x16x32_bf16 v[88:91], v[136:139], v[186:189], v[88:91]
	v_mfma_f32_16x16x32_bf16 v[76:79], v[128:131], v[200:203], v[76:79]
	v_mfma_f32_16x16x32_bf16 v[72:75], v[136:139], v[200:203], v[72:75]
	v_mfma_f32_16x16x32_bf16 v[124:127], v[132:135], v[164:167], v[124:127]
	v_mfma_f32_16x16x32_bf16 v[120:123], v[140:143], v[164:167], v[120:123]
	v_mfma_f32_16x16x32_bf16 v[108:111], v[132:135], v[172:175], v[108:111]
	v_mfma_f32_16x16x32_bf16 v[104:107], v[140:143], v[172:175], v[104:107]
	v_mfma_f32_16x16x32_bf16 v[92:95], v[132:135], v[196:199], v[92:95]
	v_mfma_f32_16x16x32_bf16 v[88:91], v[140:143], v[196:199], v[88:91]
	v_mfma_f32_16x16x32_bf16 v[76:79], v[132:135], v[204:207], v[76:79]
	v_mfma_f32_16x16x32_bf16 v[72:75], v[140:143], v[204:207], v[72:75]
	s_setprio 0
	s_setprio 1
	v_mfma_f32_16x16x32_bf16 v[116:119], v[144:147], v[160:163], v[116:119]
	v_mfma_f32_16x16x32_bf16 v[112:115], v[152:155], v[160:163], v[112:115]
	v_mfma_f32_16x16x32_bf16 v[100:103], v[144:147], v[168:171], v[100:103]
	v_mfma_f32_16x16x32_bf16 v[96:99], v[152:155], v[168:171], v[96:99]
	v_mfma_f32_16x16x32_bf16 v[84:87], v[144:147], v[186:189], v[84:87]
	v_mfma_f32_16x16x32_bf16 v[80:83], v[152:155], v[186:189], v[80:83]
	v_mfma_f32_16x16x32_bf16 v[68:71], v[144:147], v[200:203], v[68:71]
	v_mfma_f32_16x16x32_bf16 v[64:67], v[152:155], v[200:203], v[64:67]
	v_mfma_f32_16x16x32_bf16 v[116:119], v[148:151], v[164:167], v[116:119]
	v_mfma_f32_16x16x32_bf16 v[112:115], v[156:159], v[164:167], v[112:115]
	v_mfma_f32_16x16x32_bf16 v[100:103], v[148:151], v[172:175], v[100:103]
	v_mfma_f32_16x16x32_bf16 v[96:99], v[156:159], v[172:175], v[96:99]
	v_mfma_f32_16x16x32_bf16 v[84:87], v[148:151], v[196:199], v[84:87]
	v_mfma_f32_16x16x32_bf16 v[80:83], v[156:159], v[196:199], v[80:83]
	v_mfma_f32_16x16x32_bf16 v[68:71], v[148:151], v[204:207], v[68:71]
	v_mfma_f32_16x16x32_bf16 v[64:67], v[156:159], v[204:207], v[64:67]
	s_setprio 0
	s_barrier
; #define PG8_STAGE(bufoff, gbase, voff) do { _Pragma("unroll") for (int _i = 0; _i < 2; ++_i) \
;         __builtin_amdgcn_global_load_lds((const unsigned*)((const char*)(gbase) + (voff)[_i]), (PG8_LAS unsigned*)(lds + (bufoff) + ldsw + _i * 8192), 16, 0, 0); } while (0)
; #define PG8_LDA(dst, b, h) do { _Pragma("unroll") for (int m = 0; m < 4; ++m) _Pragma("unroll") for (int k = 0; k < 2; ++k) dst[m][k] = *(const PG8_LAS bf16x8*)(lds + PG8_SA(b, h) + aoff + m * 2048 + k * 1024); } while (0)
; #define PG8_MMA(ai, bj, At, Bt) do { __builtin_amdgcn_s_setprio(1); _Pragma("unroll") for (int m = 0; m < 4; ++m) _Pragma("unroll") for (int n = 0; n < 2; ++n) _Pragma("unroll") for (int k = 0; k < 2; ++k) \
;         acc[ai][bj][m][n] = mma16<Epi::F16>(Bt[n][k], At[m][k], acc[ai][bj][m][n]); __builtin_amdgcn_s_setprio(0); } while (0)
; #define PG8_WAIT_V(n) asm volatile("s_waitcnt vmcnt(" #n ")" ::: "memory")
; #define PG8_WAIT_L(n) asm volatile("s_waitcnt lgkmcnt(" #n ")" ::: "memory")
; #define PG8_BAR __builtin_amdgcn_s_barrier()
; #define PG8_SCHED __builtin_amdgcn_sched_barrier(0)
; template <class Epi, class Sched, bool ALIGN_EPI = false, bool SP2 = false>
; __device__ __forceinline__ void gemm_phase(PG8_LAS unsigned char* lds, const Gemm g, const Sched& S, const Epi& E) {
;     ...
;         for (int t = 0; t < nt; t += 2) {
;             const bool last = (t == nt - 2);
;             const char* a1 = cA + (size_t)(t + 1) * kstep;
;             const char* a2 = last ? nA : cA + (size_t)(t + 2) * kstep; const char* b2 = last ? nB : cB + (size_t)(t + 2) * kstep;
;     ...
;             PG8_LDA(At, 1, 1); PG8_STAGE(PG8_SB(1, 0), b3, voffB); PG8_STAGE(PG8_SB(1, 1), b3 + hstep, voffB); PG8_STAGE(PG8_SA(1, 0), a3, voffA);
;             PG8_WAIT_V(8); PG8_WAIT_L(0); PG8_BAR; PG8_MMA(1, 0, At, B0); PG8_MMA(1, 1, At, B1); PG8_BAR; PG8_SCHED;
	s_add_i32 s34, s72, s3
	v_lshl_add_u64 v[192:193], v[192:193], 0, s[20:21]
	s_mov_b32 m0, s34
	ds_read_b128 v[160:163], v195 offset:49152
	ds_read_b128 v[164:167], v195 offset:50176
	ds_read_b128 v[168:171], v195 offset:51200
	ds_read_b128 v[172:175], v195 offset:52224
	ds_read_b128 v[186:189], v195 offset:53248
	ds_read_b128 v[196:199], v195 offset:54272
	ds_read_b128 v[200:203], v195 offset:55296
	ds_read_b128 v[204:207], v195 offset:56320
	global_load_lds_dwordx4 v[192:193], off
	v_lshl_add_u64 v[192:193], v[212:213], 0, s[20:21]
	s_add_i32 m0, s34, 0x2000
	s_add_i32 s34, s73, s3
	global_load_lds_dwordx4 v[192:193], off
	v_lshl_add_u64 v[192:193], v[214:215], 0, s[20:21]
	s_mov_b32 m0, s34
	s_nop 0
	global_load_lds_dwordx4 v[192:193], off
	v_lshl_add_u64 v[192:193], v[216:217], 0, s[20:21]
	s_add_i32 m0, s34, 0x2000
	s_nop 0
	global_load_lds_dwordx4 v[192:193], off
	v_lshl_add_u64 v[192:193], v[218:219], 0, s[20:21]
	s_mov_b32 m0, s63
	s_nop 0
	global_load_lds_dwordx4 v[192:193], off
	v_lshl_add_u64 v[192:193], v[220:221], 0, s[20:21]
	s_mov_b32 m0, s64
	s_nop 0
	global_load_lds_dwordx4 v[192:193], off
	s_waitcnt vmcnt(8)
	s_waitcnt lgkmcnt(0)
	s_barrier
	s_setprio 1
	s_waitcnt lgkmcnt(0)
	v_mfma_f32_16x16x32_bf16 v[60:63], v[128:131], v[160:163], v[60:63]
	v_mfma_f32_16x16x32_bf16 v[56:59], v[136:139], v[160:163], v[56:59]
	v_mfma_f32_16x16x32_bf16 v[44:47], v[128:131], v[168:171], v[44:47]
	v_mfma_f32_16x16x32_bf16 v[40:43], v[136:139], v[168:171], v[40:43]
	v_mfma_f32_16x16x32_bf16 v[28:31], v[128:131], v[186:189], v[28:31]
	v_mfma_f32_16x16x32_bf16 v[24:27], v[136:139], v[186:189], v[24:27]
	v_mfma_f32_16x16x32_bf16 v[12:15], v[128:131], v[200:203], v[12:15]
	v_mfma_f32_16x16x32_bf16 v[8:11], v[136:139], v[200:203], v[8:11]
	v_mfma_f32_16x16x32_bf16 v[60:63], v[132:135], v[164:167], v[60:63]
	v_mfma_f32_16x16x32_bf16 v[56:59], v[140:143], v[164:167], v[56:59]
	v_mfma_f32_16x16x32_bf16 v[44:47], v[132:135], v[172:175], v[44:47]
	v_mfma_f32_16x16x32_bf16 v[40:43], v[140:143], v[172:175], v[40:43]
	v_mfma_f32_16x16x32_bf16 v[28:31], v[132:135], v[196:199], v[28:31]
	v_mfma_f32_16x16x32_bf16 v[24:27], v[140:143], v[196:199], v[24:27]
	v_mfma_f32_16x16x32_bf16 v[12:15], v[132:135], v[204:207], v[12:15]
	v_mfma_f32_16x16x32_bf16 v[8:11], v[140:143], v[204:207], v[8:11]
	s_setprio 0
	s_setprio 1
	v_mfma_f32_16x16x32_bf16 v[52:55], v[144:147], v[160:163], v[52:55]
	v_mfma_f32_16x16x32_bf16 v[48:51], v[152:155], v[160:163], v[48:51]
	v_mfma_f32_16x16x32_bf16 v[36:39], v[144:147], v[168:171], v[36:39]
	v_mfma_f32_16x16x32_bf16 v[32:35], v[152:155], v[168:171], v[32:35]
	v_mfma_f32_16x16x32_bf16 v[20:23], v[144:147], v[186:189], v[20:23]
	v_mfma_f32_16x16x32_bf16 v[16:19], v[152:155], v[186:189], v[16:19]
	v_mfma_f32_16x16x32_bf16 v[4:7], v[144:147], v[200:203], v[4:7]
	v_mfma_f32_16x16x32_bf16 v[0:3], v[152:155], v[200:203], v[0:3]
	v_mfma_f32_16x16x32_bf16 v[52:55], v[148:151], v[164:167], v[52:55]
	v_mfma_f32_16x16x32_bf16 v[48:51], v[156:159], v[164:167], v[48:51]
	v_mfma_f32_16x16x32_bf16 v[36:39], v[148:151], v[172:175], v[36:39]
	v_mfma_f32_16x16x32_bf16 v[32:35], v[156:159], v[172:175], v[32:35]
	v_mfma_f32_16x16x32_bf16 v[20:23], v[148:151], v[196:199], v[20:23]
	v_mfma_f32_16x16x32_bf16 v[16:19], v[156:159], v[196:199], v[16:19]
	v_mfma_f32_16x16x32_bf16 v[4:7], v[148:151], v[204:207], v[4:7]
	v_mfma_f32_16x16x32_bf16 v[0:3], v[156:159], v[204:207], v[0:3]
	s_setprio 0
	s_barrier
	s_add_u32 s30, s30, 0x100
	s_addc_u32 s31, s31, 0
	s_add_u32 s69, s69, 0x100
	s_addc_u32 s70, s70, 0
	s_cmp_ge_i32 s71, s60
	s_mov_b32 s34, s71
	s_cbranch_scc0 .LBB0_1147
	s_branch .LBB0_1148

; #define PG8_STAGE(bufoff, gbase, voff) do { _Pragma("unroll") for (int _i = 0; _i < 2; ++_i) \
;         __builtin_amdgcn_global_load_lds((const unsigned*)((const char*)(gbase) + (voff)[_i]), (PG8_LAS unsigned*)(lds + (bufoff) + ldsw + _i * 8192), 16, 0, 0); } while (0)
; #define PG8_LDA(dst, b, h) do { _Pragma("unroll") for (int m = 0; m < 4; ++m) _Pragma("unroll") for (int k = 0; k < 2; ++k) dst[m][k] = *(const PG8_LAS bf16x8*)(lds + PG8_SA(b, h) + aoff + m * 2048 + k * 1024); } while (0)
; #define PG8_LDB(dst, b, h) do { _Pragma("unroll") for (int n = 0; n < 2; ++n) _Pragma("unroll") for (int k = 0; k < 2; ++k) dst[n][k] = *(const PG8_LAS bf16x8*)(lds + PG8_SB(b, h) + boff + n * 2048 + k * 1024); } while (0)
; #define PG8_MMA(ai, bj, At, Bt) do { __builtin_amdgcn_s_setprio(1); _Pragma("unroll") for (int m = 0; m < 4; ++m) _Pragma("unroll") for (int n = 0; n < 2; ++n) _Pragma("unroll") for (int k = 0; k < 2; ++k) \
;         acc[ai][bj][m][n] = mma16<Epi::F16>(Bt[n][k], At[m][k], acc[ai][bj][m][n]); __builtin_amdgcn_s_setprio(0); } while (0)
; #define PG8_WAIT_V(n) asm volatile("s_waitcnt vmcnt(" #n ")" ::: "memory")
; #define PG8_WAIT_L(n) asm volatile("s_waitcnt lgkmcnt(" #n ")" ::: "memory")
; template <class Epi, class Sched, bool ALIGN_EPI = false, bool SP2 = false>
; __device__ __forceinline__ void gemm_phase(PG8_LAS unsigned char* lds, const Gemm g, const Sched& S, const Epi& E) {
;     ...
;         for (int t = 0; t < nt; t += 2) {
;             const bool last = (t == nt - 2);
;             const char* a1 = cA + (size_t)(t + 1) * kstep;
;             const char* a2 = last ? nA : cA + (size_t)(t + 2) * kstep; const char* b2 = last ? nB : cB + (size_t)(t + 2) * kstep;
;             const char* a3 = a2 + kstep; const char* b3 = b2 + kstep;
;             if (last && has_next) S.a_ready(nxt);
;             if constexpr (SP2) {
;             PG8_LDB(B0, 0, 0); PG8_LDB(B1, 0, 1); PG8_SCHED; PG8_LDA(At, 0, 0); PG8_STAGE(PG8_SA(1, 1), a1 + hstep, voffA);
;             PG8_WAIT_V(8); PG8_WAIT_L(0); PG8_BAR; PG8_MMA(0, 0, At, B0); PG8_MMA(0, 1, At, B1); PG8_BAR; PG8_SCHED;
;     ...
; #pragma unroll
;         for (int a = 0; a < 2; ++a)
; #pragma unroll
;             for (int b = 0; b < 2; ++b)
; #pragma unroll
;                 for (int m = 0; m < 4; ++m)
; #pragma unroll
;                     for (int n = 0; n < 2; ++n) acc[a][b][m][n] = (f32x4){0.f, 0.f, 0.f, 0.f};
.LBB0_1168:
	s_andn2_b64 vcc, exec, s[52:53]
	s_cbranch_vccz .Lpeel_k8
	v_mov_b32_e32 v131, 0
	v_mov_b32_e32 v130, v131
	v_mov_b32_e32 v129, v131
	v_mov_b32_e32 v128, v131
	v_mov_b32_e32 v127, v131
	v_mov_b32_e32 v126, v131
	v_mov_b32_e32 v125, v131
	v_mov_b32_e32 v124, v131
	v_mov_b32_e32 v111, v131
	v_mov_b32_e32 v110, v131
	v_mov_b32_e32 v109, v131
	v_mov_b32_e32 v108, v131
	v_mov_b32_e32 v107, v131
	v_mov_b32_e32 v106, v131
	v_mov_b32_e32 v105, v131
	v_mov_b32_e32 v104, v131
	v_mov_b32_e32 v95, v131
	v_mov_b32_e32 v94, v131
	v_mov_b32_e32 v93, v131
	v_mov_b32_e32 v92, v131
	v_mov_b32_e32 v91, v131
	v_mov_b32_e32 v90, v131
	v_mov_b32_e32 v89, v131
	v_mov_b32_e32 v88, v131
	v_mov_b32_e32 v79, v131
	v_mov_b32_e32 v78, v131
	v_mov_b32_e32 v77, v131
	v_mov_b32_e32 v76, v131
	v_mov_b32_e32 v75, v131
	v_mov_b32_e32 v74, v131
	v_mov_b32_e32 v73, v131
	v_mov_b32_e32 v72, v131
	v_mov_b32_e32 v119, v131
	v_mov_b32_e32 v118, v131
	v_mov_b32_e32 v117, v131
	v_mov_b32_e32 v116, v131
	v_mov_b32_e32 v115, v131
	v_mov_b32_e32 v114, v131
	v_mov_b32_e32 v113, v131
	v_mov_b32_e32 v112, v131
	v_mov_b32_e32 v103, v131
	v_mov_b32_e32 v102, v131
	v_mov_b32_e32 v101, v131
	v_mov_b32_e32 v100, v131
	v_mov_b32_e32 v99, v131
	v_mov_b32_e32 v98, v131
	v_mov_b32_e32 v97, v131
	v_mov_b32_e32 v96, v131
	v_mov_b32_e32 v87, v131
	v_mov_b32_e32 v86, v131
	v_mov_b32_e32 v85, v131
	v_mov_b32_e32 v84, v131
	v_mov_b32_e32 v83, v131
	v_mov_b32_e32 v82, v131
	v_mov_b32_e32 v81, v131
	v_mov_b32_e32 v80, v131
	v_mov_b32_e32 v71, v131
	v_mov_b32_e32 v70, v131
	v_mov_b32_e32 v69, v131
	v_mov_b32_e32 v68, v131
	v_mov_b32_e32 v67, v131
	v_mov_b32_e32 v66, v131
	v_mov_b32_e32 v65, v131
	v_mov_b32_e32 v64, v131
	v_mov_b32_e32 v63, v131
	v_mov_b32_e32 v62, v131
	v_mov_b32_e32 v61, v131
	v_mov_b32_e32 v60, v131
	v_mov_b32_e32 v59, v131
	v_mov_b32_e32 v58, v131
	v_mov_b32_e32 v57, v131
	v_mov_b32_e32 v56, v131
	v_mov_b32_e32 v47, v131
	v_mov_b32_e32 v46, v131
	v_mov_b32_e32 v45, v131
	v_mov_b32_e32 v44, v131
	v_mov_b32_e32 v43, v131
	v_mov_b32_e32 v42, v131
	v_mov_b32_e32 v41, v131
	v_mov_b32_e32 v40, v131
	v_mov_b32_e32 v31, v131
	v_mov_b32_e32 v30, v131
	v_mov_b32_e32 v29, v131
	v_mov_b32_e32 v28, v131
	v_mov_b32_e32 v27, v131
	v_mov_b32_e32 v26, v131
	v_mov_b32_e32 v25, v131
	v_mov_b32_e32 v24, v131
	v_mov_b32_e32 v15, v131
	v_mov_b32_e32 v14, v131
	v_mov_b32_e32 v13, v131
	v_mov_b32_e32 v12, v131
	v_mov_b32_e32 v11, v131
	v_mov_b32_e32 v10, v131
	v_mov_b32_e32 v9, v131
	v_mov_b32_e32 v8, v131
	v_mov_b32_e32 v55, v131
	v_mov_b32_e32 v54, v131
	v_mov_b32_e32 v53, v131
	v_mov_b32_e32 v52, v131
	v_mov_b32_e32 v51, v131
	v_mov_b32_e32 v50, v131
	v_mov_b32_e32 v49, v131
	v_mov_b32_e32 v48, v131
	v_mov_b32_e32 v39, v131
	v_mov_b32_e32 v38, v131
	v_mov_b32_e32 v37, v131
	v_mov_b32_e32 v36, v131
	v_mov_b32_e32 v35, v131
	v_mov_b32_e32 v34, v131
	v_mov_b32_e32 v33, v131
	v_mov_b32_e32 v32, v131
	v_mov_b32_e32 v23, v131
	v_mov_b32_e32 v22, v131
	v_mov_b32_e32 v21, v131
	v_mov_b32_e32 v20, v131
	v_mov_b32_e32 v19, v131
	v_mov_b32_e32 v18, v131
	v_mov_b32_e32 v17, v131
	v_mov_b32_e32 v16, v131
	v_mov_b32_e32 v7, v131
	v_mov_b32_e32 v6, v131
	v_mov_b32_e32 v5, v131
	v_mov_b32_e32 v4, v131
	v_mov_b32_e32 v3, v131
	v_mov_b32_e32 v2, v131
	v_mov_b32_e32 v1, v131
	v_mov_b32_e32 v0, v131
	s_branch .LBB0_1171
.Lpeel_k8:
	s_add_u32 s30, s30, 0x80
	s_addc_u32 s31, s31, 0
	s_add_u32 s40, s34, 0x100
	s_addc_u32 s41, s35, 0
	s_mov_b32 s34, 0
	s_add_i32 s71, s34, 2
	s_add_u32 s72, s30, 0x80
	s_addc_u32 s35, s31, 0
	s_add_i32 s77, 0, 0x10000
	s_cmp_eq_u32 s62, s34
	s_cselect_b32 s35, s1, s35
	s_cselect_b32 s34, s0, s72
	s_cselect_b32 s73, s29, s41
	s_cselect_b32 s72, s28, s40
	s_add_i32 s82, 0, 0x14000
	v_add_u32_e32 v140, s77, v190
	v_add_u32_e32 v156, s82, v190
	ds_read_b128 v[120:123], v140
	ds_read_b128 v[132:135], v140 offset:1024
	ds_read_b128 v[136:139], v140 offset:2048
	ds_read_b128 v[140:143], v140 offset:3072
	ds_read_b128 v[144:147], v156
	ds_read_b128 v[148:151], v156 offset:1024
	ds_read_b128 v[152:155], v156 offset:2048
	ds_read_b128 v[156:159], v156 offset:3072
	v_lshl_add_u64 v[204:205], s[30:31], 0, v[166:167]
	s_add_i32 m0, s8, 0xc000
	ds_read_b128 v[170:173], v191
	ds_read_b128 v[174:177], v191 offset:1024
	ds_read_b128 v[178:181], v191 offset:2048
	ds_read_b128 v[182:185], v191 offset:3072
	ds_read_b128 v[186:189], v191 offset:4096
	ds_read_b128 v[192:195], v191 offset:5120
	ds_read_b128 v[196:199], v191 offset:6144
	ds_read_b128 v[200:203], v191 offset:7168
	global_load_lds_dwordx4 v[204:205], off
	v_lshl_add_u64 v[204:205], s[30:31], 0, v[168:169]
	s_add_i32 m0, s8, 0xe000
	s_nop 0
	global_load_lds_dwordx4 v[204:205], off
	s_waitcnt vmcnt(8)
	s_waitcnt lgkmcnt(0)
	s_barrier
; #define PG8_STAGE(bufoff, gbase, voff) do { _Pragma("unroll") for (int _i = 0; _i < 2; ++_i) \
;         __builtin_amdgcn_global_load_lds((const unsigned*)((const char*)(gbase) + (voff)[_i]), (PG8_LAS unsigned*)(lds + (bufoff) + ldsw + _i * 8192), 16, 0, 0); } while (0)
; #define PG8_LDA(dst, b, h) do { _Pragma("unroll") for (int m = 0; m < 4; ++m) _Pragma("unroll") for (int k = 0; k < 2; ++k) dst[m][k] = *(const PG8_LAS bf16x8*)(lds + PG8_SA(b, h) + aoff + m * 2048 + k * 1024); } while (0)
; #define PG8_MMA(ai, bj, At, Bt) do { __builtin_amdgcn_s_setprio(1); _Pragma("unroll") for (int m = 0; m < 4; ++m) _Pragma("unroll") for (int n = 0; n < 2; ++n) _Pragma("unroll") for (int k = 0; k < 2; ++k) \
;         acc[ai][bj][m][n] = mma16<Epi::F16>(Bt[n][k], At[m][k], acc[ai][bj][m][n]); __builtin_amdgcn_s_setprio(0); } while (0)
; #define PG8_WAIT_V(n) asm volatile("s_waitcnt vmcnt(" #n ")" ::: "memory")
; #define PG8_WAIT_L(n) asm volatile("s_waitcnt lgkmcnt(" #n ")" ::: "memory")
; #define PG8_BAR __builtin_amdgcn_s_barrier()
; #define PG8_SCHED __builtin_amdgcn_sched_barrier(0)
; template <class Epi, class Sched, bool ALIGN_EPI = false, bool SP2 = false>
; __device__ __forceinline__ void gemm_phase(PG8_LAS unsigned char* lds, const Gemm g, const Sched& S, const Epi& E) {
;     ...
;             PG8_WAIT_V(8); PG8_WAIT_L(0); PG8_BAR; PG8_MMA(0, 0, At, B0); PG8_MMA(0, 1, At, B1); PG8_BAR; PG8_SCHED;
;             PG8_LDA(At, 0, 1); PG8_STAGE(PG8_SB(0, 0), b2, voffB); PG8_STAGE(PG8_SB(0, 1), b2 + hstep, voffB); PG8_STAGE(PG8_SA(0, 0), a2, voffA);
;             PG8_WAIT_V(8); PG8_WAIT_L(0); PG8_BAR; PG8_MMA(1, 0, At, B0); PG8_MMA(1, 1, At, B1); PG8_BAR; PG8_SCHED;
	s_setprio 1
	s_waitcnt lgkmcnt(0)
	v_mfma_f32_16x16x32_bf16 v[128:131], v[120:123], v[170:173], 0
	v_mfma_f32_16x16x32_bf16 v[124:127], v[136:139], v[170:173], 0
	v_mfma_f32_16x16x32_bf16 v[108:111], v[120:123], v[178:181], 0
	v_mfma_f32_16x16x32_bf16 v[104:107], v[136:139], v[178:181], 0
	v_mfma_f32_16x16x32_bf16 v[92:95], v[120:123], v[186:189], 0
	v_mfma_f32_16x16x32_bf16 v[88:91], v[136:139], v[186:189], 0
	v_mfma_f32_16x16x32_bf16 v[76:79], v[120:123], v[196:199], 0
	v_mfma_f32_16x16x32_bf16 v[72:75], v[136:139], v[196:199], 0
	v_mfma_f32_16x16x32_bf16 v[128:131], v[132:135], v[174:177], v[128:131]
	v_mfma_f32_16x16x32_bf16 v[124:127], v[140:143], v[174:177], v[124:127]
	v_mfma_f32_16x16x32_bf16 v[108:111], v[132:135], v[182:185], v[108:111]
	v_mfma_f32_16x16x32_bf16 v[104:107], v[140:143], v[182:185], v[104:107]
	v_mfma_f32_16x16x32_bf16 v[92:95], v[132:135], v[192:195], v[92:95]
	v_mfma_f32_16x16x32_bf16 v[88:91], v[140:143], v[192:195], v[88:91]
	v_mfma_f32_16x16x32_bf16 v[76:79], v[132:135], v[200:203], v[76:79]
	v_mfma_f32_16x16x32_bf16 v[72:75], v[140:143], v[200:203], v[72:75]
	s_setprio 0
	s_setprio 1
	v_mfma_f32_16x16x32_bf16 v[116:119], v[144:147], v[170:173], 0
	v_mfma_f32_16x16x32_bf16 v[112:115], v[152:155], v[170:173], 0
	v_mfma_f32_16x16x32_bf16 v[100:103], v[144:147], v[178:181], 0
	v_mfma_f32_16x16x32_bf16 v[96:99], v[152:155], v[178:181], 0
	v_mfma_f32_16x16x32_bf16 v[84:87], v[144:147], v[186:189], 0
	v_mfma_f32_16x16x32_bf16 v[80:83], v[152:155], v[186:189], 0
	v_mfma_f32_16x16x32_bf16 v[68:71], v[144:147], v[196:199], 0
	v_mfma_f32_16x16x32_bf16 v[64:67], v[152:155], v[196:199], 0
	v_mfma_f32_16x16x32_bf16 v[116:119], v[148:151], v[174:177], v[116:119]
	v_mfma_f32_16x16x32_bf16 v[112:115], v[156:159], v[174:177], v[112:115]
	v_mfma_f32_16x16x32_bf16 v[100:103], v[148:151], v[182:185], v[100:103]
	v_mfma_f32_16x16x32_bf16 v[96:99], v[156:159], v[182:185], v[96:99]
	v_mfma_f32_16x16x32_bf16 v[84:87], v[148:151], v[192:195], v[84:87]
	v_mfma_f32_16x16x32_bf16 v[80:83], v[156:159], v[192:195], v[80:83]
	v_mfma_f32_16x16x32_bf16 v[68:71], v[148:151], v[200:203], v[68:71]
	v_mfma_f32_16x16x32_bf16 v[64:67], v[156:159], v[200:203], v[64:67]
	s_setprio 0
	s_barrier
	s_add_i32 s77, s77, s3
	v_lshl_add_u64 v[204:205], s[72:73], 0, v[160:161]
	s_mov_b32 m0, s77
	ds_read_b128 v[170:173], v191 offset:16384
	ds_read_b128 v[174:177], v191 offset:17408
	ds_read_b128 v[178:181], v191 offset:18432
	ds_read_b128 v[182:185], v191 offset:19456
	ds_read_b128 v[186:189], v191 offset:20480
	ds_read_b128 v[192:195], v191 offset:21504
	ds_read_b128 v[196:199], v191 offset:22528
	ds_read_b128 v[200:203], v191 offset:23552
	global_load_lds_dwordx4 v[204:205], off
	s_add_i32 m0, s77, 0x2000
	v_lshl_add_u64 v[206:207], s[72:73], 0, v[162:163]
	s_add_u32 s72, s72, s42
	s_addc_u32 s73, s73, s43
	s_add_i32 s77, s82, s3
	global_load_lds_dwordx4 v[206:207], off
	v_lshl_add_u64 v[212:213], s[72:73], 0, v[160:161]
	s_mov_b32 m0, s77
	v_lshl_add_u64 v[214:215], s[72:73], 0, v[162:163]
	global_load_lds_dwordx4 v[212:213], off
	s_add_i32 m0, s77, 0x2000
	v_lshl_add_u64 v[216:217], s[34:35], 0, v[160:161]
	global_load_lds_dwordx4 v[214:215], off
	s_mov_b32 m0, s8
	v_lshl_add_u64 v[218:219], s[34:35], 0, v[162:163]
	global_load_lds_dwordx4 v[216:217], off
	s_mov_b32 m0, s9
	s_nop 0
	global_load_lds_dwordx4 v[218:219], off
	s_waitcnt vmcnt(8)
	s_waitcnt lgkmcnt(0)
	s_barrier
	s_setprio 1
	s_waitcnt lgkmcnt(0)
	v_mfma_f32_16x16x32_bf16 v[60:63], v[120:123], v[170:173], 0
	v_mfma_f32_16x16x32_bf16 v[56:59], v[136:139], v[170:173], 0
	v_mfma_f32_16x16x32_bf16 v[44:47], v[120:123], v[178:181], 0
	v_mfma_f32_16x16x32_bf16 v[40:43], v[136:139], v[178:181], 0
	v_mfma_f32_16x16x32_bf16 v[28:31], v[120:123], v[186:189], 0
	v_mfma_f32_16x16x32_bf16 v[24:27], v[136:139], v[186:189], 0
	v_mfma_f32_16x16x32_bf16 v[12:15], v[120:123], v[196:199], 0
	v_mfma_f32_16x16x32_bf16 v[8:11], v[136:139], v[196:199], 0
	v_mfma_f32_16x16x32_bf16 v[60:63], v[132:135], v[174:177], v[60:63]
	v_mfma_f32_16x16x32_bf16 v[56:59], v[140:143], v[174:177], v[56:59]
	v_mfma_f32_16x16x32_bf16 v[44:47], v[132:135], v[182:185], v[44:47]
	v_mfma_f32_16x16x32_bf16 v[40:43], v[140:143], v[182:185], v[40:43]
	v_mfma_f32_16x16x32_bf16 v[28:31], v[132:135], v[192:195], v[28:31]
	v_mfma_f32_16x16x32_bf16 v[24:27], v[140:143], v[192:195], v[24:27]
	v_mfma_f32_16x16x32_bf16 v[12:15], v[132:135], v[200:203], v[12:15]
	v_mfma_f32_16x16x32_bf16 v[8:11], v[140:143], v[200:203], v[8:11]
	s_setprio 0
	s_setprio 1
	v_mfma_f32_16x16x32_bf16 v[52:55], v[144:147], v[170:173], 0
	v_mfma_f32_16x16x32_bf16 v[48:51], v[152:155], v[170:173], 0
	v_mfma_f32_16x16x32_bf16 v[36:39], v[144:147], v[178:181], 0
	v_mfma_f32_16x16x32_bf16 v[32:35], v[152:155], v[178:181], 0
	v_mfma_f32_16x16x32_bf16 v[20:23], v[144:147], v[186:189], 0
	v_mfma_f32_16x16x32_bf16 v[16:19], v[152:155], v[186:189], 0
	v_mfma_f32_16x16x32_bf16 v[4:7], v[144:147], v[196:199], 0
	v_mfma_f32_16x16x32_bf16 v[0:3], v[152:155], v[196:199], 0
	v_mfma_f32_16x16x32_bf16 v[52:55], v[148:151], v[174:177], v[52:55]
	v_mfma_f32_16x16x32_bf16 v[48:51], v[156:159], v[174:177], v[48:51]
	v_mfma_f32_16x16x32_bf16 v[36:39], v[148:151], v[182:185], v[36:39]
	v_mfma_f32_16x16x32_bf16 v[32:35], v[156:159], v[182:185], v[32:35]
	v_mfma_f32_16x16x32_bf16 v[20:23], v[148:151], v[192:195], v[20:23]
	v_mfma_f32_16x16x32_bf16 v[16:19], v[156:159], v[192:195], v[16:19]
	v_mfma_f32_16x16x32_bf16 v[4:7], v[148:151], v[200:203], v[4:7]
	v_mfma_f32_16x16x32_bf16 v[0:3], v[156:159], v[200:203], v[0:3]
	s_setprio 0
	s_barrier
; #define PG8_STAGE(bufoff, gbase, voff) do { _Pragma("unroll") for (int _i = 0; _i < 2; ++_i) \
;         __builtin_amdgcn_global_load_lds((const unsigned*)((const char*)(gbase) + (voff)[_i]), (PG8_LAS unsigned*)(lds + (bufoff) + ldsw + _i * 8192), 16, 0, 0); } while (0)
; #define PG8_LDA(dst, b, h) do { _Pragma("unroll") for (int m = 0; m < 4; ++m) _Pragma("unroll") for (int k = 0; k < 2; ++k) dst[m][k] = *(const PG8_LAS bf16x8*)(lds + PG8_SA(b, h) + aoff + m * 2048 + k * 1024); } while (0)
; #define PG8_LDB(dst, b, h) do { _Pragma("unroll") for (int n = 0; n < 2; ++n) _Pragma("unroll") for (int k = 0; k < 2; ++k) dst[n][k] = *(const PG8_LAS bf16x8*)(lds + PG8_SB(b, h) + boff + n * 2048 + k * 1024); } while (0)
; #define PG8_MMA(ai, bj, At, Bt) do { __builtin_amdgcn_s_setprio(1); _Pragma("unroll") for (int m = 0; m < 4; ++m) _Pragma("unroll") for (int n = 0; n < 2; ++n) _Pragma("unroll") for (int k = 0; k < 2; ++k) \
;         acc[ai][bj][m][n] = mma16<Epi::F16>(Bt[n][k], At[m][k], acc[ai][bj][m][n]); __builtin_amdgcn_s_setprio(0); } while (0)
; #define PG8_WAIT_V(n) asm volatile("s_waitcnt vmcnt(" #n ")" ::: "memory")
; #define PG8_WAIT_L(n) asm volatile("s_waitcnt lgkmcnt(" #n ")" ::: "memory")
; #define PG8_BAR __builtin_amdgcn_s_barrier()
; #define PG8_SCHED __builtin_amdgcn_sched_barrier(0)
; template <class Epi, class Sched, bool ALIGN_EPI = false, bool SP2 = false>
; __device__ __forceinline__ void gemm_phase(PG8_LAS unsigned char* lds, const Gemm g, const Sched& S, const Epi& E) {
;     ...
;             PG8_LDB(B0, 1, 0); PG8_LDB(B1, 1, 1); PG8_SCHED; PG8_LDA(At, 1, 0); PG8_STAGE(PG8_SA(0, 1), a2 + hstep, voffA);
;             PG8_WAIT_V(8); PG8_WAIT_L(0); PG8_BAR; PG8_MMA(0, 0, At, B0); PG8_MMA(0, 1, At, B1); PG8_BAR; PG8_SCHED;
	s_add_i32 s72, 0, 0x18000
	s_add_i32 s73, 0, 0x1c000
	v_add_u32_e32 v140, s72, v190
	v_add_u32_e32 v156, s73, v190
	ds_read_b128 v[120:123], v140
	ds_read_b128 v[132:135], v140 offset:1024
	ds_read_b128 v[136:139], v140 offset:2048
	ds_read_b128 v[140:143], v140 offset:3072
	ds_read_b128 v[144:147], v156
	ds_read_b128 v[148:151], v156 offset:1024
	ds_read_b128 v[152:155], v156 offset:2048
	ds_read_b128 v[156:159], v156 offset:3072
	s_add_u32 s34, s34, s42
	s_addc_u32 s35, s35, s43
	s_mov_b32 m0, s11
	v_lshl_add_u64 v[220:221], s[34:35], 0, v[160:161]
	ds_read_b128 v[170:173], v191 offset:32768
	ds_read_b128 v[174:177], v191 offset:33792
	ds_read_b128 v[178:181], v191 offset:34816
	ds_read_b128 v[182:185], v191 offset:35840
	ds_read_b128 v[186:189], v191 offset:36864
	ds_read_b128 v[192:195], v191 offset:37888
	ds_read_b128 v[196:199], v191 offset:38912
	ds_read_b128 v[200:203], v191 offset:39936
	global_load_lds_dwordx4 v[220:221], off
	v_lshl_add_u64 v[220:221], s[34:35], 0, v[162:163]
	s_mov_b32 m0, s36
	s_nop 0
	global_load_lds_dwordx4 v[220:221], off
	s_waitcnt vmcnt(8)
	s_waitcnt lgkmcnt(0)
	s_barrier
	s_setprio 1
	s_waitcnt lgkmcnt(0)
	v_mfma_f32_16x16x32_bf16 v[128:131], v[120:123], v[170:173], v[128:131]
	v_mfma_f32_16x16x32_bf16 v[124:127], v[136:139], v[170:173], v[124:127]
	v_mfma_f32_16x16x32_bf16 v[108:111], v[120:123], v[178:181], v[108:111]
	v_mfma_f32_16x16x32_bf16 v[104:107], v[136:139], v[178:181], v[104:107]
	v_mfma_f32_16x16x32_bf16 v[92:95], v[120:123], v[186:189], v[92:95]
	v_mfma_f32_16x16x32_bf16 v[88:91], v[136:139], v[186:189], v[88:91]
	v_mfma_f32_16x16x32_bf16 v[76:79], v[120:123], v[196:199], v[76:79]
	v_mfma_f32_16x16x32_bf16 v[72:75], v[136:139], v[196:199], v[72:75]
	v_mfma_f32_16x16x32_bf16 v[128:131], v[132:135], v[174:177], v[128:131]
	v_mfma_f32_16x16x32_bf16 v[124:127], v[140:143], v[174:177], v[124:127]
	v_mfma_f32_16x16x32_bf16 v[108:111], v[132:135], v[182:185], v[108:111]
	v_mfma_f32_16x16x32_bf16 v[104:107], v[140:143], v[182:185], v[104:107]
	v_mfma_f32_16x16x32_bf16 v[92:95], v[132:135], v[192:195], v[92:95]
	v_mfma_f32_16x16x32_bf16 v[88:91], v[140:143], v[192:195], v[88:91]
	v_mfma_f32_16x16x32_bf16 v[76:79], v[132:135], v[200:203], v[76:79]
	v_mfma_f32_16x16x32_bf16 v[72:75], v[140:143], v[200:203], v[72:75]
	s_setprio 0
	s_setprio 1
	v_mfma_f32_16x16x32_bf16 v[116:119], v[144:147], v[170:173], v[116:119]
	v_mfma_f32_16x16x32_bf16 v[112:115], v[152:155], v[170:173], v[112:115]
	v_mfma_f32_16x16x32_bf16 v[100:103], v[144:147], v[178:181], v[100:103]
	v_mfma_f32_16x16x32_bf16 v[96:99], v[152:155], v[178:181], v[96:99]
	v_mfma_f32_16x16x32_bf16 v[84:87], v[144:147], v[186:189], v[84:87]
	v_mfma_f32_16x16x32_bf16 v[80:83], v[152:155], v[186:189], v[80:83]
	v_mfma_f32_16x16x32_bf16 v[68:71], v[144:147], v[196:199], v[68:71]
	v_mfma_f32_16x16x32_bf16 v[64:67], v[152:155], v[196:199], v[64:67]
	v_mfma_f32_16x16x32_bf16 v[116:119], v[148:151], v[174:177], v[116:119]
	v_mfma_f32_16x16x32_bf16 v[112:115], v[156:159], v[174:177], v[112:115]
	v_mfma_f32_16x16x32_bf16 v[100:103], v[148:151], v[182:185], v[100:103]
	v_mfma_f32_16x16x32_bf16 v[96:99], v[156:159], v[182:185], v[96:99]
	v_mfma_f32_16x16x32_bf16 v[84:87], v[148:151], v[192:195], v[84:87]
	v_mfma_f32_16x16x32_bf16 v[80:83], v[156:159], v[192:195], v[80:83]
	v_mfma_f32_16x16x32_bf16 v[68:71], v[148:151], v[200:203], v[68:71]
	v_mfma_f32_16x16x32_bf16 v[64:67], v[156:159], v[200:203], v[64:67]
	s_setprio 0
	s_barrier
; #define PG8_STAGE(bufoff, gbase, voff) do { _Pragma("unroll") for (int _i = 0; _i < 2; ++_i) \
;         __builtin_amdgcn_global_load_lds((const unsigned*)((const char*)(gbase) + (voff)[_i]), (PG8_LAS unsigned*)(lds + (bufoff) + ldsw + _i * 8192), 16, 0, 0); } while (0)
; #define PG8_LDA(dst, b, h) do { _Pragma("unroll") for (int m = 0; m < 4; ++m) _Pragma("unroll") for (int k = 0; k < 2; ++k) dst[m][k] = *(const PG8_LAS bf16x8*)(lds + PG8_SA(b, h) + aoff + m * 2048 + k * 1024); } while (0)
; #define PG8_MMA(ai, bj, At, Bt) do { __builtin_amdgcn_s_setprio(1); _Pragma("unroll") for (int m = 0; m < 4; ++m) _Pragma("unroll") for (int n = 0; n < 2; ++n) _Pragma("unroll") for (int k = 0; k < 2; ++k) \
;         acc[ai][bj][m][n] = mma16<Epi::F16>(Bt[n][k], At[m][k], acc[ai][bj][m][n]); __builtin_amdgcn_s_setprio(0); } while (0)
; #define PG8_WAIT_V(n) asm volatile("s_waitcnt vmcnt(" #n ")" ::: "memory")
; #define PG8_WAIT_L(n) asm volatile("s_waitcnt lgkmcnt(" #n ")" ::: "memory")
; #define PG8_BAR __builtin_amdgcn_s_barrier()
; #define PG8_SCHED __builtin_amdgcn_sched_barrier(0)
; template <class Epi, class Sched, bool ALIGN_EPI = false, bool SP2 = false>
; __device__ __forceinline__ void gemm_phase(PG8_LAS unsigned char* lds, const Gemm g, const Sched& S, const Epi& E) {
;     ...
;         for (int t = 0; t < nt; t += 2) {
;             const bool last = (t == nt - 2);
;             const char* a1 = cA + (size_t)(t + 1) * kstep;
;             const char* a2 = last ? nA : cA + (size_t)(t + 2) * kstep; const char* b2 = last ? nB : cB + (size_t)(t + 2) * kstep;
;     ...
;             PG8_LDA(At, 1, 1); PG8_STAGE(PG8_SB(1, 0), b3, voffB); PG8_STAGE(PG8_SB(1, 1), b3 + hstep, voffB); PG8_STAGE(PG8_SA(1, 0), a3, voffA);
;             PG8_WAIT_V(8); PG8_WAIT_L(0); PG8_BAR; PG8_MMA(1, 0, At, B0); PG8_MMA(1, 1, At, B1); PG8_BAR; PG8_SCHED;
	s_add_i32 s34, s72, s3
	v_lshl_add_u64 v[204:205], v[204:205], 0, s[20:21]
	s_mov_b32 m0, s34
	ds_read_b128 v[170:173], v191 offset:49152
	ds_read_b128 v[174:177], v191 offset:50176
	ds_read_b128 v[178:181], v191 offset:51200
	ds_read_b128 v[182:185], v191 offset:52224
	ds_read_b128 v[186:189], v191 offset:53248
	ds_read_b128 v[192:195], v191 offset:54272
	ds_read_b128 v[196:199], v191 offset:55296
	ds_read_b128 v[200:203], v191 offset:56320
	global_load_lds_dwordx4 v[204:205], off
	v_lshl_add_u64 v[204:205], v[206:207], 0, s[20:21]
	s_add_i32 m0, s34, 0x2000
	s_add_i32 s34, s73, s3
	global_load_lds_dwordx4 v[204:205], off
	v_lshl_add_u64 v[204:205], v[212:213], 0, s[20:21]
	s_mov_b32 m0, s34
	s_nop 0
	global_load_lds_dwordx4 v[204:205], off
	v_lshl_add_u64 v[204:205], v[214:215], 0, s[20:21]
	s_add_i32 m0, s34, 0x2000
	s_nop 0
	global_load_lds_dwordx4 v[204:205], off
	v_lshl_add_u64 v[204:205], v[216:217], 0, s[20:21]
	s_mov_b32 m0, s60
	s_nop 0
	global_load_lds_dwordx4 v[204:205], off
	v_lshl_add_u64 v[204:205], v[218:219], 0, s[20:21]
	s_mov_b32 m0, s61
	s_nop 0
	global_load_lds_dwordx4 v[204:205], off
	s_waitcnt vmcnt(8)
	s_waitcnt lgkmcnt(0)
	s_barrier
	s_setprio 1
	s_waitcnt lgkmcnt(0)
	v_mfma_f32_16x16x32_bf16 v[60:63], v[120:123], v[170:173], v[60:63]
	v_mfma_f32_16x16x32_bf16 v[56:59], v[136:139], v[170:173], v[56:59]
	v_mfma_f32_16x16x32_bf16 v[44:47], v[120:123], v[178:181], v[44:47]
	v_mfma_f32_16x16x32_bf16 v[40:43], v[136:139], v[178:181], v[40:43]
	v_mfma_f32_16x16x32_bf16 v[28:31], v[120:123], v[186:189], v[28:31]
	v_mfma_f32_16x16x32_bf16 v[24:27], v[136:139], v[186:189], v[24:27]
	v_mfma_f32_16x16x32_bf16 v[12:15], v[120:123], v[196:199], v[12:15]
	v_mfma_f32_16x16x32_bf16 v[8:11], v[136:139], v[196:199], v[8:11]
	v_mfma_f32_16x16x32_bf16 v[60:63], v[132:135], v[174:177], v[60:63]
	v_mfma_f32_16x16x32_bf16 v[56:59], v[140:143], v[174:177], v[56:59]
	v_mfma_f32_16x16x32_bf16 v[44:47], v[132:135], v[182:185], v[44:47]
	v_mfma_f32_16x16x32_bf16 v[40:43], v[140:143], v[182:185], v[40:43]
	v_mfma_f32_16x16x32_bf16 v[28:31], v[132:135], v[192:195], v[28:31]
	v_mfma_f32_16x16x32_bf16 v[24:27], v[140:143], v[192:195], v[24:27]
	v_mfma_f32_16x16x32_bf16 v[12:15], v[132:135], v[200:203], v[12:15]
	v_mfma_f32_16x16x32_bf16 v[8:11], v[140:143], v[200:203], v[8:11]
	s_setprio 0
	s_setprio 1
	v_mfma_f32_16x16x32_bf16 v[52:55], v[144:147], v[170:173], v[52:55]
	v_mfma_f32_16x16x32_bf16 v[48:51], v[152:155], v[170:173], v[48:51]
	v_mfma_f32_16x16x32_bf16 v[36:39], v[144:147], v[178:181], v[36:39]
	v_mfma_f32_16x16x32_bf16 v[32:35], v[152:155], v[178:181], v[32:35]
	v_mfma_f32_16x16x32_bf16 v[20:23], v[144:147], v[186:189], v[20:23]
	v_mfma_f32_16x16x32_bf16 v[16:19], v[152:155], v[186:189], v[16:19]
	v_mfma_f32_16x16x32_bf16 v[4:7], v[144:147], v[196:199], v[4:7]
	v_mfma_f32_16x16x32_bf16 v[0:3], v[152:155], v[196:199], v[0:3]
	v_mfma_f32_16x16x32_bf16 v[52:55], v[148:151], v[174:177], v[52:55]
	v_mfma_f32_16x16x32_bf16 v[48:51], v[156:159], v[174:177], v[48:51]
	v_mfma_f32_16x16x32_bf16 v[36:39], v[148:151], v[182:185], v[36:39]
	v_mfma_f32_16x16x32_bf16 v[32:35], v[156:159], v[182:185], v[32:35]
	v_mfma_f32_16x16x32_bf16 v[20:23], v[148:151], v[192:195], v[20:23]
	v_mfma_f32_16x16x32_bf16 v[16:19], v[156:159], v[192:195], v[16:19]
	v_mfma_f32_16x16x32_bf16 v[4:7], v[148:151], v[200:203], v[4:7]
	v_mfma_f32_16x16x32_bf16 v[0:3], v[156:159], v[200:203], v[0:3]
	s_setprio 0
	s_barrier
	s_add_u32 s30, s30, 0x100
	s_addc_u32 s31, s31, 0
	s_add_u32 s40, s40, 0x100
	s_addc_u32 s41, s41, 0
	s_cmp_ge_i32 s71, s48
	s_mov_b32 s34, s71
	s_cbranch_scc0 .LBB0_1170
	s_branch .LBB0_1171

; #define PG8_STAGE(bufoff, gbase, voff) do { _Pragma("unroll") for (int _i = 0; _i < 2; ++_i) \
;         __builtin_amdgcn_global_load_lds((const unsigned*)((const char*)(gbase) + (voff)[_i]), (PG8_LAS unsigned*)(lds + (bufoff) + ldsw + _i * 8192), 16, 0, 0); } while (0)
; #define PG8_LDA(dst, b, h) do { _Pragma("unroll") for (int m = 0; m < 4; ++m) _Pragma("unroll") for (int k = 0; k < 2; ++k) dst[m][k] = *(const PG8_LAS bf16x8*)(lds + PG8_SA(b, h) + aoff + m * 2048 + k * 1024); } while (0)
; #define PG8_LDB(dst, b, h) do { _Pragma("unroll") for (int n = 0; n < 2; ++n) _Pragma("unroll") for (int k = 0; k < 2; ++k) dst[n][k] = *(const PG8_LAS bf16x8*)(lds + PG8_SB(b, h) + boff + n * 2048 + k * 1024); } while (0)
; #define PG8_MMA(ai, bj, At, Bt) do { __builtin_amdgcn_s_setprio(1); _Pragma("unroll") for (int m = 0; m < 4; ++m) _Pragma("unroll") for (int n = 0; n < 2; ++n) _Pragma("unroll") for (int k = 0; k < 2; ++k) \
;         acc[ai][bj][m][n] = mma16<Epi::F16>(Bt[n][k], At[m][k], acc[ai][bj][m][n]); __builtin_amdgcn_s_setprio(0); } while (0)
; #define PG8_WAIT_V(n) asm volatile("s_waitcnt vmcnt(" #n ")" ::: "memory")
; #define PG8_WAIT_L(n) asm volatile("s_waitcnt lgkmcnt(" #n ")" ::: "memory")
; template <class Epi, class Sched, bool ALIGN_EPI = false, bool SP2 = false>
; __device__ __forceinline__ void gemm_phase(PG8_LAS unsigned char* lds, const Gemm g, const Sched& S, const Epi& E) {
;     ...
;         for (int t = 0; t < nt; t += 2) {
;             const bool last = (t == nt - 2);
;             const char* a1 = cA + (size_t)(t + 1) * kstep;
;             const char* a2 = last ? nA : cA + (size_t)(t + 2) * kstep; const char* b2 = last ? nB : cB + (size_t)(t + 2) * kstep;
;             const char* a3 = a2 + kstep; const char* b3 = b2 + kstep;
;             if (last && has_next) S.a_ready(nxt);
;             if constexpr (SP2) {
;             PG8_LDB(B0, 0, 0); PG8_LDB(B1, 0, 1); PG8_SCHED; PG8_LDA(At, 0, 0); PG8_STAGE(PG8_SA(1, 1), a1 + hstep, voffA);
;             PG8_WAIT_V(8); PG8_WAIT_L(0); PG8_BAR; PG8_MMA(0, 0, At, B0); PG8_MMA(0, 1, At, B1); PG8_BAR; PG8_SCHED;
;     ...
; #pragma unroll
;         for (int a = 0; a < 2; ++a)
; #pragma unroll
;             for (int b = 0; b < 2; ++b)
; #pragma unroll
;                 for (int m = 0; m < 4; ++m)
; #pragma unroll
;                     for (int n = 0; n < 2; ++n) acc[a][b][m][n] = (f32x4){0.f, 0.f, 0.f, 0.f};
.LBB0_1478:
	s_andn2_b64 vcc, exec, s[52:53]
	s_cbranch_vccz .Lpeel_k9
	v_mov_b32_e32 v123, 0
	v_mov_b32_e32 v122, v123
	v_mov_b32_e32 v121, v123
	v_mov_b32_e32 v120, v123
	v_mov_b32_e32 v127, v123
	v_mov_b32_e32 v126, v123
	v_mov_b32_e32 v125, v123
	v_mov_b32_e32 v124, v123
	v_mov_b32_e32 v111, v123
	v_mov_b32_e32 v110, v123
	v_mov_b32_e32 v109, v123
	v_mov_b32_e32 v108, v123
	v_mov_b32_e32 v107, v123
	v_mov_b32_e32 v106, v123
	v_mov_b32_e32 v105, v123
	v_mov_b32_e32 v104, v123
	v_mov_b32_e32 v95, v123
	v_mov_b32_e32 v94, v123
	v_mov_b32_e32 v93, v123
	v_mov_b32_e32 v92, v123
	v_mov_b32_e32 v91, v123
	v_mov_b32_e32 v90, v123
	v_mov_b32_e32 v89, v123
	v_mov_b32_e32 v88, v123
	v_mov_b32_e32 v79, v123
	v_mov_b32_e32 v78, v123
	v_mov_b32_e32 v77, v123
	v_mov_b32_e32 v76, v123
	v_mov_b32_e32 v75, v123
	v_mov_b32_e32 v74, v123
	v_mov_b32_e32 v73, v123
	v_mov_b32_e32 v72, v123
	v_mov_b32_e32 v119, v123
	v_mov_b32_e32 v118, v123
	v_mov_b32_e32 v117, v123
	v_mov_b32_e32 v116, v123
	v_mov_b32_e32 v115, v123
	v_mov_b32_e32 v114, v123
	v_mov_b32_e32 v113, v123
	v_mov_b32_e32 v112, v123
	v_mov_b32_e32 v103, v123
	v_mov_b32_e32 v102, v123
	v_mov_b32_e32 v101, v123
	v_mov_b32_e32 v100, v123
	v_mov_b32_e32 v99, v123
	v_mov_b32_e32 v98, v123
	v_mov_b32_e32 v97, v123
	v_mov_b32_e32 v96, v123
	v_mov_b32_e32 v87, v123
	v_mov_b32_e32 v86, v123
	v_mov_b32_e32 v85, v123
	v_mov_b32_e32 v84, v123
	v_mov_b32_e32 v83, v123
	v_mov_b32_e32 v82, v123
	v_mov_b32_e32 v81, v123
	v_mov_b32_e32 v80, v123
	v_mov_b32_e32 v71, v123
	v_mov_b32_e32 v70, v123
	v_mov_b32_e32 v69, v123
	v_mov_b32_e32 v68, v123
	v_mov_b32_e32 v67, v123
	v_mov_b32_e32 v66, v123
	v_mov_b32_e32 v65, v123
	v_mov_b32_e32 v64, v123
	v_mov_b32_e32 v63, v123
	v_mov_b32_e32 v62, v123
	v_mov_b32_e32 v61, v123
	v_mov_b32_e32 v60, v123
	v_mov_b32_e32 v59, v123
	v_mov_b32_e32 v58, v123
	v_mov_b32_e32 v57, v123
	v_mov_b32_e32 v56, v123
	v_mov_b32_e32 v47, v123
	v_mov_b32_e32 v46, v123
	v_mov_b32_e32 v45, v123
	v_mov_b32_e32 v44, v123
	v_mov_b32_e32 v43, v123
	v_mov_b32_e32 v42, v123
	v_mov_b32_e32 v41, v123
	v_mov_b32_e32 v40, v123
	v_mov_b32_e32 v31, v123
	v_mov_b32_e32 v30, v123
	v_mov_b32_e32 v29, v123
	v_mov_b32_e32 v28, v123
	v_mov_b32_e32 v27, v123
	v_mov_b32_e32 v26, v123
	v_mov_b32_e32 v25, v123
	v_mov_b32_e32 v24, v123
	v_mov_b32_e32 v15, v123
	v_mov_b32_e32 v14, v123
	v_mov_b32_e32 v13, v123
	v_mov_b32_e32 v12, v123
	v_mov_b32_e32 v11, v123
	v_mov_b32_e32 v10, v123
	v_mov_b32_e32 v9, v123
	v_mov_b32_e32 v8, v123
	v_mov_b32_e32 v55, v123
	v_mov_b32_e32 v54, v123
	v_mov_b32_e32 v53, v123
	v_mov_b32_e32 v52, v123
	v_mov_b32_e32 v51, v123
	v_mov_b32_e32 v50, v123
	v_mov_b32_e32 v49, v123
	v_mov_b32_e32 v48, v123
	v_mov_b32_e32 v39, v123
	v_mov_b32_e32 v38, v123
	v_mov_b32_e32 v37, v123
	v_mov_b32_e32 v36, v123
	v_mov_b32_e32 v35, v123
	v_mov_b32_e32 v34, v123
	v_mov_b32_e32 v33, v123
	v_mov_b32_e32 v32, v123
	v_mov_b32_e32 v23, v123
	v_mov_b32_e32 v22, v123
	v_mov_b32_e32 v21, v123
	v_mov_b32_e32 v20, v123
	v_mov_b32_e32 v19, v123
	v_mov_b32_e32 v18, v123
	v_mov_b32_e32 v17, v123
	v_mov_b32_e32 v16, v123
	v_mov_b32_e32 v7, v123
	v_mov_b32_e32 v6, v123
	v_mov_b32_e32 v5, v123
	v_mov_b32_e32 v4, v123
	v_mov_b32_e32 v3, v123
	v_mov_b32_e32 v2, v123
	v_mov_b32_e32 v1, v123
	v_mov_b32_e32 v0, v123
	s_branch .LBB0_1481
.Lpeel_k9:
	s_add_u32 s30, s30, 0x80
	s_addc_u32 s31, s31, 0
	s_add_u32 s29, s34, 0x100
	s_addc_u32 s71, s35, 0
	s_mov_b32 s34, 0
	s_add_i32 s72, s34, 2
	s_add_u32 s73, s30, 0x80
	s_addc_u32 s35, s31, 0
	s_add_i32 s77, 0, 0x10000
	s_cmp_eq_u32 s59, s34
	s_cselect_b32 s35, s1, s35
	s_cselect_b32 s34, s0, s73
	v_add_u32_e32 v131, s77, v133
	s_cselect_b32 s85, s57, s71
	s_cselect_b32 s84, s56, s29
	s_add_i32 s73, 0, 0x14000
	ds_read_b128 v[140:143], v131
	ds_read_b128 v[144:147], v131 offset:1024
	ds_read_b128 v[148:151], v131 offset:2048
	ds_read_b128 v[152:155], v131 offset:3072
	v_add_u32_e32 v131, s73, v133
	ds_read_b128 v[156:159], v131
	ds_read_b128 v[160:163], v131 offset:1024
	ds_read_b128 v[164:167], v131 offset:2048
	ds_read_b128 v[168:171], v131 offset:3072
	v_lshl_add_u64 v[212:213], s[30:31], 0, v[136:137]
	s_add_i32 m0, s9, 0xc000
	ds_read_b128 v[172:175], v199
	ds_read_b128 v[176:179], v199 offset:1024
	ds_read_b128 v[180:183], v199 offset:2048
	ds_read_b128 v[184:187], v199 offset:3072
	ds_read_b128 v[188:191], v199 offset:4096
	ds_read_b128 v[192:195], v199 offset:5120
	ds_read_b128 v[200:203], v199 offset:6144
	ds_read_b128 v[204:207], v199 offset:7168
	global_load_lds_dwordx4 v[212:213], off
	v_lshl_add_u64 v[212:213], s[30:31], 0, v[138:139]
	s_add_i32 m0, s9, 0xe000
	s_nop 0
	global_load_lds_dwordx4 v[212:213], off
	s_waitcnt vmcnt(8)
	s_waitcnt lgkmcnt(0)
	s_barrier
; #define PG8_STAGE(bufoff, gbase, voff) do { _Pragma("unroll") for (int _i = 0; _i < 2; ++_i) \
;         __builtin_amdgcn_global_load_lds((const unsigned*)((const char*)(gbase) + (voff)[_i]), (PG8_LAS unsigned*)(lds + (bufoff) + ldsw + _i * 8192), 16, 0, 0); } while (0)
; #define PG8_LDA(dst, b, h) do { _Pragma("unroll") for (int m = 0; m < 4; ++m) _Pragma("unroll") for (int k = 0; k < 2; ++k) dst[m][k] = *(const PG8_LAS bf16x8*)(lds + PG8_SA(b, h) + aoff + m * 2048 + k * 1024); } while (0)
; #define PG8_MMA(ai, bj, At, Bt) do { __builtin_amdgcn_s_setprio(1); _Pragma("unroll") for (int m = 0; m < 4; ++m) _Pragma("unroll") for (int n = 0; n < 2; ++n) _Pragma("unroll") for (int k = 0; k < 2; ++k) \
;         acc[ai][bj][m][n] = mma16<Epi::F16>(Bt[n][k], At[m][k], acc[ai][bj][m][n]); __builtin_amdgcn_s_setprio(0); } while (0)
; #define PG8_WAIT_V(n) asm volatile("s_waitcnt vmcnt(" #n ")" ::: "memory")
; #define PG8_WAIT_L(n) asm volatile("s_waitcnt lgkmcnt(" #n ")" ::: "memory")
; #define PG8_BAR __builtin_amdgcn_s_barrier()
; #define PG8_SCHED __builtin_amdgcn_sched_barrier(0)
; template <class Epi, class Sched, bool ALIGN_EPI = false, bool SP2 = false>
; __device__ __forceinline__ void gemm_phase(PG8_LAS unsigned char* lds, const Gemm g, const Sched& S, const Epi& E) {
;     ...
;             PG8_WAIT_V(8); PG8_WAIT_L(0); PG8_BAR; PG8_MMA(0, 0, At, B0); PG8_MMA(0, 1, At, B1); PG8_BAR; PG8_SCHED;
;             PG8_LDA(At, 0, 1); PG8_STAGE(PG8_SB(0, 0), b2, voffB); PG8_STAGE(PG8_SB(0, 1), b2 + hstep, voffB); PG8_STAGE(PG8_SA(0, 0), a2, voffA);
;             PG8_WAIT_V(8); PG8_WAIT_L(0); PG8_BAR; PG8_MMA(1, 0, At, B0); PG8_MMA(1, 1, At, B1); PG8_BAR; PG8_SCHED;
	s_setprio 1
	s_waitcnt lgkmcnt(0)
	v_mfma_f32_16x16x32_bf16 v[120:123], v[140:143], v[172:175], 0
	v_mfma_f32_16x16x32_bf16 v[124:127], v[148:151], v[172:175], 0
	v_mfma_f32_16x16x32_bf16 v[108:111], v[140:143], v[180:183], 0
	v_mfma_f32_16x16x32_bf16 v[104:107], v[148:151], v[180:183], 0
	v_mfma_f32_16x16x32_bf16 v[92:95], v[140:143], v[188:191], 0
	v_mfma_f32_16x16x32_bf16 v[88:91], v[148:151], v[188:191], 0
	v_mfma_f32_16x16x32_bf16 v[76:79], v[140:143], v[200:203], 0
	v_mfma_f32_16x16x32_bf16 v[72:75], v[148:151], v[200:203], 0
	v_mfma_f32_16x16x32_bf16 v[120:123], v[144:147], v[176:179], v[120:123]
	v_mfma_f32_16x16x32_bf16 v[124:127], v[152:155], v[176:179], v[124:127]
	v_mfma_f32_16x16x32_bf16 v[108:111], v[144:147], v[184:187], v[108:111]
	v_mfma_f32_16x16x32_bf16 v[104:107], v[152:155], v[184:187], v[104:107]
	v_mfma_f32_16x16x32_bf16 v[92:95], v[144:147], v[192:195], v[92:95]
	v_mfma_f32_16x16x32_bf16 v[88:91], v[152:155], v[192:195], v[88:91]
	v_mfma_f32_16x16x32_bf16 v[76:79], v[144:147], v[204:207], v[76:79]
	v_mfma_f32_16x16x32_bf16 v[72:75], v[152:155], v[204:207], v[72:75]
	s_setprio 0
	s_setprio 1
	v_mfma_f32_16x16x32_bf16 v[116:119], v[156:159], v[172:175], 0
	v_mfma_f32_16x16x32_bf16 v[112:115], v[164:167], v[172:175], 0
	v_mfma_f32_16x16x32_bf16 v[100:103], v[156:159], v[180:183], 0
	v_mfma_f32_16x16x32_bf16 v[96:99], v[164:167], v[180:183], 0
	v_mfma_f32_16x16x32_bf16 v[84:87], v[156:159], v[188:191], 0
	v_mfma_f32_16x16x32_bf16 v[80:83], v[164:167], v[188:191], 0
	v_mfma_f32_16x16x32_bf16 v[68:71], v[156:159], v[200:203], 0
	v_mfma_f32_16x16x32_bf16 v[64:67], v[164:167], v[200:203], 0
	v_mfma_f32_16x16x32_bf16 v[116:119], v[160:163], v[176:179], v[116:119]
	v_mfma_f32_16x16x32_bf16 v[112:115], v[168:171], v[176:179], v[112:115]
	v_mfma_f32_16x16x32_bf16 v[100:103], v[160:163], v[184:187], v[100:103]
	v_mfma_f32_16x16x32_bf16 v[96:99], v[168:171], v[184:187], v[96:99]
	v_mfma_f32_16x16x32_bf16 v[84:87], v[160:163], v[192:195], v[84:87]
	v_mfma_f32_16x16x32_bf16 v[80:83], v[168:171], v[192:195], v[80:83]
	v_mfma_f32_16x16x32_bf16 v[68:71], v[160:163], v[204:207], v[68:71]
	v_mfma_f32_16x16x32_bf16 v[64:67], v[168:171], v[204:207], v[64:67]
	s_setprio 0
	s_barrier
	s_add_i32 s77, s77, s8
	v_lshl_add_u64 v[212:213], s[84:85], 0, v[208:209]
	s_mov_b32 m0, s77
	ds_read_b128 v[172:175], v199 offset:16384
	ds_read_b128 v[176:179], v199 offset:17408
	ds_read_b128 v[180:183], v199 offset:18432
	ds_read_b128 v[184:187], v199 offset:19456
	ds_read_b128 v[188:191], v199 offset:20480
	ds_read_b128 v[192:195], v199 offset:21504
	ds_read_b128 v[200:203], v199 offset:22528
	ds_read_b128 v[204:207], v199 offset:23552
	global_load_lds_dwordx4 v[212:213], off
	s_add_i32 m0, s77, 0x2000
	v_lshl_add_u64 v[214:215], s[84:85], 0, v[128:129]
	s_add_u32 s84, s84, s42
	s_addc_u32 s85, s85, s43
	s_add_i32 s73, s73, s8
	global_load_lds_dwordx4 v[214:215], off
	v_lshl_add_u64 v[216:217], s[84:85], 0, v[208:209]
	s_mov_b32 m0, s73
	v_lshl_add_u64 v[218:219], s[84:85], 0, v[128:129]
	global_load_lds_dwordx4 v[216:217], off
	s_add_i32 m0, s73, 0x2000
	v_lshl_add_u64 v[220:221], s[34:35], 0, v[208:209]
	global_load_lds_dwordx4 v[218:219], off
	s_mov_b32 m0, s9
	v_lshl_add_u64 v[222:223], s[34:35], 0, v[128:129]
	global_load_lds_dwordx4 v[220:221], off
	s_mov_b32 m0, s11
	s_nop 0
	global_load_lds_dwordx4 v[222:223], off
	s_waitcnt vmcnt(8)
	s_waitcnt lgkmcnt(0)
	s_barrier
	s_setprio 1
	s_waitcnt lgkmcnt(0)
	v_mfma_f32_16x16x32_bf16 v[60:63], v[140:143], v[172:175], 0
	v_mfma_f32_16x16x32_bf16 v[56:59], v[148:151], v[172:175], 0
	v_mfma_f32_16x16x32_bf16 v[44:47], v[140:143], v[180:183], 0
	v_mfma_f32_16x16x32_bf16 v[40:43], v[148:151], v[180:183], 0
	v_mfma_f32_16x16x32_bf16 v[28:31], v[140:143], v[188:191], 0
	v_mfma_f32_16x16x32_bf16 v[24:27], v[148:151], v[188:191], 0
	v_mfma_f32_16x16x32_bf16 v[12:15], v[140:143], v[200:203], 0
	v_mfma_f32_16x16x32_bf16 v[8:11], v[148:151], v[200:203], 0
	v_mfma_f32_16x16x32_bf16 v[60:63], v[144:147], v[176:179], v[60:63]
	v_mfma_f32_16x16x32_bf16 v[56:59], v[152:155], v[176:179], v[56:59]
	v_mfma_f32_16x16x32_bf16 v[44:47], v[144:147], v[184:187], v[44:47]
	v_mfma_f32_16x16x32_bf16 v[40:43], v[152:155], v[184:187], v[40:43]
	v_mfma_f32_16x16x32_bf16 v[28:31], v[144:147], v[192:195], v[28:31]
	v_mfma_f32_16x16x32_bf16 v[24:27], v[152:155], v[192:195], v[24:27]
	v_mfma_f32_16x16x32_bf16 v[12:15], v[144:147], v[204:207], v[12:15]
	v_mfma_f32_16x16x32_bf16 v[8:11], v[152:155], v[204:207], v[8:11]
	s_setprio 0
	s_setprio 1
	v_mfma_f32_16x16x32_bf16 v[52:55], v[156:159], v[172:175], 0
	v_mfma_f32_16x16x32_bf16 v[48:51], v[164:167], v[172:175], 0
	v_mfma_f32_16x16x32_bf16 v[36:39], v[156:159], v[180:183], 0
	v_mfma_f32_16x16x32_bf16 v[32:35], v[164:167], v[180:183], 0
	v_mfma_f32_16x16x32_bf16 v[20:23], v[156:159], v[188:191], 0
	v_mfma_f32_16x16x32_bf16 v[16:19], v[164:167], v[188:191], 0
	v_mfma_f32_16x16x32_bf16 v[4:7], v[156:159], v[200:203], 0
	v_mfma_f32_16x16x32_bf16 v[0:3], v[164:167], v[200:203], 0
	v_mfma_f32_16x16x32_bf16 v[52:55], v[160:163], v[176:179], v[52:55]
	v_mfma_f32_16x16x32_bf16 v[48:51], v[168:171], v[176:179], v[48:51]
	v_mfma_f32_16x16x32_bf16 v[36:39], v[160:163], v[184:187], v[36:39]
	v_mfma_f32_16x16x32_bf16 v[32:35], v[168:171], v[184:187], v[32:35]
	v_mfma_f32_16x16x32_bf16 v[20:23], v[160:163], v[192:195], v[20:23]
	v_mfma_f32_16x16x32_bf16 v[16:19], v[168:171], v[192:195], v[16:19]
	v_mfma_f32_16x16x32_bf16 v[4:7], v[160:163], v[204:207], v[4:7]
	v_mfma_f32_16x16x32_bf16 v[0:3], v[168:171], v[204:207], v[0:3]
	s_setprio 0
	s_barrier
; #define PG8_STAGE(bufoff, gbase, voff) do { _Pragma("unroll") for (int _i = 0; _i < 2; ++_i) \
;         __builtin_amdgcn_global_load_lds((const unsigned*)((const char*)(gbase) + (voff)[_i]), (PG8_LAS unsigned*)(lds + (bufoff) + ldsw + _i * 8192), 16, 0, 0); } while (0)
; #define PG8_LDA(dst, b, h) do { _Pragma("unroll") for (int m = 0; m < 4; ++m) _Pragma("unroll") for (int k = 0; k < 2; ++k) dst[m][k] = *(const PG8_LAS bf16x8*)(lds + PG8_SA(b, h) + aoff + m * 2048 + k * 1024); } while (0)
; #define PG8_LDB(dst, b, h) do { _Pragma("unroll") for (int n = 0; n < 2; ++n) _Pragma("unroll") for (int k = 0; k < 2; ++k) dst[n][k] = *(const PG8_LAS bf16x8*)(lds + PG8_SB(b, h) + boff + n * 2048 + k * 1024); } while (0)
; #define PG8_MMA(ai, bj, At, Bt) do { __builtin_amdgcn_s_setprio(1); _Pragma("unroll") for (int m = 0; m < 4; ++m) _Pragma("unroll") for (int n = 0; n < 2; ++n) _Pragma("unroll") for (int k = 0; k < 2; ++k) \
;         acc[ai][bj][m][n] = mma16<Epi::F16>(Bt[n][k], At[m][k], acc[ai][bj][m][n]); __builtin_amdgcn_s_setprio(0); } while (0)
; #define PG8_WAIT_V(n) asm volatile("s_waitcnt vmcnt(" #n ")" ::: "memory")
; #define PG8_WAIT_L(n) asm volatile("s_waitcnt lgkmcnt(" #n ")" ::: "memory")
; #define PG8_BAR __builtin_amdgcn_s_barrier()
; #define PG8_SCHED __builtin_amdgcn_sched_barrier(0)
; template <class Epi, class Sched, bool ALIGN_EPI = false, bool SP2 = false>
; __device__ __forceinline__ void gemm_phase(PG8_LAS unsigned char* lds, const Gemm g, const Sched& S, const Epi& E) {
;     ...
;             PG8_LDB(B0, 1, 0); PG8_LDB(B1, 1, 1); PG8_SCHED; PG8_LDA(At, 1, 0); PG8_STAGE(PG8_SA(0, 1), a2 + hstep, voffA);
;             PG8_WAIT_V(8); PG8_WAIT_L(0); PG8_BAR; PG8_MMA(0, 0, At, B0); PG8_MMA(0, 1, At, B1); PG8_BAR; PG8_SCHED;
	s_add_i32 s73, 0, 0x18000
	v_add_u32_e32 v131, s73, v133
	s_add_i32 s77, 0, 0x1c000
	ds_read_b128 v[140:143], v131
	ds_read_b128 v[144:147], v131 offset:1024
	ds_read_b128 v[148:151], v131 offset:2048
	ds_read_b128 v[152:155], v131 offset:3072
	v_add_u32_e32 v131, s77, v133
	ds_read_b128 v[156:159], v131
	ds_read_b128 v[160:163], v131 offset:1024
	ds_read_b128 v[164:167], v131 offset:2048
	ds_read_b128 v[168:171], v131 offset:3072
	s_add_u32 s34, s34, s42
	s_addc_u32 s35, s35, s43
	s_mov_b32 m0, s18
	v_lshl_add_u64 v[224:225], s[34:35], 0, v[208:209]
	ds_read_b128 v[172:175], v199 offset:32768
	ds_read_b128 v[176:179], v199 offset:33792
	ds_read_b128 v[180:183], v199 offset:34816
	ds_read_b128 v[184:187], v199 offset:35840
	ds_read_b128 v[188:191], v199 offset:36864
	ds_read_b128 v[192:195], v199 offset:37888
	ds_read_b128 v[200:203], v199 offset:38912
	ds_read_b128 v[204:207], v199 offset:39936
	global_load_lds_dwordx4 v[224:225], off
	v_lshl_add_u64 v[224:225], s[34:35], 0, v[128:129]
	s_mov_b32 m0, s36
	s_nop 0
	global_load_lds_dwordx4 v[224:225], off
	s_waitcnt vmcnt(8)
	s_waitcnt lgkmcnt(0)
	s_barrier
	s_setprio 1
	s_waitcnt lgkmcnt(0)
	v_mfma_f32_16x16x32_bf16 v[120:123], v[140:143], v[172:175], v[120:123]
	v_mfma_f32_16x16x32_bf16 v[124:127], v[148:151], v[172:175], v[124:127]
	v_mfma_f32_16x16x32_bf16 v[108:111], v[140:143], v[180:183], v[108:111]
	v_mfma_f32_16x16x32_bf16 v[104:107], v[148:151], v[180:183], v[104:107]
	v_mfma_f32_16x16x32_bf16 v[92:95], v[140:143], v[188:191], v[92:95]
	v_mfma_f32_16x16x32_bf16 v[88:91], v[148:151], v[188:191], v[88:91]
	v_mfma_f32_16x16x32_bf16 v[76:79], v[140:143], v[200:203], v[76:79]
	v_mfma_f32_16x16x32_bf16 v[72:75], v[148:151], v[200:203], v[72:75]
	v_mfma_f32_16x16x32_bf16 v[120:123], v[144:147], v[176:179], v[120:123]
	v_mfma_f32_16x16x32_bf16 v[124:127], v[152:155], v[176:179], v[124:127]
	v_mfma_f32_16x16x32_bf16 v[108:111], v[144:147], v[184:187], v[108:111]
	v_mfma_f32_16x16x32_bf16 v[104:107], v[152:155], v[184:187], v[104:107]
	v_mfma_f32_16x16x32_bf16 v[92:95], v[144:147], v[192:195], v[92:95]
	v_mfma_f32_16x16x32_bf16 v[88:91], v[152:155], v[192:195], v[88:91]
	v_mfma_f32_16x16x32_bf16 v[76:79], v[144:147], v[204:207], v[76:79]
	v_mfma_f32_16x16x32_bf16 v[72:75], v[152:155], v[204:207], v[72:75]
	s_setprio 0
	s_setprio 1
	v_mfma_f32_16x16x32_bf16 v[116:119], v[156:159], v[172:175], v[116:119]
	v_mfma_f32_16x16x32_bf16 v[112:115], v[164:167], v[172:175], v[112:115]
	v_mfma_f32_16x16x32_bf16 v[100:103], v[156:159], v[180:183], v[100:103]
	v_mfma_f32_16x16x32_bf16 v[96:99], v[164:167], v[180:183], v[96:99]
	v_mfma_f32_16x16x32_bf16 v[84:87], v[156:159], v[188:191], v[84:87]
	v_mfma_f32_16x16x32_bf16 v[80:83], v[164:167], v[188:191], v[80:83]
	v_mfma_f32_16x16x32_bf16 v[68:71], v[156:159], v[200:203], v[68:71]
	v_mfma_f32_16x16x32_bf16 v[64:67], v[164:167], v[200:203], v[64:67]
	v_mfma_f32_16x16x32_bf16 v[116:119], v[160:163], v[176:179], v[116:119]
	v_mfma_f32_16x16x32_bf16 v[112:115], v[168:171], v[176:179], v[112:115]
	v_mfma_f32_16x16x32_bf16 v[100:103], v[160:163], v[184:187], v[100:103]
	v_mfma_f32_16x16x32_bf16 v[96:99], v[168:171], v[184:187], v[96:99]
	v_mfma_f32_16x16x32_bf16 v[84:87], v[160:163], v[192:195], v[84:87]
	v_mfma_f32_16x16x32_bf16 v[80:83], v[168:171], v[192:195], v[80:83]
	v_mfma_f32_16x16x32_bf16 v[68:71], v[160:163], v[204:207], v[68:71]
	v_mfma_f32_16x16x32_bf16 v[64:67], v[168:171], v[204:207], v[64:67]
	s_setprio 0
	s_barrier
; #define PG8_STAGE(bufoff, gbase, voff) do { _Pragma("unroll") for (int _i = 0; _i < 2; ++_i) \
;         __builtin_amdgcn_global_load_lds((const unsigned*)((const char*)(gbase) + (voff)[_i]), (PG8_LAS unsigned*)(lds + (bufoff) + ldsw + _i * 8192), 16, 0, 0); } while (0)
; #define PG8_LDA(dst, b, h) do { _Pragma("unroll") for (int m = 0; m < 4; ++m) _Pragma("unroll") for (int k = 0; k < 2; ++k) dst[m][k] = *(const PG8_LAS bf16x8*)(lds + PG8_SA(b, h) + aoff + m * 2048 + k * 1024); } while (0)
; #define PG8_MMA(ai, bj, At, Bt) do { __builtin_amdgcn_s_setprio(1); _Pragma("unroll") for (int m = 0; m < 4; ++m) _Pragma("unroll") for (int n = 0; n < 2; ++n) _Pragma("unroll") for (int k = 0; k < 2; ++k) \
;         acc[ai][bj][m][n] = mma16<Epi::F16>(Bt[n][k], At[m][k], acc[ai][bj][m][n]); __builtin_amdgcn_s_setprio(0); } while (0)
; #define PG8_WAIT_V(n) asm volatile("s_waitcnt vmcnt(" #n ")" ::: "memory")
; #define PG8_WAIT_L(n) asm volatile("s_waitcnt lgkmcnt(" #n ")" ::: "memory")
; #define PG8_BAR __builtin_amdgcn_s_barrier()
; #define PG8_SCHED __builtin_amdgcn_sched_barrier(0)
; template <class Epi, class Sched, bool ALIGN_EPI = false, bool SP2 = false>
; __device__ __forceinline__ void gemm_phase(PG8_LAS unsigned char* lds, const Gemm g, const Sched& S, const Epi& E) {
;     ...
;         for (int t = 0; t < nt; t += 2) {
;             const bool last = (t == nt - 2);
;             const char* a1 = cA + (size_t)(t + 1) * kstep;
;             const char* a2 = last ? nA : cA + (size_t)(t + 2) * kstep; const char* b2 = last ? nB : cB + (size_t)(t + 2) * kstep;
;     ...
;             PG8_LDA(At, 1, 1); PG8_STAGE(PG8_SB(1, 0), b3, voffB); PG8_STAGE(PG8_SB(1, 1), b3 + hstep, voffB); PG8_STAGE(PG8_SA(1, 0), a3, voffA);
;             PG8_WAIT_V(8); PG8_WAIT_L(0); PG8_BAR; PG8_MMA(1, 0, At, B0); PG8_MMA(1, 1, At, B1); PG8_BAR; PG8_SCHED;
	s_add_i32 s34, s73, s8
	v_lshl_add_u64 v[212:213], v[212:213], 0, s[20:21]
	s_mov_b32 m0, s34
	ds_read_b128 v[172:175], v199 offset:49152
	ds_read_b128 v[176:179], v199 offset:50176
	ds_read_b128 v[180:183], v199 offset:51200
	ds_read_b128 v[184:187], v199 offset:52224
	ds_read_b128 v[188:191], v199 offset:53248
	ds_read_b128 v[192:195], v199 offset:54272
	ds_read_b128 v[200:203], v199 offset:55296
	ds_read_b128 v[204:207], v199 offset:56320
	global_load_lds_dwordx4 v[212:213], off
	v_lshl_add_u64 v[212:213], v[214:215], 0, s[20:21]
	s_add_i32 m0, s34, 0x2000
	s_add_i32 s34, s77, s8
	global_load_lds_dwordx4 v[212:213], off
	v_lshl_add_u64 v[212:213], v[216:217], 0, s[20:21]
	s_mov_b32 m0, s34
	s_nop 0
	global_load_lds_dwordx4 v[212:213], off
	v_lshl_add_u64 v[212:213], v[218:219], 0, s[20:21]
	s_add_i32 m0, s34, 0x2000
	s_nop 0
	global_load_lds_dwordx4 v[212:213], off
	v_lshl_add_u64 v[212:213], v[220:221], 0, s[20:21]
	s_mov_b32 m0, s37
	s_nop 0
	global_load_lds_dwordx4 v[212:213], off
	v_lshl_add_u64 v[212:213], v[222:223], 0, s[20:21]
	s_mov_b32 m0, s48
	s_nop 0
	global_load_lds_dwordx4 v[212:213], off
	s_waitcnt vmcnt(8)
	s_waitcnt lgkmcnt(0)
	s_barrier
	s_setprio 1
	s_waitcnt lgkmcnt(0)
	v_mfma_f32_16x16x32_bf16 v[60:63], v[140:143], v[172:175], v[60:63]
	v_mfma_f32_16x16x32_bf16 v[56:59], v[148:151], v[172:175], v[56:59]
	v_mfma_f32_16x16x32_bf16 v[44:47], v[140:143], v[180:183], v[44:47]
	v_mfma_f32_16x16x32_bf16 v[40:43], v[148:151], v[180:183], v[40:43]
	v_mfma_f32_16x16x32_bf16 v[28:31], v[140:143], v[188:191], v[28:31]
	v_mfma_f32_16x16x32_bf16 v[24:27], v[148:151], v[188:191], v[24:27]
	v_mfma_f32_16x16x32_bf16 v[12:15], v[140:143], v[200:203], v[12:15]
	v_mfma_f32_16x16x32_bf16 v[8:11], v[148:151], v[200:203], v[8:11]
	v_mfma_f32_16x16x32_bf16 v[60:63], v[144:147], v[176:179], v[60:63]
	v_mfma_f32_16x16x32_bf16 v[56:59], v[152:155], v[176:179], v[56:59]
	v_mfma_f32_16x16x32_bf16 v[44:47], v[144:147], v[184:187], v[44:47]
	v_mfma_f32_16x16x32_bf16 v[40:43], v[152:155], v[184:187], v[40:43]
	v_mfma_f32_16x16x32_bf16 v[28:31], v[144:147], v[192:195], v[28:31]
	v_mfma_f32_16x16x32_bf16 v[24:27], v[152:155], v[192:195], v[24:27]
	v_mfma_f32_16x16x32_bf16 v[12:15], v[144:147], v[204:207], v[12:15]
	v_mfma_f32_16x16x32_bf16 v[8:11], v[152:155], v[204:207], v[8:11]
	s_setprio 0
	s_setprio 1
	v_mfma_f32_16x16x32_bf16 v[52:55], v[156:159], v[172:175], v[52:55]
	v_mfma_f32_16x16x32_bf16 v[48:51], v[164:167], v[172:175], v[48:51]
	v_mfma_f32_16x16x32_bf16 v[36:39], v[156:159], v[180:183], v[36:39]
	v_mfma_f32_16x16x32_bf16 v[32:35], v[164:167], v[180:183], v[32:35]
	v_mfma_f32_16x16x32_bf16 v[20:23], v[156:159], v[188:191], v[20:23]
	v_mfma_f32_16x16x32_bf16 v[16:19], v[164:167], v[188:191], v[16:19]
	v_mfma_f32_16x16x32_bf16 v[4:7], v[156:159], v[200:203], v[4:7]
	v_mfma_f32_16x16x32_bf16 v[0:3], v[164:167], v[200:203], v[0:3]
	v_mfma_f32_16x16x32_bf16 v[52:55], v[160:163], v[176:179], v[52:55]
	v_mfma_f32_16x16x32_bf16 v[48:51], v[168:171], v[176:179], v[48:51]
	v_mfma_f32_16x16x32_bf16 v[36:39], v[160:163], v[184:187], v[36:39]
	v_mfma_f32_16x16x32_bf16 v[32:35], v[168:171], v[184:187], v[32:35]
	v_mfma_f32_16x16x32_bf16 v[20:23], v[160:163], v[192:195], v[20:23]
	v_mfma_f32_16x16x32_bf16 v[16:19], v[168:171], v[192:195], v[16:19]
	v_mfma_f32_16x16x32_bf16 v[4:7], v[160:163], v[204:207], v[4:7]
	v_mfma_f32_16x16x32_bf16 v[0:3], v[168:171], v[204:207], v[0:3]
	s_setprio 0
	s_barrier
	s_add_u32 s30, s30, 0x100
	s_addc_u32 s31, s31, 0
	s_add_u32 s29, s29, 0x100
	s_addc_u32 s71, s71, 0
	s_cmp_ge_i32 s72, s58
	s_mov_b32 s34, s72
	s_cbranch_scc0 .LBB0_1480
	s_branch .LBB0_1481
